# GEMM K-loops: LDS-DMA loads use scalar base plus 32-bit lane offset, the 16 per-iteration 64-bit vector address adds removed
# speedup vs baseline: 1.0086x; 1.0002x over previous
; #define PG8_STAGE(bufoff, gbase, voff) do { _Pragma("unroll") for (int _i = 0; _i < 2; ++_i) \
;     __builtin_amdgcn_global_load_lds((const unsigned*)((const char*)(gbase) + (voff)[_i]), (LAS unsigned*)(lds + (bufoff) + ldsw + _i * 8192), 16, 0, 0); } while (0)
; #define PG8_LDA(dst, b, h) do { _Pragma("unroll") for (int m = 0; m < 4; ++m) _Pragma("unroll") for (int k = 0; k < 2; ++k) dst[m][k] = *(const LAS bf16x8*)(lds + PG8_SA(b, h) + aoff + m * 2048 + k * 1024); } while (0)
; #define PG8_LDB(dst, b, h) do { _Pragma("unroll") for (int n = 0; n < 2; ++n) _Pragma("unroll") for (int k = 0; k < 2; ++k) dst[n][k] = *(const LAS bf16x8*)(lds + PG8_SB(b, h) + boff + n * 2048 + k * 1024); } while (0)
; #define PG8_WAIT_V(n) asm volatile("s_waitcnt vmcnt(" #n ")" ::: "memory")
; template <class Epi, class Sched>
; DI void gemm_phase(LAS unsigned char* lds, const Gemm g, const Sched& S, const Epi& E) {
;     ...
;     for (int t = 0; t < nt; t += 2) {
;       const bool last = (t == nt - 2);
;       const char* a1 = cA + (size_t)(t + 1) * kstep;
;       const char* a2 = last ? nA : cA + (size_t)(t + 2) * kstep; const char* b2 = last ? nB : cB + (size_t)(t + 2) * kstep;
;       const char* a3 = a2 + kstep; const char* b3 = b2 + kstep;
;       PG8_LDB(B0, 0, 0); PG8_SCHED; PG8_LDA(At, 0, 0); PG8_STAGE(PG8_SA(1, 1), a1 + hstep, voffA);
;       PG8_WAIT_L(8); PG8_BAR; PG8_WAIT_L(0); PG8_MMA(0, 0, At, B0); PG8_BAR; PG8_SCHED;
;       PG8_LDB(B1, 0, 1); PG8_STAGE(PG8_SB(0, 0), b2, voffB);
;       PG8_BAR; PG8_WAIT_L(0); PG8_MMA(0, 1, At, B1); PG8_BAR;
;       PG8_LDA(At, 0, 1); PG8_STAGE(PG8_SA(0, 0), a2, voffA);
;       PG8_BAR; PG8_WAIT_L(0); PG8_MMA(1, 0, At, B0); PG8_BAR; PG8_SCHED;
;       PG8_STAGE(PG8_SB(0, 1), b2 + hstep, voffB);
;       PG8_WAIT_V(6); PG8_BAR; PG8_MMA(1, 1, At, B1); PG8_BAR;
;       PG8_LDB(B0, 1, 0); PG8_SCHED; PG8_LDA(At, 1, 0); PG8_STAGE(PG8_SA(0, 1), a2 + hstep, voffA);
;       PG8_WAIT_L(8); PG8_BAR; PG8_WAIT_L(0); PG8_MMA(0, 0, At, B0); PG8_BAR; PG8_SCHED;
;       PG8_LDB(B1, 1, 1); PG8_STAGE(PG8_SB(1, 0), b3, voffB);
;       PG8_BAR; PG8_WAIT_L(0); PG8_MMA(0, 1, At, B1); PG8_BAR;
;       PG8_LDA(At, 1, 1); PG8_STAGE(PG8_SA(1, 0), a3, voffA);
;       PG8_BAR; PG8_WAIT_L(0); PG8_MMA(1, 0, At, B0); PG8_BAR; PG8_SCHED;
;       PG8_STAGE(PG8_SB(1, 1), b3 + hstep, voffB);
;       PG8_WAIT_V(6); PG8_BAR; PG8_MMA(1, 1, At, B1); PG8_BAR;
.LBB0_370:
	s_add_u32 s4, s2, 0xfffc0080
	s_addc_u32 s5, s3, -1
	s_add_i32 s51, 0, 0x10000
	v_add_u32_e32 v144, s51, v155
	ds_read_b128 v[128:131], v144
	ds_read_b128 v[146:149], v144 offset:1024
	ds_read_b128 v[150:153], v144 offset:2048
	ds_read_b128 v[160:163], v144 offset:3072
	s_cmp_eq_u32 s50, 12
	s_cselect_b32 s21, s15, s5
	s_cselect_b32 s20, s29, s4
	s_cselect_b32 s5, s13, s49
	s_cselect_b32 s4, s36, s37
	s_add_i32 m0, s40, 0xc000
	ds_read_b128 v[164:167], v158
	ds_read_b128 v[168:171], v158 offset:1024
	ds_read_b128 v[172:175], v158 offset:2048
	ds_read_b128 v[176:179], v158 offset:3072
	ds_read_b128 v[196:199], v158 offset:4096
	ds_read_b128 v[200:203], v158 offset:5120
	ds_read_b128 v[204:207], v158 offset:6144
	ds_read_b128 v[208:211], v158 offset:7168
	global_load_lds_dwordx4 v140, s[2:3]
	s_add_i32 m0, s40, 0xe000
	s_nop 0
	global_load_lds_dwordx4 v142, s[2:3]
	s_waitcnt lgkmcnt(8)
	s_barrier
	s_waitcnt lgkmcnt(0)
	s_waitcnt lgkmcnt(0)
	v_mfma_f32_16x16x32_bf16 v[124:127], v[128:131], v[164:167], v[124:127]
	v_mfma_f32_16x16x32_bf16 v[120:123], v[150:153], v[164:167], v[120:123]
	v_mfma_f32_16x16x32_bf16 v[108:111], v[128:131], v[172:175], v[108:111]
	v_mfma_f32_16x16x32_bf16 v[104:107], v[150:153], v[172:175], v[104:107]
	v_mfma_f32_16x16x32_bf16 v[92:95], v[128:131], v[196:199], v[92:95]
	v_mfma_f32_16x16x32_bf16 v[88:91], v[150:153], v[196:199], v[88:91]
	v_mfma_f32_16x16x32_bf16 v[76:79], v[128:131], v[204:207], v[76:79]
	v_mfma_f32_16x16x32_bf16 v[72:75], v[150:153], v[204:207], v[72:75]
	v_mfma_f32_16x16x32_bf16 v[124:127], v[146:149], v[168:171], v[124:127]
	v_mfma_f32_16x16x32_bf16 v[120:123], v[160:163], v[168:171], v[120:123]
	v_mfma_f32_16x16x32_bf16 v[108:111], v[146:149], v[176:179], v[108:111]
	v_mfma_f32_16x16x32_bf16 v[104:107], v[160:163], v[176:179], v[104:107]
	v_mfma_f32_16x16x32_bf16 v[92:95], v[146:149], v[200:203], v[92:95]
	v_mfma_f32_16x16x32_bf16 v[88:91], v[160:163], v[200:203], v[88:91]
	v_mfma_f32_16x16x32_bf16 v[76:79], v[146:149], v[208:211], v[76:79]
	v_mfma_f32_16x16x32_bf16 v[72:75], v[160:163], v[208:211], v[72:75]
	s_barrier
	s_add_i32 s54, 0, 0x14000
	s_add_i32 s51, s51, s34
	v_add_u32_e32 v144, s54, v155
	s_add_u32 vcc_lo, s4, s0
	s_addc_u32 vcc_hi, s5, s1
	s_mov_b32 m0, s51
	ds_read_b128 v[212:215], v144
	ds_read_b128 v[216:219], v144 offset:1024
	ds_read_b128 v[220:223], v144 offset:2048
	ds_read_b128 v[224:227], v144 offset:3072
	global_load_lds_dwordx4 v136, s[4:5]
	s_add_i32 m0, s51, 0x2000
	s_nop 0
	global_load_lds_dwordx4 v132, s[4:5]
	s_barrier
	s_waitcnt lgkmcnt(0)
	s_waitcnt lgkmcnt(0)
	v_mfma_f32_16x16x32_bf16 v[116:119], v[212:215], v[164:167], v[116:119]
	v_mfma_f32_16x16x32_bf16 v[112:115], v[220:223], v[164:167], v[112:115]
	v_mfma_f32_16x16x32_bf16 v[100:103], v[212:215], v[172:175], v[100:103]
	v_mfma_f32_16x16x32_bf16 v[96:99], v[220:223], v[172:175], v[96:99]
	v_mfma_f32_16x16x32_bf16 v[84:87], v[212:215], v[196:199], v[84:87]
	v_mfma_f32_16x16x32_bf16 v[80:83], v[220:223], v[196:199], v[80:83]
	v_mfma_f32_16x16x32_bf16 v[68:71], v[212:215], v[204:207], v[68:71]
	v_mfma_f32_16x16x32_bf16 v[64:67], v[220:223], v[204:207], v[64:67]
	v_mfma_f32_16x16x32_bf16 v[116:119], v[216:219], v[168:171], v[116:119]
	v_mfma_f32_16x16x32_bf16 v[112:115], v[224:227], v[168:171], v[112:115]
	v_mfma_f32_16x16x32_bf16 v[100:103], v[216:219], v[176:179], v[100:103]
	v_mfma_f32_16x16x32_bf16 v[96:99], v[224:227], v[176:179], v[96:99]
	v_mfma_f32_16x16x32_bf16 v[84:87], v[216:219], v[200:203], v[84:87]
	v_mfma_f32_16x16x32_bf16 v[80:83], v[224:227], v[200:203], v[80:83]
	v_mfma_f32_16x16x32_bf16 v[68:71], v[216:219], v[208:211], v[68:71]
	v_mfma_f32_16x16x32_bf16 v[64:67], v[224:227], v[208:211], v[64:67]
	s_mov_b32 m0, s40
	s_add_u32 s100, s20, s0
	s_addc_u32 s101, s21, s1
	s_barrier
	ds_read_b128 v[164:167], v158 offset:16384
	ds_read_b128 v[168:171], v158 offset:17408
	ds_read_b128 v[172:175], v158 offset:18432
	ds_read_b128 v[176:179], v158 offset:19456
	ds_read_b128 v[196:199], v158 offset:20480
	ds_read_b128 v[200:203], v158 offset:21504
	ds_read_b128 v[204:207], v158 offset:22528
	ds_read_b128 v[208:211], v158 offset:23552
	global_load_lds_dwordx4 v138, s[20:21]
	s_mov_b32 m0, s41
	s_nop 0
	global_load_lds_dwordx4 v134, s[20:21]
	s_barrier
	s_waitcnt lgkmcnt(0)
	s_waitcnt lgkmcnt(0)
	v_mfma_f32_16x16x32_bf16 v[60:63], v[128:131], v[164:167], v[60:63]
	v_mfma_f32_16x16x32_bf16 v[56:59], v[150:153], v[164:167], v[56:59]
	v_mfma_f32_16x16x32_bf16 v[44:47], v[128:131], v[172:175], v[44:47]
	v_mfma_f32_16x16x32_bf16 v[40:43], v[150:153], v[172:175], v[40:43]
	v_mfma_f32_16x16x32_bf16 v[28:31], v[128:131], v[196:199], v[28:31]
	v_mfma_f32_16x16x32_bf16 v[24:27], v[150:153], v[196:199], v[24:27]
	v_mfma_f32_16x16x32_bf16 v[12:15], v[128:131], v[204:207], v[12:15]
	v_mfma_f32_16x16x32_bf16 v[8:11], v[150:153], v[204:207], v[8:11]
	v_mfma_f32_16x16x32_bf16 v[60:63], v[146:149], v[168:171], v[60:63]
	v_mfma_f32_16x16x32_bf16 v[56:59], v[160:163], v[168:171], v[56:59]
	v_mfma_f32_16x16x32_bf16 v[44:47], v[146:149], v[176:179], v[44:47]
	v_mfma_f32_16x16x32_bf16 v[40:43], v[160:163], v[176:179], v[40:43]
	v_mfma_f32_16x16x32_bf16 v[28:31], v[146:149], v[200:203], v[28:31]
	v_mfma_f32_16x16x32_bf16 v[24:27], v[160:163], v[200:203], v[24:27]
	v_mfma_f32_16x16x32_bf16 v[12:15], v[146:149], v[208:211], v[12:15]
	v_mfma_f32_16x16x32_bf16 v[8:11], v[160:163], v[208:211], v[8:11]
	s_barrier
	s_add_u32 s52, s4, 0x40000
	s_addc_u32 s53, s5, 0
	s_add_i32 s51, s54, s34
	s_mov_b32 m0, s51
	s_nop 0
	global_load_lds_dwordx4 v136, s[52:53]
	s_add_i32 m0, s51, 0x2000
	s_nop 0
	global_load_lds_dwordx4 v132, s[52:53]
	s_waitcnt vmcnt(6)
	s_barrier
; #define PG8_STAGE(bufoff, gbase, voff) do { _Pragma("unroll") for (int _i = 0; _i < 2; ++_i) \
;     __builtin_amdgcn_global_load_lds((const unsigned*)((const char*)(gbase) + (voff)[_i]), (LAS unsigned*)(lds + (bufoff) + ldsw + _i * 8192), 16, 0, 0); } while (0)
; #define PG8_LDA(dst, b, h) do { _Pragma("unroll") for (int m = 0; m < 4; ++m) _Pragma("unroll") for (int k = 0; k < 2; ++k) dst[m][k] = *(const LAS bf16x8*)(lds + PG8_SA(b, h) + aoff + m * 2048 + k * 1024); } while (0)
; #define PG8_LDB(dst, b, h) do { _Pragma("unroll") for (int n = 0; n < 2; ++n) _Pragma("unroll") for (int k = 0; k < 2; ++k) dst[n][k] = *(const LAS bf16x8*)(lds + PG8_SB(b, h) + boff + n * 2048 + k * 1024); } while (0)
; #define PG8_WAIT_V(n) asm volatile("s_waitcnt vmcnt(" #n ")" ::: "memory")
; template <class Epi, class Sched>
; DI void gemm_phase(LAS unsigned char* lds, const Gemm g, const Sched& S, const Epi& E) {
;     ...
;     for (int t = 0; t < nt; t += 2) {
;       const bool last = (t == nt - 2);
;       const char* a1 = cA + (size_t)(t + 1) * kstep;
;       const char* a2 = last ? nA : cA + (size_t)(t + 2) * kstep; const char* b2 = last ? nB : cB + (size_t)(t + 2) * kstep;
;       const char* a3 = a2 + kstep; const char* b3 = b2 + kstep;
;       PG8_LDB(B0, 0, 0); PG8_SCHED; PG8_LDA(At, 0, 0); PG8_STAGE(PG8_SA(1, 1), a1 + hstep, voffA);
;       PG8_WAIT_L(8); PG8_BAR; PG8_WAIT_L(0); PG8_MMA(0, 0, At, B0); PG8_BAR; PG8_SCHED;
;       PG8_LDB(B1, 0, 1); PG8_STAGE(PG8_SB(0, 0), b2, voffB);
;       PG8_BAR; PG8_WAIT_L(0); PG8_MMA(0, 1, At, B1); PG8_BAR;
;       PG8_LDA(At, 0, 1); PG8_STAGE(PG8_SA(0, 0), a2, voffA);
;       PG8_BAR; PG8_WAIT_L(0); PG8_MMA(1, 0, At, B0); PG8_BAR; PG8_SCHED;
;       PG8_STAGE(PG8_SB(0, 1), b2 + hstep, voffB);
;       PG8_WAIT_V(6); PG8_BAR; PG8_MMA(1, 1, At, B1); PG8_BAR;
;       PG8_LDB(B0, 1, 0); PG8_SCHED; PG8_LDA(At, 1, 0); PG8_STAGE(PG8_SA(0, 1), a2 + hstep, voffA);
;       PG8_WAIT_L(8); PG8_BAR; PG8_WAIT_L(0); PG8_MMA(0, 0, At, B0); PG8_BAR; PG8_SCHED;
;       PG8_LDB(B1, 1, 1); PG8_STAGE(PG8_SB(1, 0), b3, voffB);
;       PG8_BAR; PG8_WAIT_L(0); PG8_MMA(0, 1, At, B1); PG8_BAR;
;       PG8_LDA(At, 1, 1); PG8_STAGE(PG8_SA(1, 0), a3, voffA);
;       PG8_BAR; PG8_WAIT_L(0); PG8_MMA(1, 0, At, B0); PG8_BAR; PG8_SCHED;
;       PG8_STAGE(PG8_SB(1, 1), b3 + hstep, voffB);
;       PG8_WAIT_V(6); PG8_BAR; PG8_MMA(1, 1, At, B1); PG8_BAR;
	v_mfma_f32_16x16x32_bf16 v[52:55], v[212:215], v[164:167], v[52:55]
	v_mfma_f32_16x16x32_bf16 v[48:51], v[220:223], v[164:167], v[48:51]
	v_mfma_f32_16x16x32_bf16 v[36:39], v[212:215], v[172:175], v[36:39]
	v_mfma_f32_16x16x32_bf16 v[32:35], v[220:223], v[172:175], v[32:35]
	v_mfma_f32_16x16x32_bf16 v[20:23], v[212:215], v[196:199], v[20:23]
	v_mfma_f32_16x16x32_bf16 v[16:19], v[220:223], v[196:199], v[16:19]
	v_mfma_f32_16x16x32_bf16 v[4:7], v[212:215], v[204:207], v[4:7]
	v_mfma_f32_16x16x32_bf16 v[0:3], v[220:223], v[204:207], v[0:3]
	v_mfma_f32_16x16x32_bf16 v[52:55], v[216:219], v[168:171], v[52:55]
	v_mfma_f32_16x16x32_bf16 v[48:51], v[224:227], v[168:171], v[48:51]
	v_mfma_f32_16x16x32_bf16 v[36:39], v[216:219], v[176:179], v[36:39]
	v_mfma_f32_16x16x32_bf16 v[32:35], v[224:227], v[176:179], v[32:35]
	v_mfma_f32_16x16x32_bf16 v[20:23], v[216:219], v[200:203], v[20:23]
	v_mfma_f32_16x16x32_bf16 v[16:19], v[224:227], v[200:203], v[16:19]
	v_mfma_f32_16x16x32_bf16 v[4:7], v[216:219], v[208:211], v[4:7]
	v_mfma_f32_16x16x32_bf16 v[0:3], v[224:227], v[208:211], v[0:3]
	s_add_i32 s51, 0, 0x18000
	v_add_u32_e32 v144, s51, v155
	s_barrier
	ds_read_b128 v[128:131], v144
	ds_read_b128 v[146:149], v144 offset:1024
	ds_read_b128 v[150:153], v144 offset:2048
	ds_read_b128 v[160:163], v144 offset:3072
	s_add_u32 s20, s20, 0x40000
	s_addc_u32 s21, s21, 0
	s_mov_b32 m0, s42
	ds_read_b128 v[164:167], v158 offset:32768
	ds_read_b128 v[168:171], v158 offset:33792
	ds_read_b128 v[172:175], v158 offset:34816
	ds_read_b128 v[176:179], v158 offset:35840
	ds_read_b128 v[196:199], v158 offset:36864
	ds_read_b128 v[200:203], v158 offset:37888
	ds_read_b128 v[204:207], v158 offset:38912
	ds_read_b128 v[208:211], v158 offset:39936
	global_load_lds_dwordx4 v138, s[20:21]
	s_mov_b32 m0, s43
	s_nop 0
	global_load_lds_dwordx4 v134, s[20:21]
	s_waitcnt lgkmcnt(8)
	s_barrier
	s_waitcnt lgkmcnt(0)
	s_waitcnt lgkmcnt(0)
	v_mfma_f32_16x16x32_bf16 v[124:127], v[128:131], v[164:167], v[124:127]
	v_mfma_f32_16x16x32_bf16 v[120:123], v[150:153], v[164:167], v[120:123]
	v_mfma_f32_16x16x32_bf16 v[108:111], v[128:131], v[172:175], v[108:111]
	v_mfma_f32_16x16x32_bf16 v[104:107], v[150:153], v[172:175], v[104:107]
	v_mfma_f32_16x16x32_bf16 v[92:95], v[128:131], v[196:199], v[92:95]
	v_mfma_f32_16x16x32_bf16 v[88:91], v[150:153], v[196:199], v[88:91]
	v_mfma_f32_16x16x32_bf16 v[76:79], v[128:131], v[204:207], v[76:79]
	v_mfma_f32_16x16x32_bf16 v[72:75], v[150:153], v[204:207], v[72:75]
	v_mfma_f32_16x16x32_bf16 v[124:127], v[146:149], v[168:171], v[124:127]
	v_mfma_f32_16x16x32_bf16 v[120:123], v[160:163], v[168:171], v[120:123]
	v_mfma_f32_16x16x32_bf16 v[108:111], v[146:149], v[176:179], v[108:111]
	v_mfma_f32_16x16x32_bf16 v[104:107], v[160:163], v[176:179], v[104:107]
	v_mfma_f32_16x16x32_bf16 v[92:95], v[146:149], v[200:203], v[92:95]
	v_mfma_f32_16x16x32_bf16 v[88:91], v[160:163], v[200:203], v[88:91]
	v_mfma_f32_16x16x32_bf16 v[76:79], v[146:149], v[208:211], v[76:79]
	v_mfma_f32_16x16x32_bf16 v[72:75], v[160:163], v[208:211], v[72:75]
	s_barrier
	s_add_i32 s20, 0, 0x1c000
	s_add_i32 s21, s51, s34
	v_add_u32_e32 v144, s20, v155
	s_mov_b32 m0, s21
	ds_read_b128 v[212:215], v144
	ds_read_b128 v[216:219], v144 offset:1024
	ds_read_b128 v[220:223], v144 offset:2048
	ds_read_b128 v[224:227], v144 offset:3072
	global_load_lds_dwordx4 v136, vcc
	s_add_i32 m0, s21, 0x2000
	s_nop 0
	global_load_lds_dwordx4 v132, vcc
	s_barrier
	s_waitcnt lgkmcnt(0)
	s_waitcnt lgkmcnt(0)
	v_mfma_f32_16x16x32_bf16 v[116:119], v[212:215], v[164:167], v[116:119]
	v_mfma_f32_16x16x32_bf16 v[112:115], v[220:223], v[164:167], v[112:115]
	v_mfma_f32_16x16x32_bf16 v[100:103], v[212:215], v[172:175], v[100:103]
	v_mfma_f32_16x16x32_bf16 v[96:99], v[220:223], v[172:175], v[96:99]
	v_mfma_f32_16x16x32_bf16 v[84:87], v[212:215], v[196:199], v[84:87]
	v_mfma_f32_16x16x32_bf16 v[80:83], v[220:223], v[196:199], v[80:83]
	v_mfma_f32_16x16x32_bf16 v[68:71], v[212:215], v[204:207], v[68:71]
	v_mfma_f32_16x16x32_bf16 v[64:67], v[220:223], v[204:207], v[64:67]
	v_mfma_f32_16x16x32_bf16 v[116:119], v[216:219], v[168:171], v[116:119]
	v_mfma_f32_16x16x32_bf16 v[112:115], v[224:227], v[168:171], v[112:115]
	v_mfma_f32_16x16x32_bf16 v[100:103], v[216:219], v[176:179], v[100:103]
	v_mfma_f32_16x16x32_bf16 v[96:99], v[224:227], v[176:179], v[96:99]
	v_mfma_f32_16x16x32_bf16 v[84:87], v[216:219], v[200:203], v[84:87]
	v_mfma_f32_16x16x32_bf16 v[80:83], v[224:227], v[200:203], v[80:83]
	v_mfma_f32_16x16x32_bf16 v[68:71], v[216:219], v[208:211], v[68:71]
	v_mfma_f32_16x16x32_bf16 v[64:67], v[224:227], v[208:211], v[64:67]
	s_mov_b32 m0, s46
	s_barrier
; #define PG8_STAGE(bufoff, gbase, voff) do { _Pragma("unroll") for (int _i = 0; _i < 2; ++_i) \
;     __builtin_amdgcn_global_load_lds((const unsigned*)((const char*)(gbase) + (voff)[_i]), (LAS unsigned*)(lds + (bufoff) + ldsw + _i * 8192), 16, 0, 0); } while (0)
; #define PG8_LDA(dst, b, h) do { _Pragma("unroll") for (int m = 0; m < 4; ++m) _Pragma("unroll") for (int k = 0; k < 2; ++k) dst[m][k] = *(const LAS bf16x8*)(lds + PG8_SA(b, h) + aoff + m * 2048 + k * 1024); } while (0)
; #define PG8_LDB(dst, b, h) do { _Pragma("unroll") for (int n = 0; n < 2; ++n) _Pragma("unroll") for (int k = 0; k < 2; ++k) dst[n][k] = *(const LAS bf16x8*)(lds + PG8_SB(b, h) + boff + n * 2048 + k * 1024); } while (0)
; #define PG8_WAIT_V(n) asm volatile("s_waitcnt vmcnt(" #n ")" ::: "memory")
; #define PG8_WAIT_L(n) asm volatile("s_waitcnt lgkmcnt(" #n ")" ::: "memory")
; #define PG8_BAR __builtin_amdgcn_s_barrier()
; template <class Epi, class Sched>
; DI void gemm_phase(LAS unsigned char* lds, const Gemm g, const Sched& S, const Epi& E) {
;     ...
;       PG8_WAIT_V(6); PG8_BAR; PG8_MMA(1, 1, At, B1); PG8_BAR;
;       PG8_LDB(B0, 1, 0); PG8_SCHED; PG8_LDA(At, 1, 0); PG8_STAGE(PG8_SA(0, 1), a2 + hstep, voffA);
;       PG8_WAIT_L(8); PG8_BAR; PG8_WAIT_L(0); PG8_MMA(0, 0, At, B0); PG8_BAR; PG8_SCHED;
;       PG8_LDB(B1, 1, 1); PG8_STAGE(PG8_SB(1, 0), b3, voffB);
;       PG8_BAR; PG8_WAIT_L(0); PG8_MMA(0, 1, At, B1); PG8_BAR;
;       PG8_LDA(At, 1, 1); PG8_STAGE(PG8_SA(1, 0), a3, voffA);
;       PG8_BAR; PG8_WAIT_L(0); PG8_MMA(1, 0, At, B0); PG8_BAR; PG8_SCHED;
;       PG8_STAGE(PG8_SB(1, 1), b3 + hstep, voffB);
;       PG8_WAIT_V(6); PG8_BAR; PG8_MMA(1, 1, At, B1); PG8_BAR;
;   DI void operator()(const f32x4 (&acc)[2][2][4][2], const pg8::Unit& u, int wr, int wc, int fr_, int fq_) const {
;     ...
;             } else if (EPI == EPI_CIN) {
;               if (n == 0) {
;                 const int gb = u.pn * 256 + bj * 128 + wc * 32;
;                 const int f8 = gb + 8 * fq;
;                 const f32x4 v1 = acc[ai][bj][m][1];
;                 if (gb < 1024) st_bf8((u16*)(big + O_QD) + (size_t)token * 1024 + f8, v, v1, rinv * (0.125f * LOG2E));
;                 else if (gb < 2048) st_bf8((u16*)(big + O_KD) + (size_t)token * 1024 + (f8 - 1024), v, v1, rinv);
;                 else st_bf8((u16*)(big + O_VDT) + (size_t)token * 1024 + (f8 - 2048), v, v1, rinv);
;               }
	ds_read_b128 v[164:167], v158 offset:49152
	ds_read_b128 v[168:171], v158 offset:50176
	ds_read_b128 v[172:175], v158 offset:51200
	ds_read_b128 v[176:179], v158 offset:52224
	ds_read_b128 v[196:199], v158 offset:53248
	ds_read_b128 v[200:203], v158 offset:54272
	ds_read_b128 v[204:207], v158 offset:55296
	ds_read_b128 v[208:211], v158 offset:56320
	global_load_lds_dwordx4 v138, s[100:101]
	s_mov_b32 m0, s47
	s_nop 0
	global_load_lds_dwordx4 v134, s[100:101]
	s_barrier
	s_waitcnt lgkmcnt(0)
	s_waitcnt lgkmcnt(0)
	v_mfma_f32_16x16x32_bf16 v[60:63], v[128:131], v[164:167], v[60:63]
	v_mfma_f32_16x16x32_bf16 v[56:59], v[150:153], v[164:167], v[56:59]
	v_mfma_f32_16x16x32_bf16 v[44:47], v[128:131], v[172:175], v[44:47]
	v_mfma_f32_16x16x32_bf16 v[40:43], v[150:153], v[172:175], v[40:43]
	v_mfma_f32_16x16x32_bf16 v[28:31], v[128:131], v[196:199], v[28:31]
	v_mfma_f32_16x16x32_bf16 v[24:27], v[150:153], v[196:199], v[24:27]
	v_mfma_f32_16x16x32_bf16 v[12:15], v[128:131], v[204:207], v[12:15]
	v_mfma_f32_16x16x32_bf16 v[8:11], v[150:153], v[204:207], v[8:11]
	v_mfma_f32_16x16x32_bf16 v[60:63], v[146:149], v[168:171], v[60:63]
	v_mfma_f32_16x16x32_bf16 v[56:59], v[160:163], v[168:171], v[56:59]
	v_mfma_f32_16x16x32_bf16 v[44:47], v[146:149], v[176:179], v[44:47]
	v_mfma_f32_16x16x32_bf16 v[40:43], v[160:163], v[176:179], v[40:43]
	v_mfma_f32_16x16x32_bf16 v[28:31], v[146:149], v[200:203], v[28:31]
	v_mfma_f32_16x16x32_bf16 v[24:27], v[160:163], v[200:203], v[24:27]
	v_mfma_f32_16x16x32_bf16 v[12:15], v[146:149], v[208:211], v[12:15]
	v_mfma_f32_16x16x32_bf16 v[8:11], v[160:163], v[208:211], v[8:11]
	s_barrier
	s_add_u32 s4, s4, 0x40080
	s_addc_u32 s5, s5, 0
	s_add_i32 s20, s20, s34
	s_mov_b32 m0, s20
	s_nop 0
	global_load_lds_dwordx4 v136, s[4:5]
	s_add_i32 m0, s20, 0x2000
	s_nop 0
	global_load_lds_dwordx4 v132, s[4:5]
	s_waitcnt vmcnt(6)
	s_barrier
	v_mfma_f32_16x16x32_bf16 v[52:55], v[212:215], v[164:167], v[52:55]
	v_mfma_f32_16x16x32_bf16 v[48:51], v[220:223], v[164:167], v[48:51]
	v_mfma_f32_16x16x32_bf16 v[36:39], v[212:215], v[172:175], v[36:39]
	v_mfma_f32_16x16x32_bf16 v[32:35], v[220:223], v[172:175], v[32:35]
	v_mfma_f32_16x16x32_bf16 v[20:23], v[212:215], v[196:199], v[20:23]
	v_mfma_f32_16x16x32_bf16 v[16:19], v[220:223], v[196:199], v[16:19]
	v_mfma_f32_16x16x32_bf16 v[4:7], v[212:215], v[204:207], v[4:7]
	v_mfma_f32_16x16x32_bf16 v[0:3], v[220:223], v[204:207], v[0:3]
	v_mfma_f32_16x16x32_bf16 v[52:55], v[216:219], v[168:171], v[52:55]
	v_mfma_f32_16x16x32_bf16 v[48:51], v[224:227], v[168:171], v[48:51]
	v_mfma_f32_16x16x32_bf16 v[36:39], v[216:219], v[176:179], v[36:39]
	v_mfma_f32_16x16x32_bf16 v[32:35], v[224:227], v[176:179], v[32:35]
	v_mfma_f32_16x16x32_bf16 v[20:23], v[216:219], v[200:203], v[20:23]
	v_mfma_f32_16x16x32_bf16 v[16:19], v[224:227], v[200:203], v[16:19]
	v_mfma_f32_16x16x32_bf16 v[4:7], v[216:219], v[208:211], v[4:7]
	v_mfma_f32_16x16x32_bf16 v[0:3], v[224:227], v[208:211], v[0:3]
	s_add_i32 s50, s50, 2
	s_add_u32 s2, s2, 0x100
	s_addc_u32 s3, s3, 0
	s_add_u32 s37, s37, 0x100
	s_addc_u32 s49, s49, 0
	s_cmp_gt_u32 s50, 13
	s_barrier
	s_cbranch_scc0 .LBB0_370
	v_mov_b32_e32 v128, v182
	s_lshl_b32 s2, s22, 10
	v_and_or_b32 v160, v128, 15, s44
	v_lshrrev_b32_e32 v128, 1, v128
	s_add_i32 s2, s2, 0
	v_and_b32_e32 v146, 24, v128
	v_lshl_add_u32 v128, v160, 2, s2
	v_add_u32_e32 v159, 0x20000, v128
	s_lshl_b32 s13, s28, 8
	s_lshl_b32 s3, s23, 8
	ds_read_b32 v154, v159
	v_add_u32_e32 v150, s13, v160
	s_or_b32 s20, s3, s45
	v_ashrrev_i32_e32 v151, 31, v150
	s_cmpk_gt_i32 s20, 0x3ff
	v_lshlrev_b64 v[128:129], 11, v[150:151]
	v_or_b32_e32 v148, s20, v146
	s_cselect_b64 s[4:5], -1, 0
	s_cmpk_gt_u32 s3, 0x7ff
	s_cselect_b64 s[2:3], -1, 0
	v_mov_b32_e32 v144, v148
	v_lshl_add_u64 v[152:153], s[10:11], 0, v[128:129]
	s_mov_b64 s[22:23], -1
	s_and_b64 vcc, exec, s[4:5]
	s_cbranch_vccz .LBB0_377
	s_waitcnt lgkmcnt(0)
	v_pk_mul_f32 v[128:129], v[124:125], v[154:155] op_sel_hi:[1,0]
	v_pk_mul_f32 v[130:131], v[126:127], v[154:155] op_sel_hi:[1,0]
	v_cvt_pk_bf16_f32 v128, v128, v129
	v_cvt_pk_bf16_f32 v129, v130, v131
	v_pk_mul_f32 v[130:131], v[120:121], v[154:155] op_sel_hi:[1,0]
	v_pk_mul_f32 v[162:163], v[122:123], v[154:155] op_sel_hi:[1,0]
	v_lshl_add_u64 v[156:157], v[144:145], 1, v[152:153]
	v_cvt_pk_bf16_f32 v130, v130, v131
	v_cvt_pk_bf16_f32 v131, v162, v163
	s_and_b64 vcc, exec, s[2:3]
	s_cbranch_vccz .LBB0_374
	v_add_co_u32_e32 v162, vcc, 0x7fff000, v156
	s_mov_b64 s[22:23], 0
	s_nop 0
	v_addc_co_u32_e32 v163, vcc, 0, v157, vcc
	global_store_dwordx4 v[162:163], v[128:131], off

; #define PG8_STAGE(bufoff, gbase, voff) do { _Pragma("unroll") for (int _i = 0; _i < 2; ++_i) \
;     __builtin_amdgcn_global_load_lds((const unsigned*)((const char*)(gbase) + (voff)[_i]), (LAS unsigned*)(lds + (bufoff) + ldsw + _i * 8192), 16, 0, 0); } while (0)
; #define PG8_LDA(dst, b, h) do { _Pragma("unroll") for (int m = 0; m < 4; ++m) _Pragma("unroll") for (int k = 0; k < 2; ++k) dst[m][k] = *(const LAS bf16x8*)(lds + PG8_SA(b, h) + aoff + m * 2048 + k * 1024); } while (0)
; #define PG8_LDB(dst, b, h) do { _Pragma("unroll") for (int n = 0; n < 2; ++n) _Pragma("unroll") for (int k = 0; k < 2; ++k) dst[n][k] = *(const LAS bf16x8*)(lds + PG8_SB(b, h) + boff + n * 2048 + k * 1024); } while (0)
; #define PG8_WAIT_V(n) asm volatile("s_waitcnt vmcnt(" #n ")" ::: "memory")
; template <class Epi, class Sched>
; DI void gemm_phase(LAS unsigned char* lds, const Gemm g, const Sched& S, const Epi& E) {
;     ...
;     for (int t = 0; t < nt; t += 2) {
;       const bool last = (t == nt - 2);
;       const char* a1 = cA + (size_t)(t + 1) * kstep;
;       const char* a2 = last ? nA : cA + (size_t)(t + 2) * kstep; const char* b2 = last ? nB : cB + (size_t)(t + 2) * kstep;
;       const char* a3 = a2 + kstep; const char* b3 = b2 + kstep;
;       PG8_LDB(B0, 0, 0); PG8_SCHED; PG8_LDA(At, 0, 0); PG8_STAGE(PG8_SA(1, 1), a1 + hstep, voffA);
;       PG8_WAIT_L(8); PG8_BAR; PG8_WAIT_L(0); PG8_MMA(0, 0, At, B0); PG8_BAR; PG8_SCHED;
;       PG8_LDB(B1, 0, 1); PG8_STAGE(PG8_SB(0, 0), b2, voffB);
;       PG8_BAR; PG8_WAIT_L(0); PG8_MMA(0, 1, At, B1); PG8_BAR;
;       PG8_LDA(At, 0, 1); PG8_STAGE(PG8_SA(0, 0), a2, voffA);
;       PG8_BAR; PG8_WAIT_L(0); PG8_MMA(1, 0, At, B0); PG8_BAR; PG8_SCHED;
;       PG8_STAGE(PG8_SB(0, 1), b2 + hstep, voffB);
;       PG8_WAIT_V(6); PG8_BAR; PG8_MMA(1, 1, At, B1); PG8_BAR;
;       PG8_LDB(B0, 1, 0); PG8_SCHED; PG8_LDA(At, 1, 0); PG8_STAGE(PG8_SA(0, 1), a2 + hstep, voffA);
;       PG8_WAIT_L(8); PG8_BAR; PG8_WAIT_L(0); PG8_MMA(0, 0, At, B0); PG8_BAR; PG8_SCHED;
;       PG8_LDB(B1, 1, 1); PG8_STAGE(PG8_SB(1, 0), b3, voffB);
;       PG8_BAR; PG8_WAIT_L(0); PG8_MMA(0, 1, At, B1); PG8_BAR;
;       PG8_LDA(At, 1, 1); PG8_STAGE(PG8_SA(1, 0), a3, voffA);
;       PG8_BAR; PG8_WAIT_L(0); PG8_MMA(1, 0, At, B0); PG8_BAR; PG8_SCHED;
;       PG8_STAGE(PG8_SB(1, 1), b3 + hstep, voffB);
;       PG8_WAIT_V(6); PG8_BAR; PG8_MMA(1, 1, At, B1); PG8_BAR;
.LBB0_689:
	s_add_u32 s22, s20, 0xfffc0080
	s_addc_u32 s23, s21, -1
	s_add_i32 s42, 0, 0x10000
	v_add_u32_e32 v144, s42, v196
	ds_read_b128 v[128:131], v144
	ds_read_b128 v[132:135], v144 offset:1024
	ds_read_b128 v[150:153], v144 offset:2048
	ds_read_b128 v[154:157], v144 offset:3072
	s_cmp_eq_u32 s41, 12
	s_cselect_b32 s29, s13, s23
	s_cselect_b32 s28, s37, s22
	s_cselect_b32 s23, s15, s40
	s_cselect_b32 s22, s38, s39
	s_add_i32 m0, s56, 0xc000
	ds_read_b128 v[158:161], v197
	ds_read_b128 v[162:165], v197 offset:1024
	ds_read_b128 v[166:169], v197 offset:2048
	ds_read_b128 v[170:173], v197 offset:3072
	ds_read_b128 v[174:177], v197 offset:4096
	ds_read_b128 v[178:181], v197 offset:5120
	ds_read_b128 v[198:201], v197 offset:6144
	ds_read_b128 v[202:205], v197 offset:7168
	global_load_lds_dwordx4 v146, s[20:21]
	s_add_i32 m0, s56, 0xe000
	s_nop 0
	global_load_lds_dwordx4 v148, s[20:21]
	s_waitcnt lgkmcnt(8)
	s_barrier
	s_waitcnt lgkmcnt(0)
	s_waitcnt lgkmcnt(0)
	v_mfma_f32_16x16x32_bf16 v[124:127], v[128:131], v[158:161], v[124:127]
	v_mfma_f32_16x16x32_bf16 v[120:123], v[150:153], v[158:161], v[120:123]
	v_mfma_f32_16x16x32_bf16 v[108:111], v[128:131], v[166:169], v[108:111]
	v_mfma_f32_16x16x32_bf16 v[104:107], v[150:153], v[166:169], v[104:107]
	v_mfma_f32_16x16x32_bf16 v[92:95], v[128:131], v[174:177], v[92:95]
	v_mfma_f32_16x16x32_bf16 v[88:91], v[150:153], v[174:177], v[88:91]
	v_mfma_f32_16x16x32_bf16 v[76:79], v[128:131], v[198:201], v[76:79]
	v_mfma_f32_16x16x32_bf16 v[72:75], v[150:153], v[198:201], v[72:75]
	v_mfma_f32_16x16x32_bf16 v[124:127], v[132:135], v[162:165], v[124:127]
	v_mfma_f32_16x16x32_bf16 v[120:123], v[154:157], v[162:165], v[120:123]
	v_mfma_f32_16x16x32_bf16 v[108:111], v[132:135], v[170:173], v[108:111]
	v_mfma_f32_16x16x32_bf16 v[104:107], v[154:157], v[170:173], v[104:107]
	v_mfma_f32_16x16x32_bf16 v[92:95], v[132:135], v[178:181], v[92:95]
	v_mfma_f32_16x16x32_bf16 v[88:91], v[154:157], v[178:181], v[88:91]
	v_mfma_f32_16x16x32_bf16 v[76:79], v[132:135], v[202:205], v[76:79]
	v_mfma_f32_16x16x32_bf16 v[72:75], v[154:157], v[202:205], v[72:75]
	s_barrier
	s_add_i32 s44, 0, 0x14000
	s_add_i32 s42, s42, s52
	v_add_u32_e32 v144, s44, v196
	s_add_u32 vcc_lo, s22, s0
	s_addc_u32 vcc_hi, s23, s1
	s_mov_b32 m0, s42
	ds_read_b128 v[206:209], v144
	ds_read_b128 v[210:213], v144 offset:1024
	ds_read_b128 v[214:217], v144 offset:2048
	ds_read_b128 v[218:221], v144 offset:3072
	global_load_lds_dwordx4 v140, s[22:23]
	s_add_i32 m0, s42, 0x2000
	s_nop 0
	global_load_lds_dwordx4 v136, s[22:23]
	s_barrier
	s_waitcnt lgkmcnt(0)
	s_waitcnt lgkmcnt(0)
	v_mfma_f32_16x16x32_bf16 v[116:119], v[206:209], v[158:161], v[116:119]
	v_mfma_f32_16x16x32_bf16 v[112:115], v[214:217], v[158:161], v[112:115]
	v_mfma_f32_16x16x32_bf16 v[100:103], v[206:209], v[166:169], v[100:103]
	v_mfma_f32_16x16x32_bf16 v[96:99], v[214:217], v[166:169], v[96:99]
	v_mfma_f32_16x16x32_bf16 v[84:87], v[206:209], v[174:177], v[84:87]
	v_mfma_f32_16x16x32_bf16 v[80:83], v[214:217], v[174:177], v[80:83]
	v_mfma_f32_16x16x32_bf16 v[68:71], v[206:209], v[198:201], v[68:71]
	v_mfma_f32_16x16x32_bf16 v[64:67], v[214:217], v[198:201], v[64:67]
	v_mfma_f32_16x16x32_bf16 v[116:119], v[210:213], v[162:165], v[116:119]
	v_mfma_f32_16x16x32_bf16 v[112:115], v[218:221], v[162:165], v[112:115]
	v_mfma_f32_16x16x32_bf16 v[100:103], v[210:213], v[170:173], v[100:103]
	v_mfma_f32_16x16x32_bf16 v[96:99], v[218:221], v[170:173], v[96:99]
	v_mfma_f32_16x16x32_bf16 v[84:87], v[210:213], v[178:181], v[84:87]
	v_mfma_f32_16x16x32_bf16 v[80:83], v[218:221], v[178:181], v[80:83]
	v_mfma_f32_16x16x32_bf16 v[68:71], v[210:213], v[202:205], v[68:71]
	v_mfma_f32_16x16x32_bf16 v[64:67], v[218:221], v[202:205], v[64:67]
	s_mov_b32 m0, s56
	s_add_u32 s100, s28, s0
	s_addc_u32 s101, s29, s1
	s_barrier
	ds_read_b128 v[158:161], v197 offset:16384
	ds_read_b128 v[162:165], v197 offset:17408
	ds_read_b128 v[166:169], v197 offset:18432
	ds_read_b128 v[170:173], v197 offset:19456
	ds_read_b128 v[174:177], v197 offset:20480
	ds_read_b128 v[178:181], v197 offset:21504
	ds_read_b128 v[198:201], v197 offset:22528
	ds_read_b128 v[202:205], v197 offset:23552
	global_load_lds_dwordx4 v142, s[28:29]
	s_mov_b32 m0, s57
	s_nop 0
	global_load_lds_dwordx4 v138, s[28:29]
	s_barrier
	s_waitcnt lgkmcnt(0)
	s_waitcnt lgkmcnt(0)
	v_mfma_f32_16x16x32_bf16 v[60:63], v[128:131], v[158:161], v[60:63]
	v_mfma_f32_16x16x32_bf16 v[56:59], v[150:153], v[158:161], v[56:59]
	v_mfma_f32_16x16x32_bf16 v[44:47], v[128:131], v[166:169], v[44:47]
	v_mfma_f32_16x16x32_bf16 v[40:43], v[150:153], v[166:169], v[40:43]
	v_mfma_f32_16x16x32_bf16 v[28:31], v[128:131], v[174:177], v[28:31]
	v_mfma_f32_16x16x32_bf16 v[24:27], v[150:153], v[174:177], v[24:27]
	v_mfma_f32_16x16x32_bf16 v[12:15], v[128:131], v[198:201], v[12:15]
	v_mfma_f32_16x16x32_bf16 v[8:11], v[150:153], v[198:201], v[8:11]
	v_mfma_f32_16x16x32_bf16 v[60:63], v[132:135], v[162:165], v[60:63]
	v_mfma_f32_16x16x32_bf16 v[56:59], v[154:157], v[162:165], v[56:59]
	v_mfma_f32_16x16x32_bf16 v[44:47], v[132:135], v[170:173], v[44:47]
	v_mfma_f32_16x16x32_bf16 v[40:43], v[154:157], v[170:173], v[40:43]
	v_mfma_f32_16x16x32_bf16 v[28:31], v[132:135], v[178:181], v[28:31]
	v_mfma_f32_16x16x32_bf16 v[24:27], v[154:157], v[178:181], v[24:27]
	v_mfma_f32_16x16x32_bf16 v[12:15], v[132:135], v[202:205], v[12:15]
	v_mfma_f32_16x16x32_bf16 v[8:11], v[154:157], v[202:205], v[8:11]
	s_barrier
	s_add_u32 s42, s22, 0x40000
	s_addc_u32 s43, s23, 0
	s_add_i32 s44, s44, s52
	s_mov_b32 m0, s44
	s_nop 0
	global_load_lds_dwordx4 v140, s[42:43]
	s_add_i32 m0, s44, 0x2000
	s_nop 0
	global_load_lds_dwordx4 v136, s[42:43]
	s_waitcnt vmcnt(6)
	s_barrier
; #define PG8_STAGE(bufoff, gbase, voff) do { _Pragma("unroll") for (int _i = 0; _i < 2; ++_i) \
;     __builtin_amdgcn_global_load_lds((const unsigned*)((const char*)(gbase) + (voff)[_i]), (LAS unsigned*)(lds + (bufoff) + ldsw + _i * 8192), 16, 0, 0); } while (0)
; #define PG8_LDA(dst, b, h) do { _Pragma("unroll") for (int m = 0; m < 4; ++m) _Pragma("unroll") for (int k = 0; k < 2; ++k) dst[m][k] = *(const LAS bf16x8*)(lds + PG8_SA(b, h) + aoff + m * 2048 + k * 1024); } while (0)
; #define PG8_LDB(dst, b, h) do { _Pragma("unroll") for (int n = 0; n < 2; ++n) _Pragma("unroll") for (int k = 0; k < 2; ++k) dst[n][k] = *(const LAS bf16x8*)(lds + PG8_SB(b, h) + boff + n * 2048 + k * 1024); } while (0)
; #define PG8_WAIT_V(n) asm volatile("s_waitcnt vmcnt(" #n ")" ::: "memory")
; template <class Epi, class Sched>
; DI void gemm_phase(LAS unsigned char* lds, const Gemm g, const Sched& S, const Epi& E) {
;     ...
;     for (int t = 0; t < nt; t += 2) {
;       const bool last = (t == nt - 2);
;       const char* a1 = cA + (size_t)(t + 1) * kstep;
;       const char* a2 = last ? nA : cA + (size_t)(t + 2) * kstep; const char* b2 = last ? nB : cB + (size_t)(t + 2) * kstep;
;       const char* a3 = a2 + kstep; const char* b3 = b2 + kstep;
;       PG8_LDB(B0, 0, 0); PG8_SCHED; PG8_LDA(At, 0, 0); PG8_STAGE(PG8_SA(1, 1), a1 + hstep, voffA);
;       PG8_WAIT_L(8); PG8_BAR; PG8_WAIT_L(0); PG8_MMA(0, 0, At, B0); PG8_BAR; PG8_SCHED;
;       PG8_LDB(B1, 0, 1); PG8_STAGE(PG8_SB(0, 0), b2, voffB);
;       PG8_BAR; PG8_WAIT_L(0); PG8_MMA(0, 1, At, B1); PG8_BAR;
;       PG8_LDA(At, 0, 1); PG8_STAGE(PG8_SA(0, 0), a2, voffA);
;       PG8_BAR; PG8_WAIT_L(0); PG8_MMA(1, 0, At, B0); PG8_BAR; PG8_SCHED;
;       PG8_STAGE(PG8_SB(0, 1), b2 + hstep, voffB);
;       PG8_WAIT_V(6); PG8_BAR; PG8_MMA(1, 1, At, B1); PG8_BAR;
;       PG8_LDB(B0, 1, 0); PG8_SCHED; PG8_LDA(At, 1, 0); PG8_STAGE(PG8_SA(0, 1), a2 + hstep, voffA);
;       PG8_WAIT_L(8); PG8_BAR; PG8_WAIT_L(0); PG8_MMA(0, 0, At, B0); PG8_BAR; PG8_SCHED;
;       PG8_LDB(B1, 1, 1); PG8_STAGE(PG8_SB(1, 0), b3, voffB);
;       PG8_BAR; PG8_WAIT_L(0); PG8_MMA(0, 1, At, B1); PG8_BAR;
;       PG8_LDA(At, 1, 1); PG8_STAGE(PG8_SA(1, 0), a3, voffA);
;       PG8_BAR; PG8_WAIT_L(0); PG8_MMA(1, 0, At, B0); PG8_BAR; PG8_SCHED;
;       PG8_STAGE(PG8_SB(1, 1), b3 + hstep, voffB);
;       PG8_WAIT_V(6); PG8_BAR; PG8_MMA(1, 1, At, B1); PG8_BAR;
	v_mfma_f32_16x16x32_bf16 v[52:55], v[206:209], v[158:161], v[52:55]
	v_mfma_f32_16x16x32_bf16 v[48:51], v[214:217], v[158:161], v[48:51]
	v_mfma_f32_16x16x32_bf16 v[36:39], v[206:209], v[166:169], v[36:39]
	v_mfma_f32_16x16x32_bf16 v[32:35], v[214:217], v[166:169], v[32:35]
	v_mfma_f32_16x16x32_bf16 v[20:23], v[206:209], v[174:177], v[20:23]
	v_mfma_f32_16x16x32_bf16 v[16:19], v[214:217], v[174:177], v[16:19]
	v_mfma_f32_16x16x32_bf16 v[4:7], v[206:209], v[198:201], v[4:7]
	v_mfma_f32_16x16x32_bf16 v[0:3], v[214:217], v[198:201], v[0:3]
	v_mfma_f32_16x16x32_bf16 v[52:55], v[210:213], v[162:165], v[52:55]
	v_mfma_f32_16x16x32_bf16 v[48:51], v[218:221], v[162:165], v[48:51]
	v_mfma_f32_16x16x32_bf16 v[36:39], v[210:213], v[170:173], v[36:39]
	v_mfma_f32_16x16x32_bf16 v[32:35], v[218:221], v[170:173], v[32:35]
	v_mfma_f32_16x16x32_bf16 v[20:23], v[210:213], v[178:181], v[20:23]
	v_mfma_f32_16x16x32_bf16 v[16:19], v[218:221], v[178:181], v[16:19]
	v_mfma_f32_16x16x32_bf16 v[4:7], v[210:213], v[202:205], v[4:7]
	v_mfma_f32_16x16x32_bf16 v[0:3], v[218:221], v[202:205], v[0:3]
	s_add_i32 s42, 0, 0x18000
	v_add_u32_e32 v144, s42, v196
	s_barrier
	ds_read_b128 v[128:131], v144
	ds_read_b128 v[132:135], v144 offset:1024
	ds_read_b128 v[150:153], v144 offset:2048
	ds_read_b128 v[154:157], v144 offset:3072
	s_add_u32 s28, s28, 0x40000
	s_addc_u32 s29, s29, 0
	s_mov_b32 m0, s58
	ds_read_b128 v[158:161], v197 offset:32768
	ds_read_b128 v[162:165], v197 offset:33792
	ds_read_b128 v[166:169], v197 offset:34816
	ds_read_b128 v[170:173], v197 offset:35840
	ds_read_b128 v[174:177], v197 offset:36864
	ds_read_b128 v[178:181], v197 offset:37888
	ds_read_b128 v[198:201], v197 offset:38912
	ds_read_b128 v[202:205], v197 offset:39936
	global_load_lds_dwordx4 v142, s[28:29]
	s_mov_b32 m0, s59
	s_nop 0
	global_load_lds_dwordx4 v138, s[28:29]
	s_waitcnt lgkmcnt(8)
	s_barrier
	s_waitcnt lgkmcnt(0)
	s_waitcnt lgkmcnt(0)
	v_mfma_f32_16x16x32_bf16 v[124:127], v[128:131], v[158:161], v[124:127]
	v_mfma_f32_16x16x32_bf16 v[120:123], v[150:153], v[158:161], v[120:123]
	v_mfma_f32_16x16x32_bf16 v[108:111], v[128:131], v[166:169], v[108:111]
	v_mfma_f32_16x16x32_bf16 v[104:107], v[150:153], v[166:169], v[104:107]
	v_mfma_f32_16x16x32_bf16 v[92:95], v[128:131], v[174:177], v[92:95]
	v_mfma_f32_16x16x32_bf16 v[88:91], v[150:153], v[174:177], v[88:91]
	v_mfma_f32_16x16x32_bf16 v[76:79], v[128:131], v[198:201], v[76:79]
	v_mfma_f32_16x16x32_bf16 v[72:75], v[150:153], v[198:201], v[72:75]
	v_mfma_f32_16x16x32_bf16 v[124:127], v[132:135], v[162:165], v[124:127]
	v_mfma_f32_16x16x32_bf16 v[120:123], v[154:157], v[162:165], v[120:123]
	v_mfma_f32_16x16x32_bf16 v[108:111], v[132:135], v[170:173], v[108:111]
	v_mfma_f32_16x16x32_bf16 v[104:107], v[154:157], v[170:173], v[104:107]
	v_mfma_f32_16x16x32_bf16 v[92:95], v[132:135], v[178:181], v[92:95]
	v_mfma_f32_16x16x32_bf16 v[88:91], v[154:157], v[178:181], v[88:91]
	v_mfma_f32_16x16x32_bf16 v[76:79], v[132:135], v[202:205], v[76:79]
	v_mfma_f32_16x16x32_bf16 v[72:75], v[154:157], v[202:205], v[72:75]
	s_barrier
	s_add_i32 s28, 0, 0x1c000
	s_add_i32 s29, s42, s52
	v_add_u32_e32 v144, s28, v196
	s_mov_b32 m0, s29
	ds_read_b128 v[206:209], v144
	ds_read_b128 v[210:213], v144 offset:1024
	ds_read_b128 v[214:217], v144 offset:2048
	ds_read_b128 v[218:221], v144 offset:3072
	global_load_lds_dwordx4 v140, vcc
	s_add_i32 m0, s29, 0x2000
	s_nop 0
	global_load_lds_dwordx4 v136, vcc
	s_barrier
	s_waitcnt lgkmcnt(0)
	s_waitcnt lgkmcnt(0)
	v_mfma_f32_16x16x32_bf16 v[116:119], v[206:209], v[158:161], v[116:119]
	v_mfma_f32_16x16x32_bf16 v[112:115], v[214:217], v[158:161], v[112:115]
	v_mfma_f32_16x16x32_bf16 v[100:103], v[206:209], v[166:169], v[100:103]
	v_mfma_f32_16x16x32_bf16 v[96:99], v[214:217], v[166:169], v[96:99]
	v_mfma_f32_16x16x32_bf16 v[84:87], v[206:209], v[174:177], v[84:87]
	v_mfma_f32_16x16x32_bf16 v[80:83], v[214:217], v[174:177], v[80:83]
	v_mfma_f32_16x16x32_bf16 v[68:71], v[206:209], v[198:201], v[68:71]
	v_mfma_f32_16x16x32_bf16 v[64:67], v[214:217], v[198:201], v[64:67]
	v_mfma_f32_16x16x32_bf16 v[116:119], v[210:213], v[162:165], v[116:119]
	v_mfma_f32_16x16x32_bf16 v[112:115], v[218:221], v[162:165], v[112:115]
	v_mfma_f32_16x16x32_bf16 v[100:103], v[210:213], v[170:173], v[100:103]
	v_mfma_f32_16x16x32_bf16 v[96:99], v[218:221], v[170:173], v[96:99]
	v_mfma_f32_16x16x32_bf16 v[84:87], v[210:213], v[178:181], v[84:87]
	v_mfma_f32_16x16x32_bf16 v[80:83], v[218:221], v[178:181], v[80:83]
	v_mfma_f32_16x16x32_bf16 v[68:71], v[210:213], v[202:205], v[68:71]
	v_mfma_f32_16x16x32_bf16 v[64:67], v[218:221], v[202:205], v[64:67]
	s_mov_b32 m0, s62
	s_barrier
	ds_read_b128 v[158:161], v197 offset:49152
	ds_read_b128 v[162:165], v197 offset:50176
	ds_read_b128 v[166:169], v197 offset:51200
	ds_read_b128 v[170:173], v197 offset:52224
	ds_read_b128 v[174:177], v197 offset:53248
	ds_read_b128 v[178:181], v197 offset:54272
	ds_read_b128 v[198:201], v197 offset:55296
	ds_read_b128 v[202:205], v197 offset:56320
	global_load_lds_dwordx4 v142, s[100:101]
	s_mov_b32 m0, s63
	s_nop 0
	global_load_lds_dwordx4 v138, s[100:101]
	s_barrier
; #define PG8_STAGE(bufoff, gbase, voff) do { _Pragma("unroll") for (int _i = 0; _i < 2; ++_i) \
;     __builtin_amdgcn_global_load_lds((const unsigned*)((const char*)(gbase) + (voff)[_i]), (LAS unsigned*)(lds + (bufoff) + ldsw + _i * 8192), 16, 0, 0); } while (0)
; #define PG8_MMA(ai, bj, At, Bt) do { __builtin_amdgcn_s_setprio(1); _Pragma("unroll") for (int m = 0; m < 4; ++m) _Pragma("unroll") for (int n = 0; n < 2; ++n) _Pragma("unroll") for (int k = 0; k < 2; ++k) \
;     acc[ai][bj][m][n] = __builtin_amdgcn_mfma_f32_16x16x32_bf16(Bt[n][k], At[m][k], acc[ai][bj][m][n], 0, 0, 0); __builtin_amdgcn_s_setprio(0); } while (0)
; #define PG8_WAIT_V(n) asm volatile("s_waitcnt vmcnt(" #n ")" ::: "memory")
; #define PG8_WAIT_L(n) asm volatile("s_waitcnt lgkmcnt(" #n ")" ::: "memory")
; #define PG8_BAR __builtin_amdgcn_s_barrier()
; #define PG8_SCHED __builtin_amdgcn_sched_barrier(0)
; template <class Epi, class Sched>
; DI void gemm_phase(LAS unsigned char* lds, const Gemm g, const Sched& S, const Epi& E) {
;     ...
;       PG8_BAR; PG8_WAIT_L(0); PG8_MMA(1, 0, At, B0); PG8_BAR; PG8_SCHED;
;       PG8_STAGE(PG8_SB(1, 1), b3 + hstep, voffB);
;       PG8_WAIT_V(6); PG8_BAR; PG8_MMA(1, 1, At, B1); PG8_BAR;
;   DI void operator()(const f32x4 (&acc)[2][2][4][2], const pg8::Unit& u, int wr, int wc, int fr_, int fq_) const {
;     ...
;             if (EPI == EPI_ABIN) {
;               if (n == 0) {
;                 const int gb = u.pn * 256 + bj * 128 + wc * 32; const int f8 = gb + 8 * fq;
;                 const f32x4 v1 = acc[ai][bj][m][1];
;                 if (gb < 384) st_bf8((u16*)(big + E_CQ) + (size_t)token * 384 + f8, v, v1, rinv);
;                 else if (gb < 640) st_bf8((u16*)(big + E_CKV) + (size_t)token * 256 + (f8 - 384), v, v1, rinv);
;                 else if (gb < 672) {
;                   f32x4 a0 = v, a1 = v1;
;                   rope_perm(a0, a1, fq, t_ & 63, tcos, tsin, token & (S_ - 1));
;                   st_bf8((u16*)(big + E_KPE) + (size_t)token * 32 + 8 * fq, a0, a1, rinv);
;                 }
;                 else if (gb < 1184) st_bf8((u16*)(big + E_QNA) + (size_t)token * 512 + (f8 - 672), v, v1, rinv * (0.125f * LOG2E));
;                 else if (gb < 1696) st_bf8((u16*)(big + E_KNA) + (size_t)token * 512 + (f8 - 1184), v, v1, rinv);
;                 else if (gb < 2208) st_bf8((u16*)(big + E_VNAT) + (size_t)token * 512 + (f8 - 1696), v, v1, rinv);
	s_waitcnt lgkmcnt(0)
	s_waitcnt lgkmcnt(0)
	v_mfma_f32_16x16x32_bf16 v[60:63], v[128:131], v[158:161], v[60:63]
	v_mfma_f32_16x16x32_bf16 v[56:59], v[150:153], v[158:161], v[56:59]
	v_mfma_f32_16x16x32_bf16 v[44:47], v[128:131], v[166:169], v[44:47]
	v_mfma_f32_16x16x32_bf16 v[40:43], v[150:153], v[166:169], v[40:43]
	v_mfma_f32_16x16x32_bf16 v[28:31], v[128:131], v[174:177], v[28:31]
	v_mfma_f32_16x16x32_bf16 v[24:27], v[150:153], v[174:177], v[24:27]
	v_mfma_f32_16x16x32_bf16 v[12:15], v[128:131], v[198:201], v[12:15]
	v_mfma_f32_16x16x32_bf16 v[8:11], v[150:153], v[198:201], v[8:11]
	v_mfma_f32_16x16x32_bf16 v[60:63], v[132:135], v[162:165], v[60:63]
	v_mfma_f32_16x16x32_bf16 v[56:59], v[154:157], v[162:165], v[56:59]
	v_mfma_f32_16x16x32_bf16 v[44:47], v[132:135], v[170:173], v[44:47]
	v_mfma_f32_16x16x32_bf16 v[40:43], v[154:157], v[170:173], v[40:43]
	v_mfma_f32_16x16x32_bf16 v[28:31], v[132:135], v[178:181], v[28:31]
	v_mfma_f32_16x16x32_bf16 v[24:27], v[154:157], v[178:181], v[24:27]
	v_mfma_f32_16x16x32_bf16 v[12:15], v[132:135], v[202:205], v[12:15]
	v_mfma_f32_16x16x32_bf16 v[8:11], v[154:157], v[202:205], v[8:11]
	s_barrier
	s_add_u32 s22, s22, 0x40080
	s_addc_u32 s23, s23, 0
	s_add_i32 s28, s28, s52
	s_mov_b32 m0, s28
	s_nop 0
	global_load_lds_dwordx4 v140, s[22:23]
	s_add_i32 m0, s28, 0x2000
	s_nop 0
	global_load_lds_dwordx4 v136, s[22:23]
	s_waitcnt vmcnt(6)
	s_barrier
	v_mfma_f32_16x16x32_bf16 v[52:55], v[206:209], v[158:161], v[52:55]
	v_mfma_f32_16x16x32_bf16 v[48:51], v[214:217], v[158:161], v[48:51]
	v_mfma_f32_16x16x32_bf16 v[36:39], v[206:209], v[166:169], v[36:39]
	v_mfma_f32_16x16x32_bf16 v[32:35], v[214:217], v[166:169], v[32:35]
	v_mfma_f32_16x16x32_bf16 v[20:23], v[206:209], v[174:177], v[20:23]
	v_mfma_f32_16x16x32_bf16 v[16:19], v[214:217], v[174:177], v[16:19]
	v_mfma_f32_16x16x32_bf16 v[4:7], v[206:209], v[198:201], v[4:7]
	v_mfma_f32_16x16x32_bf16 v[0:3], v[214:217], v[198:201], v[0:3]
	v_mfma_f32_16x16x32_bf16 v[52:55], v[210:213], v[162:165], v[52:55]
	v_mfma_f32_16x16x32_bf16 v[48:51], v[218:221], v[162:165], v[48:51]
	v_mfma_f32_16x16x32_bf16 v[36:39], v[210:213], v[170:173], v[36:39]
	v_mfma_f32_16x16x32_bf16 v[32:35], v[218:221], v[170:173], v[32:35]
	v_mfma_f32_16x16x32_bf16 v[20:23], v[210:213], v[178:181], v[20:23]
	v_mfma_f32_16x16x32_bf16 v[16:19], v[218:221], v[178:181], v[16:19]
	v_mfma_f32_16x16x32_bf16 v[4:7], v[210:213], v[202:205], v[4:7]
	v_mfma_f32_16x16x32_bf16 v[0:3], v[218:221], v[202:205], v[0:3]
	s_add_i32 s41, s41, 2
	s_add_u32 s20, s20, 0x100
	s_addc_u32 s21, s21, 0
	s_add_u32 s39, s39, 0x100
	s_addc_u32 s40, s40, 0
	s_cmp_gt_u32 s41, 13
	s_barrier
	s_cbranch_scc0 .LBB0_689
	v_mov_b32_e32 v128, v182
	s_lshl_b32 s20, s34, 10
	v_bfe_u32 v129, v128, 4, 2
	v_and_or_b32 v201, v128, 15, s60
	s_lshl_b32 s13, s35, 8
	v_lshlrev_b32_e32 v128, 2, v128
	s_movk_i32 s21, 0x80
	s_add_i32 s20, s20, 0
	s_lshl_b32 s15, s36, 8
	v_bitop3_b32 v198, v128, s21, v190 bitop3:0x6c
	v_lshl_add_u32 v128, v201, 2, s20
	s_or_b32 s20, s13, s61
	v_add_u32_e32 v200, 0x20000, v128
	s_cmpk_gt_i32 s20, 0x17f
	ds_read_b32 v156, v200
	s_cselect_b64 s[28:29], -1, 0
	s_cmpk_gt_u32 s13, 0x27f
	s_cselect_b64 s[46:47], -1, 0
	s_cmpk_gt_u32 s20, 0x29f
	s_cselect_b64 s[40:41], -1, 0
	s_cmpk_gt_u32 s20, 0x49f
	v_lshlrev_b32_e32 v144, 3, v129
	v_add_u32_e32 v154, s15, v201
	s_cselect_b64 s[34:35], -1, 0
	s_cmpk_gt_u32 s20, 0x69f
	v_ashrrev_i32_e32 v155, 31, v154
	v_lshlrev_b32_e32 v128, 4, v154
	v_or_b32_e32 v150, s20, v144
	s_cselect_b64 s[22:23], -1, 0
	s_cmpk_lt_u32 s20, 0x8a0
	v_and_b32_e32 v199, 8, v144
	v_cmp_lt_u32_e64 s[92:93], 1, v129
	v_lshlrev_b64 v[164:165], 10, v[154:155]
	s_waitcnt lgkmcnt(0)
	v_mul_f32_e32 v162, 0x3e38aa3b, v156
	v_and_b32_e32 v157, 0xfcf0, v128
	v_lshlrev_b64 v[160:161], 6, v[154:155]
	v_lshlrev_b64 v[158:159], 9, v[154:155]
	s_cselect_b64 s[20:21], -1, 0
	v_mov_b32_e32 v152, v150
	v_mov_b32_e32 v153, v145
	s_mov_b64 s[36:37], -1
	s_and_b64 vcc, exec, s[28:29]
	s_cbranch_vccz .LBB0_714
	s_and_b64 vcc, exec, s[46:47]
	s_cbranch_vccz .LBB0_711
	s_and_b64 vcc, exec, s[40:41]
	s_cbranch_vccz .LBB0_704
	s_and_b64 vcc, exec, s[34:35]
	s_cbranch_vccz .LBB0_701
	s_and_b64 vcc, exec, s[22:23]
	s_cbranch_vccz .LBB0_698
	s_andn2_b64 vcc, exec, s[20:21]
	s_cbranch_vccnz .LBB0_697
	v_lshl_add_u64 v[128:129], s[2:3], 0, v[164:165]
	v_lshl_add_u64 v[132:133], v[152:153], 1, v[128:129]
	v_pk_mul_f32 v[128:129], v[124:125], v[156:157] op_sel_hi:[1,0]
	v_pk_mul_f32 v[130:131], v[126:127], v[156:157] op_sel_hi:[1,0]
	v_cvt_pk_bf16_f32 v128, v128, v129
	v_cvt_pk_bf16_f32 v129, v130, v131
	v_pk_mul_f32 v[130:131], v[120:121], v[156:157] op_sel_hi:[1,0]
	v_pk_mul_f32 v[134:135], v[122:123], v[156:157] op_sel_hi:[1,0]
	v_add_co_u32_e32 v132, vcc, 0x69ff000, v132
	v_cvt_pk_bf16_f32 v130, v130, v131
	v_cvt_pk_bf16_f32 v131, v134, v135
	v_addc_co_u32_e32 v133, vcc, 0, v133, vcc
	global_store_dwordx4 v[132:133], v[128:131], off offset:704

; #define PG8_STAGE(bufoff, gbase, voff) do { _Pragma("unroll") for (int _i = 0; _i < 2; ++_i) \
;     __builtin_amdgcn_global_load_lds((const unsigned*)((const char*)(gbase) + (voff)[_i]), (LAS unsigned*)(lds + (bufoff) + ldsw + _i * 8192), 16, 0, 0); } while (0)
; #define PG8_LDA(dst, b, h) do { _Pragma("unroll") for (int m = 0; m < 4; ++m) _Pragma("unroll") for (int k = 0; k < 2; ++k) dst[m][k] = *(const LAS bf16x8*)(lds + PG8_SA(b, h) + aoff + m * 2048 + k * 1024); } while (0)
; #define PG8_LDB(dst, b, h) do { _Pragma("unroll") for (int n = 0; n < 2; ++n) _Pragma("unroll") for (int k = 0; k < 2; ++k) dst[n][k] = *(const LAS bf16x8*)(lds + PG8_SB(b, h) + boff + n * 2048 + k * 1024); } while (0)
; #define PG8_WAIT_V(n) asm volatile("s_waitcnt vmcnt(" #n ")" ::: "memory")
; template <class Epi, class Sched>
; DI void gemm_phase(LAS unsigned char* lds, const Gemm g, const Sched& S, const Epi& E) {
;     ...
;     for (int t = 0; t < nt; t += 2) {
;       const bool last = (t == nt - 2);
;       const char* a1 = cA + (size_t)(t + 1) * kstep;
;       const char* a2 = last ? nA : cA + (size_t)(t + 2) * kstep; const char* b2 = last ? nB : cB + (size_t)(t + 2) * kstep;
;       const char* a3 = a2 + kstep; const char* b3 = b2 + kstep;
;       PG8_LDB(B0, 0, 0); PG8_SCHED; PG8_LDA(At, 0, 0); PG8_STAGE(PG8_SA(1, 1), a1 + hstep, voffA);
;       PG8_WAIT_L(8); PG8_BAR; PG8_WAIT_L(0); PG8_MMA(0, 0, At, B0); PG8_BAR; PG8_SCHED;
;       PG8_LDB(B1, 0, 1); PG8_STAGE(PG8_SB(0, 0), b2, voffB);
;       PG8_BAR; PG8_WAIT_L(0); PG8_MMA(0, 1, At, B1); PG8_BAR;
;       PG8_LDA(At, 0, 1); PG8_STAGE(PG8_SA(0, 0), a2, voffA);
;       PG8_BAR; PG8_WAIT_L(0); PG8_MMA(1, 0, At, B0); PG8_BAR; PG8_SCHED;
;       PG8_STAGE(PG8_SB(0, 1), b2 + hstep, voffB);
;       PG8_WAIT_V(6); PG8_BAR; PG8_MMA(1, 1, At, B1); PG8_BAR;
;       PG8_LDB(B0, 1, 0); PG8_SCHED; PG8_LDA(At, 1, 0); PG8_STAGE(PG8_SA(0, 1), a2 + hstep, voffA);
;       PG8_WAIT_L(8); PG8_BAR; PG8_WAIT_L(0); PG8_MMA(0, 0, At, B0); PG8_BAR; PG8_SCHED;
;       PG8_LDB(B1, 1, 1); PG8_STAGE(PG8_SB(1, 0), b3, voffB);
;       PG8_BAR; PG8_WAIT_L(0); PG8_MMA(0, 1, At, B1); PG8_BAR;
;       PG8_LDA(At, 1, 1); PG8_STAGE(PG8_SA(1, 0), a3, voffA);
;       PG8_BAR; PG8_WAIT_L(0); PG8_MMA(1, 0, At, B0); PG8_BAR; PG8_SCHED;
;       PG8_STAGE(PG8_SB(1, 1), b3 + hstep, voffB);
;       PG8_WAIT_V(6); PG8_BAR; PG8_MMA(1, 1, At, B1); PG8_BAR;
.LBB0_1202:
	s_add_u32 s20, s18, 0x100
	s_addc_u32 s21, s19, 0
	s_add_i32 s55, 0, 0x10000
	v_add_u32_e32 v144, s55, v162
	ds_read_b128 v[140:143], v144
	ds_read_b128 v[146:149], v144 offset:1024
	ds_read_b128 v[150:153], v144 offset:2048
	ds_read_b128 v[154:157], v144 offset:3072
	s_cmp_eq_u32 s54, 2
	s_cselect_b32 s29, s3, s21
	s_cselect_b32 s28, s2, s20
	s_cselect_b32 s23, s5, s53
	s_cselect_b32 s22, s4, s52
	s_add_i32 m0, s38, 0xc000
	ds_read_b128 v[158:161], v163
	ds_read_b128 v[164:167], v163 offset:1024
	ds_read_b128 v[168:171], v163 offset:2048
	ds_read_b128 v[172:175], v163 offset:3072
	ds_read_b128 v[176:179], v163 offset:4096
	ds_read_b128 v[196:199], v163 offset:5120
	ds_read_b128 v[200:203], v163 offset:6144
	ds_read_b128 v[204:207], v163 offset:7168
	global_load_lds_dwordx4 v136, s[18:19]
	s_add_i32 m0, s38, 0xe000
	s_nop 0
	global_load_lds_dwordx4 v138, s[18:19]
	s_waitcnt lgkmcnt(8)
	s_barrier
	s_waitcnt lgkmcnt(0)
	s_waitcnt lgkmcnt(0)
	v_mfma_f32_16x16x32_bf16 v[124:127], v[140:143], v[158:161], v[124:127]
	v_mfma_f32_16x16x32_bf16 v[120:123], v[150:153], v[158:161], v[120:123]
	v_mfma_f32_16x16x32_bf16 v[108:111], v[140:143], v[168:171], v[108:111]
	v_mfma_f32_16x16x32_bf16 v[104:107], v[150:153], v[168:171], v[104:107]
	v_mfma_f32_16x16x32_bf16 v[92:95], v[140:143], v[176:179], v[92:95]
	v_mfma_f32_16x16x32_bf16 v[88:91], v[150:153], v[176:179], v[88:91]
	v_mfma_f32_16x16x32_bf16 v[76:79], v[140:143], v[200:203], v[76:79]
	v_mfma_f32_16x16x32_bf16 v[72:75], v[150:153], v[200:203], v[72:75]
	v_mfma_f32_16x16x32_bf16 v[124:127], v[146:149], v[164:167], v[124:127]
	v_mfma_f32_16x16x32_bf16 v[120:123], v[154:157], v[164:167], v[120:123]
	v_mfma_f32_16x16x32_bf16 v[108:111], v[146:149], v[172:175], v[108:111]
	v_mfma_f32_16x16x32_bf16 v[104:107], v[154:157], v[172:175], v[104:107]
	v_mfma_f32_16x16x32_bf16 v[92:95], v[146:149], v[196:199], v[92:95]
	v_mfma_f32_16x16x32_bf16 v[88:91], v[154:157], v[196:199], v[88:91]
	v_mfma_f32_16x16x32_bf16 v[76:79], v[146:149], v[204:207], v[76:79]
	v_mfma_f32_16x16x32_bf16 v[72:75], v[154:157], v[204:207], v[72:75]
	s_barrier
	s_add_i32 s56, 0, 0x14000
	s_add_i32 s18, s55, s35
	v_add_u32_e32 v144, s56, v162
	s_add_u32 vcc_lo, s22, s0
	s_addc_u32 vcc_hi, s23, s1
	s_mov_b32 m0, s18
	ds_read_b128 v[208:211], v144
	ds_read_b128 v[212:215], v144 offset:1024
	ds_read_b128 v[216:219], v144 offset:2048
	ds_read_b128 v[220:223], v144 offset:3072
	global_load_lds_dwordx4 v130, s[22:23]
	s_add_i32 m0, s18, 0x2000
	s_nop 0
	global_load_lds_dwordx4 v134, s[22:23]
	s_barrier
	s_waitcnt lgkmcnt(0)
	s_waitcnt lgkmcnt(0)
	v_mfma_f32_16x16x32_bf16 v[116:119], v[208:211], v[158:161], v[116:119]
	v_mfma_f32_16x16x32_bf16 v[112:115], v[216:219], v[158:161], v[112:115]
	v_mfma_f32_16x16x32_bf16 v[100:103], v[208:211], v[168:171], v[100:103]
	v_mfma_f32_16x16x32_bf16 v[96:99], v[216:219], v[168:171], v[96:99]
	v_mfma_f32_16x16x32_bf16 v[84:87], v[208:211], v[176:179], v[84:87]
	v_mfma_f32_16x16x32_bf16 v[80:83], v[216:219], v[176:179], v[80:83]
	v_mfma_f32_16x16x32_bf16 v[68:71], v[208:211], v[200:203], v[68:71]
	v_mfma_f32_16x16x32_bf16 v[64:67], v[216:219], v[200:203], v[64:67]
	v_mfma_f32_16x16x32_bf16 v[116:119], v[212:215], v[164:167], v[116:119]
	v_mfma_f32_16x16x32_bf16 v[112:115], v[220:223], v[164:167], v[112:115]
	v_mfma_f32_16x16x32_bf16 v[100:103], v[212:215], v[172:175], v[100:103]
	v_mfma_f32_16x16x32_bf16 v[96:99], v[220:223], v[172:175], v[96:99]
	v_mfma_f32_16x16x32_bf16 v[84:87], v[212:215], v[196:199], v[84:87]
	v_mfma_f32_16x16x32_bf16 v[80:83], v[220:223], v[196:199], v[80:83]
	v_mfma_f32_16x16x32_bf16 v[68:71], v[212:215], v[204:207], v[68:71]
	v_mfma_f32_16x16x32_bf16 v[64:67], v[220:223], v[204:207], v[64:67]
	s_mov_b32 m0, s38
	s_add_u32 s100, s28, s0
	s_addc_u32 s101, s29, s1
	s_barrier
	ds_read_b128 v[158:161], v163 offset:16384
	ds_read_b128 v[164:167], v163 offset:17408
	ds_read_b128 v[168:171], v163 offset:18432
	ds_read_b128 v[172:175], v163 offset:19456
	ds_read_b128 v[176:179], v163 offset:20480
	ds_read_b128 v[196:199], v163 offset:21504
	ds_read_b128 v[200:203], v163 offset:22528
	ds_read_b128 v[204:207], v163 offset:23552
	global_load_lds_dwordx4 v128, s[28:29]
	s_mov_b32 m0, s39
	s_nop 0
	global_load_lds_dwordx4 v132, s[28:29]
	s_barrier
	s_waitcnt lgkmcnt(0)
	s_waitcnt lgkmcnt(0)
	v_mfma_f32_16x16x32_bf16 v[60:63], v[140:143], v[158:161], v[60:63]
	v_mfma_f32_16x16x32_bf16 v[56:59], v[150:153], v[158:161], v[56:59]
	v_mfma_f32_16x16x32_bf16 v[44:47], v[140:143], v[168:171], v[44:47]
	v_mfma_f32_16x16x32_bf16 v[40:43], v[150:153], v[168:171], v[40:43]
	v_mfma_f32_16x16x32_bf16 v[28:31], v[140:143], v[176:179], v[28:31]
	v_mfma_f32_16x16x32_bf16 v[24:27], v[150:153], v[176:179], v[24:27]
	v_mfma_f32_16x16x32_bf16 v[12:15], v[140:143], v[200:203], v[12:15]
	v_mfma_f32_16x16x32_bf16 v[8:11], v[150:153], v[200:203], v[8:11]
	v_mfma_f32_16x16x32_bf16 v[60:63], v[146:149], v[164:167], v[60:63]
	v_mfma_f32_16x16x32_bf16 v[56:59], v[154:157], v[164:167], v[56:59]
	v_mfma_f32_16x16x32_bf16 v[44:47], v[146:149], v[172:175], v[44:47]
	v_mfma_f32_16x16x32_bf16 v[40:43], v[154:157], v[172:175], v[40:43]
	v_mfma_f32_16x16x32_bf16 v[28:31], v[146:149], v[196:199], v[28:31]
	v_mfma_f32_16x16x32_bf16 v[24:27], v[154:157], v[196:199], v[24:27]
	v_mfma_f32_16x16x32_bf16 v[12:15], v[146:149], v[204:207], v[12:15]
	v_mfma_f32_16x16x32_bf16 v[8:11], v[154:157], v[204:207], v[8:11]
	s_barrier
	s_add_u32 s18, s22, 0x18000
	s_addc_u32 s19, s23, 0
	s_add_i32 s55, s56, s35
	s_mov_b32 m0, s55
	s_nop 0
	global_load_lds_dwordx4 v130, s[18:19]
	s_add_i32 m0, s55, 0x2000
	s_nop 0
	global_load_lds_dwordx4 v134, s[18:19]
	s_waitcnt vmcnt(6)
	s_barrier
; #define PG8_STAGE(bufoff, gbase, voff) do { _Pragma("unroll") for (int _i = 0; _i < 2; ++_i) \
;     __builtin_amdgcn_global_load_lds((const unsigned*)((const char*)(gbase) + (voff)[_i]), (LAS unsigned*)(lds + (bufoff) + ldsw + _i * 8192), 16, 0, 0); } while (0)
; #define PG8_LDA(dst, b, h) do { _Pragma("unroll") for (int m = 0; m < 4; ++m) _Pragma("unroll") for (int k = 0; k < 2; ++k) dst[m][k] = *(const LAS bf16x8*)(lds + PG8_SA(b, h) + aoff + m * 2048 + k * 1024); } while (0)
; #define PG8_LDB(dst, b, h) do { _Pragma("unroll") for (int n = 0; n < 2; ++n) _Pragma("unroll") for (int k = 0; k < 2; ++k) dst[n][k] = *(const LAS bf16x8*)(lds + PG8_SB(b, h) + boff + n * 2048 + k * 1024); } while (0)
; #define PG8_WAIT_V(n) asm volatile("s_waitcnt vmcnt(" #n ")" ::: "memory")
; template <class Epi, class Sched>
; DI void gemm_phase(LAS unsigned char* lds, const Gemm g, const Sched& S, const Epi& E) {
;     ...
;     for (int t = 0; t < nt; t += 2) {
;       const bool last = (t == nt - 2);
;       const char* a1 = cA + (size_t)(t + 1) * kstep;
;       const char* a2 = last ? nA : cA + (size_t)(t + 2) * kstep; const char* b2 = last ? nB : cB + (size_t)(t + 2) * kstep;
;       const char* a3 = a2 + kstep; const char* b3 = b2 + kstep;
;       PG8_LDB(B0, 0, 0); PG8_SCHED; PG8_LDA(At, 0, 0); PG8_STAGE(PG8_SA(1, 1), a1 + hstep, voffA);
;       PG8_WAIT_L(8); PG8_BAR; PG8_WAIT_L(0); PG8_MMA(0, 0, At, B0); PG8_BAR; PG8_SCHED;
;       PG8_LDB(B1, 0, 1); PG8_STAGE(PG8_SB(0, 0), b2, voffB);
;       PG8_BAR; PG8_WAIT_L(0); PG8_MMA(0, 1, At, B1); PG8_BAR;
;       PG8_LDA(At, 0, 1); PG8_STAGE(PG8_SA(0, 0), a2, voffA);
;       PG8_BAR; PG8_WAIT_L(0); PG8_MMA(1, 0, At, B0); PG8_BAR; PG8_SCHED;
;       PG8_STAGE(PG8_SB(0, 1), b2 + hstep, voffB);
;       PG8_WAIT_V(6); PG8_BAR; PG8_MMA(1, 1, At, B1); PG8_BAR;
;       PG8_LDB(B0, 1, 0); PG8_SCHED; PG8_LDA(At, 1, 0); PG8_STAGE(PG8_SA(0, 1), a2 + hstep, voffA);
;       PG8_WAIT_L(8); PG8_BAR; PG8_WAIT_L(0); PG8_MMA(0, 0, At, B0); PG8_BAR; PG8_SCHED;
;       PG8_LDB(B1, 1, 1); PG8_STAGE(PG8_SB(1, 0), b3, voffB);
;       PG8_BAR; PG8_WAIT_L(0); PG8_MMA(0, 1, At, B1); PG8_BAR;
;       PG8_LDA(At, 1, 1); PG8_STAGE(PG8_SA(1, 0), a3, voffA);
;       PG8_BAR; PG8_WAIT_L(0); PG8_MMA(1, 0, At, B0); PG8_BAR; PG8_SCHED;
;       PG8_STAGE(PG8_SB(1, 1), b3 + hstep, voffB);
;       PG8_WAIT_V(6); PG8_BAR; PG8_MMA(1, 1, At, B1); PG8_BAR;
	v_mfma_f32_16x16x32_bf16 v[52:55], v[208:211], v[158:161], v[52:55]
	v_mfma_f32_16x16x32_bf16 v[48:51], v[216:219], v[158:161], v[48:51]
	v_mfma_f32_16x16x32_bf16 v[36:39], v[208:211], v[168:171], v[36:39]
	v_mfma_f32_16x16x32_bf16 v[32:35], v[216:219], v[168:171], v[32:35]
	v_mfma_f32_16x16x32_bf16 v[20:23], v[208:211], v[176:179], v[20:23]
	v_mfma_f32_16x16x32_bf16 v[16:19], v[216:219], v[176:179], v[16:19]
	v_mfma_f32_16x16x32_bf16 v[4:7], v[208:211], v[200:203], v[4:7]
	v_mfma_f32_16x16x32_bf16 v[0:3], v[216:219], v[200:203], v[0:3]
	v_mfma_f32_16x16x32_bf16 v[52:55], v[212:215], v[164:167], v[52:55]
	v_mfma_f32_16x16x32_bf16 v[48:51], v[220:223], v[164:167], v[48:51]
	v_mfma_f32_16x16x32_bf16 v[36:39], v[212:215], v[172:175], v[36:39]
	v_mfma_f32_16x16x32_bf16 v[32:35], v[220:223], v[172:175], v[32:35]
	v_mfma_f32_16x16x32_bf16 v[20:23], v[212:215], v[196:199], v[20:23]
	v_mfma_f32_16x16x32_bf16 v[16:19], v[220:223], v[196:199], v[16:19]
	v_mfma_f32_16x16x32_bf16 v[4:7], v[212:215], v[204:207], v[4:7]
	v_mfma_f32_16x16x32_bf16 v[0:3], v[220:223], v[204:207], v[0:3]
	s_add_i32 s55, 0, 0x18000
	v_add_u32_e32 v144, s55, v162
	s_barrier
	ds_read_b128 v[140:143], v144
	ds_read_b128 v[146:149], v144 offset:1024
	ds_read_b128 v[150:153], v144 offset:2048
	ds_read_b128 v[154:157], v144 offset:3072
	s_add_u32 s18, s28, 0x18000
	s_addc_u32 s19, s29, 0
	s_mov_b32 m0, s40
	ds_read_b128 v[158:161], v163 offset:32768
	ds_read_b128 v[164:167], v163 offset:33792
	ds_read_b128 v[168:171], v163 offset:34816
	ds_read_b128 v[172:175], v163 offset:35840
	ds_read_b128 v[176:179], v163 offset:36864
	ds_read_b128 v[196:199], v163 offset:37888
	ds_read_b128 v[200:203], v163 offset:38912
	ds_read_b128 v[204:207], v163 offset:39936
	global_load_lds_dwordx4 v128, s[18:19]
	s_mov_b32 m0, s41
	s_nop 0
	global_load_lds_dwordx4 v132, s[18:19]
	s_waitcnt lgkmcnt(8)
	s_barrier
	s_waitcnt lgkmcnt(0)
	s_waitcnt lgkmcnt(0)
	v_mfma_f32_16x16x32_bf16 v[124:127], v[140:143], v[158:161], v[124:127]
	v_mfma_f32_16x16x32_bf16 v[120:123], v[150:153], v[158:161], v[120:123]
	v_mfma_f32_16x16x32_bf16 v[108:111], v[140:143], v[168:171], v[108:111]
	v_mfma_f32_16x16x32_bf16 v[104:107], v[150:153], v[168:171], v[104:107]
	v_mfma_f32_16x16x32_bf16 v[92:95], v[140:143], v[176:179], v[92:95]
	v_mfma_f32_16x16x32_bf16 v[88:91], v[150:153], v[176:179], v[88:91]
	v_mfma_f32_16x16x32_bf16 v[76:79], v[140:143], v[200:203], v[76:79]
	v_mfma_f32_16x16x32_bf16 v[72:75], v[150:153], v[200:203], v[72:75]
	v_mfma_f32_16x16x32_bf16 v[124:127], v[146:149], v[164:167], v[124:127]
	v_mfma_f32_16x16x32_bf16 v[120:123], v[154:157], v[164:167], v[120:123]
	v_mfma_f32_16x16x32_bf16 v[108:111], v[146:149], v[172:175], v[108:111]
	v_mfma_f32_16x16x32_bf16 v[104:107], v[154:157], v[172:175], v[104:107]
	v_mfma_f32_16x16x32_bf16 v[92:95], v[146:149], v[196:199], v[92:95]
	v_mfma_f32_16x16x32_bf16 v[88:91], v[154:157], v[196:199], v[88:91]
	v_mfma_f32_16x16x32_bf16 v[76:79], v[146:149], v[204:207], v[76:79]
	v_mfma_f32_16x16x32_bf16 v[72:75], v[154:157], v[204:207], v[72:75]
	s_barrier
	s_add_i32 s28, 0, 0x1c000
	s_add_i32 s18, s55, s35
	v_add_u32_e32 v144, s28, v162
	s_mov_b32 m0, s18
	ds_read_b128 v[208:211], v144
	ds_read_b128 v[212:215], v144 offset:1024
	ds_read_b128 v[216:219], v144 offset:2048
	ds_read_b128 v[220:223], v144 offset:3072
	global_load_lds_dwordx4 v130, vcc
	s_add_i32 m0, s18, 0x2000
	s_nop 0
	global_load_lds_dwordx4 v134, vcc
	s_barrier
	s_waitcnt lgkmcnt(0)
	s_waitcnt lgkmcnt(0)
	v_mfma_f32_16x16x32_bf16 v[116:119], v[208:211], v[158:161], v[116:119]
	v_mfma_f32_16x16x32_bf16 v[112:115], v[216:219], v[158:161], v[112:115]
	v_mfma_f32_16x16x32_bf16 v[100:103], v[208:211], v[168:171], v[100:103]
	v_mfma_f32_16x16x32_bf16 v[96:99], v[216:219], v[168:171], v[96:99]
	v_mfma_f32_16x16x32_bf16 v[84:87], v[208:211], v[176:179], v[84:87]
	v_mfma_f32_16x16x32_bf16 v[80:83], v[216:219], v[176:179], v[80:83]
	v_mfma_f32_16x16x32_bf16 v[68:71], v[208:211], v[200:203], v[68:71]
	v_mfma_f32_16x16x32_bf16 v[64:67], v[216:219], v[200:203], v[64:67]
	v_mfma_f32_16x16x32_bf16 v[116:119], v[212:215], v[164:167], v[116:119]
	v_mfma_f32_16x16x32_bf16 v[112:115], v[220:223], v[164:167], v[112:115]
	v_mfma_f32_16x16x32_bf16 v[100:103], v[212:215], v[172:175], v[100:103]
	v_mfma_f32_16x16x32_bf16 v[96:99], v[220:223], v[172:175], v[96:99]
	v_mfma_f32_16x16x32_bf16 v[84:87], v[212:215], v[196:199], v[84:87]
	v_mfma_f32_16x16x32_bf16 v[80:83], v[220:223], v[196:199], v[80:83]
	v_mfma_f32_16x16x32_bf16 v[68:71], v[212:215], v[204:207], v[68:71]
	v_mfma_f32_16x16x32_bf16 v[64:67], v[220:223], v[204:207], v[64:67]
	s_mov_b32 m0, s44
	s_barrier
	ds_read_b128 v[158:161], v163 offset:49152
	ds_read_b128 v[164:167], v163 offset:50176
	ds_read_b128 v[168:171], v163 offset:51200
	ds_read_b128 v[172:175], v163 offset:52224
	ds_read_b128 v[176:179], v163 offset:53248
	ds_read_b128 v[196:199], v163 offset:54272
	ds_read_b128 v[200:203], v163 offset:55296
	ds_read_b128 v[204:207], v163 offset:56320
	global_load_lds_dwordx4 v128, s[100:101]
	s_mov_b32 m0, s45
	s_nop 0
	global_load_lds_dwordx4 v132, s[100:101]
	s_barrier
; #define PG8_STAGE(bufoff, gbase, voff) do { _Pragma("unroll") for (int _i = 0; _i < 2; ++_i) \
;     __builtin_amdgcn_global_load_lds((const unsigned*)((const char*)(gbase) + (voff)[_i]), (LAS unsigned*)(lds + (bufoff) + ldsw + _i * 8192), 16, 0, 0); } while (0)
; #define PG8_LDA(dst, b, h) do { _Pragma("unroll") for (int m = 0; m < 4; ++m) _Pragma("unroll") for (int k = 0; k < 2; ++k) dst[m][k] = *(const LAS bf16x8*)(lds + PG8_SA(b, h) + aoff + m * 2048 + k * 1024); } while (0)
; #define PG8_LDB(dst, b, h) do { _Pragma("unroll") for (int n = 0; n < 2; ++n) _Pragma("unroll") for (int k = 0; k < 2; ++k) dst[n][k] = *(const LAS bf16x8*)(lds + PG8_SB(b, h) + boff + n * 2048 + k * 1024); } while (0)
; #define PG8_WAIT_V(n) asm volatile("s_waitcnt vmcnt(" #n ")" ::: "memory")
; #define PG8_WAIT_L(n) asm volatile("s_waitcnt lgkmcnt(" #n ")" ::: "memory")
; #define PG8_BAR __builtin_amdgcn_s_barrier()
; #define PG8_SCHED __builtin_amdgcn_sched_barrier(0)
; template <class Epi, class Sched>
; DI void gemm_phase(LAS unsigned char* lds, const Gemm g, const Sched& S, const Epi& E) {
;     ...
;       PG8_WAIT_V(6); PG8_BAR; PG8_MMA(1, 1, At, B1); PG8_BAR;
;       PG8_LDB(B0, 1, 0); PG8_SCHED; PG8_LDA(At, 1, 0); PG8_STAGE(PG8_SA(0, 1), a2 + hstep, voffA);
;       PG8_WAIT_L(8); PG8_BAR; PG8_WAIT_L(0); PG8_MMA(0, 0, At, B0); PG8_BAR; PG8_SCHED;
;       PG8_LDB(B1, 1, 1); PG8_STAGE(PG8_SB(1, 0), b3, voffB);
;       PG8_BAR; PG8_WAIT_L(0); PG8_MMA(0, 1, At, B1); PG8_BAR;
;       PG8_LDA(At, 1, 1); PG8_STAGE(PG8_SA(1, 0), a3, voffA);
;       PG8_BAR; PG8_WAIT_L(0); PG8_MMA(1, 0, At, B0); PG8_BAR; PG8_SCHED;
;       PG8_STAGE(PG8_SB(1, 1), b3 + hstep, voffB);
;       PG8_WAIT_V(6); PG8_BAR; PG8_MMA(1, 1, At, B1); PG8_BAR;
;   DI void operator()(const f32x4 (&acc)[2][2][4][2], const pg8::Unit& u, int wr, int wc, int fr_, int fq_) const {
;     ...
;             } else if (EPI == EPI_UQ) {
;               if (n == 0) {
;                 const float sc = rinv * (0.10206207261596575f * LOG2E);
;                 const int gb = u.pn * 256 + bj * 128 + wc * 32;
;                 const int hd = gb / 96; const int within = gb - hd * 96;
;                 f32x4 a0 = v, a1 = acc[ai][bj][m][1];
;                 if (within == 64) rope_perm(a0, a1, fq, t_ & 63, tcos, tsin, token & (S_ - 1));
;                 st_bf8((u16*)(big + E_QMLA) + (size_t)token * 768 + gb + 8 * fq, a0, a1, sc);
	s_waitcnt lgkmcnt(0)
	s_waitcnt lgkmcnt(0)
	v_mfma_f32_16x16x32_bf16 v[60:63], v[140:143], v[158:161], v[60:63]
	v_mfma_f32_16x16x32_bf16 v[56:59], v[150:153], v[158:161], v[56:59]
	v_mfma_f32_16x16x32_bf16 v[44:47], v[140:143], v[168:171], v[44:47]
	v_mfma_f32_16x16x32_bf16 v[40:43], v[150:153], v[168:171], v[40:43]
	v_mfma_f32_16x16x32_bf16 v[28:31], v[140:143], v[176:179], v[28:31]
	v_mfma_f32_16x16x32_bf16 v[24:27], v[150:153], v[176:179], v[24:27]
	v_mfma_f32_16x16x32_bf16 v[12:15], v[140:143], v[200:203], v[12:15]
	v_mfma_f32_16x16x32_bf16 v[8:11], v[150:153], v[200:203], v[8:11]
	v_mfma_f32_16x16x32_bf16 v[60:63], v[146:149], v[164:167], v[60:63]
	v_mfma_f32_16x16x32_bf16 v[56:59], v[154:157], v[164:167], v[56:59]
	v_mfma_f32_16x16x32_bf16 v[44:47], v[146:149], v[172:175], v[44:47]
	v_mfma_f32_16x16x32_bf16 v[40:43], v[154:157], v[172:175], v[40:43]
	v_mfma_f32_16x16x32_bf16 v[28:31], v[146:149], v[196:199], v[28:31]
	v_mfma_f32_16x16x32_bf16 v[24:27], v[154:157], v[196:199], v[24:27]
	v_mfma_f32_16x16x32_bf16 v[12:15], v[146:149], v[204:207], v[12:15]
	v_mfma_f32_16x16x32_bf16 v[8:11], v[154:157], v[204:207], v[8:11]
	s_barrier
	s_add_u32 s18, s22, 0x18080
	s_addc_u32 s19, s23, 0
	s_add_i32 s22, s28, s35
	s_mov_b32 m0, s22
	s_nop 0
	global_load_lds_dwordx4 v130, s[18:19]
	s_add_i32 m0, s22, 0x2000
	s_nop 0
	global_load_lds_dwordx4 v134, s[18:19]
	s_waitcnt vmcnt(6)
	s_barrier
	v_mfma_f32_16x16x32_bf16 v[52:55], v[208:211], v[158:161], v[52:55]
	v_mfma_f32_16x16x32_bf16 v[48:51], v[216:219], v[158:161], v[48:51]
	v_mfma_f32_16x16x32_bf16 v[36:39], v[208:211], v[168:171], v[36:39]
	v_mfma_f32_16x16x32_bf16 v[32:35], v[216:219], v[168:171], v[32:35]
	v_mfma_f32_16x16x32_bf16 v[20:23], v[208:211], v[176:179], v[20:23]
	v_mfma_f32_16x16x32_bf16 v[16:19], v[216:219], v[176:179], v[16:19]
	v_mfma_f32_16x16x32_bf16 v[4:7], v[208:211], v[200:203], v[4:7]
	v_mfma_f32_16x16x32_bf16 v[0:3], v[216:219], v[200:203], v[0:3]
	v_mfma_f32_16x16x32_bf16 v[52:55], v[212:215], v[164:167], v[52:55]
	v_mfma_f32_16x16x32_bf16 v[48:51], v[220:223], v[164:167], v[48:51]
	v_mfma_f32_16x16x32_bf16 v[36:39], v[212:215], v[172:175], v[36:39]
	v_mfma_f32_16x16x32_bf16 v[32:35], v[220:223], v[172:175], v[32:35]
	v_mfma_f32_16x16x32_bf16 v[20:23], v[212:215], v[196:199], v[20:23]
	v_mfma_f32_16x16x32_bf16 v[16:19], v[220:223], v[196:199], v[16:19]
	v_mfma_f32_16x16x32_bf16 v[4:7], v[212:215], v[204:207], v[4:7]
	v_mfma_f32_16x16x32_bf16 v[0:3], v[220:223], v[204:207], v[0:3]
	s_add_i32 s54, s54, 2
	s_add_u32 s52, s52, 0x100
	s_addc_u32 s53, s53, 0
	s_cmp_gt_u32 s54, 3
	s_mov_b64 s[18:19], s[20:21]
	s_barrier
	s_cbranch_scc0 .LBB0_1202
	v_mov_b32_e32 v140, v182
	s_lshl_b32 s19, s51, 10
	s_lshl_b32 s18, s49, 8
	s_or_b32 s18, s18, s43
	v_and_or_b32 v167, v140, 15, s42
	v_lshlrev_b32_e32 v141, 2, v140
	s_movk_i32 s20, 0x80
	s_add_i32 s19, s19, 0
	v_bitop3_b32 v164, v141, s20, v190 bitop3:0x6c
	v_lshl_add_u32 v141, v167, 2, s19
	s_mul_hi_i32 s19, s18, 0x2aaaaaab
	v_add_u32_e32 v166, 0x20000, v141
	s_lshr_b32 s20, s19, 31
	s_lshr_b32 s19, s19, 4
	s_lshl_b32 s50, s50, 8
	ds_read_b32 v144, v166
	s_add_i32 s19, s19, s20
	v_add_u32_e32 v165, s50, v167
	s_mulk_i32 s19, 0x60
	v_bfe_u32 v168, v140, 4, 2
	v_lshrrev_b32_e32 v140, 1, v140
	v_lshlrev_b32_e32 v141, 4, v165
	s_sub_i32 s19, s18, s19
	v_and_b32_e32 v140, 8, v140
	v_and_b32_e32 v141, 0xfcf0, v141
	s_cmp_eq_u32 s19, 64
	v_cmp_lt_u32_e64 s[78:79], 1, v168
	s_cselect_b64 s[20:21], -1, 0
	s_cmp_lg_u32 s19, 64
	v_lshlrev_b32_e32 v142, 2, v141
	v_lshlrev_b32_e32 v140, 2, v140
	s_cbranch_scc1 .LBB0_1209
	v_mov_b32_e32 v143, v145
	v_lshl_add_u64 v[146:147], s[12:13], 0, v[142:143]
	v_mov_b32_e32 v141, v145
	v_lshl_add_u64 v[152:153], s[14:15], 0, v[142:143]
	v_lshl_add_u64 v[146:147], v[146:147], 0, v[140:141]
	v_lshl_add_u64 v[152:153], v[152:153], 0, v[140:141]
	global_load_dwordx4 v[148:151], v[146:147], off
	global_load_dwordx4 v[154:157], v[152:153], off
	global_load_dwordx4 v[170:173], v[152:153], off offset:16
	global_load_dwordx4 v[174:177], v[146:147], off offset:16
	ds_bpermute_b32 v152, v164, v124
	ds_bpermute_b32 v160, v164, v120
	ds_bpermute_b32 v153, v164, v125
	ds_bpermute_b32 v161, v164, v121
	ds_bpermute_b32 v158, v164, v126
	ds_bpermute_b32 v178, v164, v122
	ds_bpermute_b32 v159, v164, v127
	ds_bpermute_b32 v179, v164, v123
	s_waitcnt vmcnt(0) lgkmcnt(0)
	v_pk_mul_f32 v[154:155], v[154:155], v[152:153]
	v_pk_mul_f32 v[146:147], v[126:127], v[150:151]
	v_pk_mul_f32 v[150:151], v[124:125], v[148:149]
	v_pk_mul_f32 v[158:159], v[156:157], v[158:159]
	v_pk_mul_f32 v[148:149], v[170:171], v[160:161]
	v_pk_mul_f32 v[152:153], v[172:173], v[178:179]
	v_pk_mul_f32 v[156:157], v[122:123], v[176:177]
	v_pk_mul_f32 v[160:161], v[120:121], v[174:175]
	s_and_saveexec_b64 s[22:23], s[78:79]
	s_xor_b64 s[22:23], exec, s[22:23]
	v_pk_add_f32 v[126:127], v[146:147], v[158:159]
	v_pk_add_f32 v[124:125], v[150:151], v[154:155]
	v_pk_add_f32 v[122:123], v[156:157], v[152:153]
	v_pk_add_f32 v[120:121], v[160:161], v[148:149]
	s_andn2_saveexec_b64 s[22:23], s[22:23]
	v_sub_f32_e32 v127, v147, v159
	v_sub_f32_e32 v126, v146, v158
	v_sub_f32_e32 v125, v151, v155
	v_sub_f32_e32 v124, v150, v154
	v_sub_f32_e32 v123, v157, v153
	v_sub_f32_e32 v122, v156, v152
	v_sub_f32_e32 v121, v161, v149
	v_sub_f32_e32 v120, v160, v148
	s_or_b64 exec, exec, s[22:23]

; #define PG8_STAGE(bufoff, gbase, voff) do { _Pragma("unroll") for (int _i = 0; _i < 2; ++_i) \
;     __builtin_amdgcn_global_load_lds((const unsigned*)((const char*)(gbase) + (voff)[_i]), (LAS unsigned*)(lds + (bufoff) + ldsw + _i * 8192), 16, 0, 0); } while (0)
; #define PG8_LDA(dst, b, h) do { _Pragma("unroll") for (int m = 0; m < 4; ++m) _Pragma("unroll") for (int k = 0; k < 2; ++k) dst[m][k] = *(const LAS bf16x8*)(lds + PG8_SA(b, h) + aoff + m * 2048 + k * 1024); } while (0)
; #define PG8_LDB(dst, b, h) do { _Pragma("unroll") for (int n = 0; n < 2; ++n) _Pragma("unroll") for (int k = 0; k < 2; ++k) dst[n][k] = *(const LAS bf16x8*)(lds + PG8_SB(b, h) + boff + n * 2048 + k * 1024); } while (0)
; #define PG8_WAIT_V(n) asm volatile("s_waitcnt vmcnt(" #n ")" ::: "memory")
; template <class Epi, class Sched>
; DI void gemm_phase(LAS unsigned char* lds, const Gemm g, const Sched& S, const Epi& E) {
;     ...
;     for (int t = 0; t < nt; t += 2) {
;       const bool last = (t == nt - 2);
;       const char* a1 = cA + (size_t)(t + 1) * kstep;
;       const char* a2 = last ? nA : cA + (size_t)(t + 2) * kstep; const char* b2 = last ? nB : cB + (size_t)(t + 2) * kstep;
;       const char* a3 = a2 + kstep; const char* b3 = b2 + kstep;
;       PG8_LDB(B0, 0, 0); PG8_SCHED; PG8_LDA(At, 0, 0); PG8_STAGE(PG8_SA(1, 1), a1 + hstep, voffA);
;       PG8_WAIT_L(8); PG8_BAR; PG8_WAIT_L(0); PG8_MMA(0, 0, At, B0); PG8_BAR; PG8_SCHED;
;       PG8_LDB(B1, 0, 1); PG8_STAGE(PG8_SB(0, 0), b2, voffB);
;       PG8_BAR; PG8_WAIT_L(0); PG8_MMA(0, 1, At, B1); PG8_BAR;
;       PG8_LDA(At, 0, 1); PG8_STAGE(PG8_SA(0, 0), a2, voffA);
;       PG8_BAR; PG8_WAIT_L(0); PG8_MMA(1, 0, At, B0); PG8_BAR; PG8_SCHED;
;       PG8_STAGE(PG8_SB(0, 1), b2 + hstep, voffB);
;       PG8_WAIT_V(6); PG8_BAR; PG8_MMA(1, 1, At, B1); PG8_BAR;
;       PG8_LDB(B0, 1, 0); PG8_SCHED; PG8_LDA(At, 1, 0); PG8_STAGE(PG8_SA(0, 1), a2 + hstep, voffA);
;       PG8_WAIT_L(8); PG8_BAR; PG8_WAIT_L(0); PG8_MMA(0, 0, At, B0); PG8_BAR; PG8_SCHED;
;       PG8_LDB(B1, 1, 1); PG8_STAGE(PG8_SB(1, 0), b3, voffB);
;       PG8_BAR; PG8_WAIT_L(0); PG8_MMA(0, 1, At, B1); PG8_BAR;
;       PG8_LDA(At, 1, 1); PG8_STAGE(PG8_SA(1, 0), a3, voffA);
;       PG8_BAR; PG8_WAIT_L(0); PG8_MMA(1, 0, At, B0); PG8_BAR; PG8_SCHED;
;       PG8_STAGE(PG8_SB(1, 1), b3 + hstep, voffB);
;       PG8_WAIT_V(6); PG8_BAR; PG8_MMA(1, 1, At, B1); PG8_BAR;
.LBB0_1346:
	s_add_u32 s48, s28, s40
	s_addc_u32 s49, s29, s41
	s_add_u32 s44, s48, 0x100
	s_addc_u32 s45, s49, 0
	s_and_b64 s[42:43], s[36:37], exec
	s_cselect_b32 s45, s15, s45
	s_cselect_b32 s44, s21, s44
	s_add_u32 s40, s22, s40
	s_addc_u32 s41, s23, s41
	s_add_u32 s40, s40, 0x100
	s_addc_u32 s41, s41, 0
	s_add_i32 s70, 0, 0x10000
	s_and_b64 s[36:37], s[36:37], exec
	s_cselect_b32 s47, s13, s41
	s_cselect_b32 s46, s24, s40
	s_add_u32 s48, s48, 0x10080
	s_addc_u32 s49, s49, 0
	s_add_i32 s74, s70, s51
	s_add_i32 m0, s56, 0xc000
	s_add_i32 s75, s56, 0xe000
	s_add_i32 s73, 0, 0x14000
	s_add_i32 s72, s74, 0x2000
	s_add_u32 s42, s46, 0x10000
	v_add_u32_e32 v140, s70, v142
	s_addc_u32 s43, s47, 0
	s_add_i32 s69, s73, s51
	ds_read_b128 v[136:139], v140
	ds_read_b128 v[146:149], v140 offset:1024
	ds_read_b128 v[150:153], v140 offset:2048
	ds_read_b128 v[154:157], v140 offset:3072
	s_add_i32 s68, s69, 0x2000
	s_add_i32 s67, 0, 0x18000
	s_add_u32 s40, s44, 0x10000
	s_addc_u32 s41, s45, 0
	s_add_i32 s66, s67, s51
	s_add_i32 s65, 0, 0x1c000
	s_add_i32 s64, s66, 0x2000
	s_add_u32 s36, s46, 0x10080
	s_addc_u32 s37, s47, 0
	s_add_i32 s71, s65, s51
	s_add_i32 s70, s71, 0x2000
	ds_read_b128 v[158:161], v143
	ds_read_b128 v[162:165], v143 offset:1024
	ds_read_b128 v[166:169], v143 offset:2048
	ds_read_b128 v[170:173], v143 offset:3072
	ds_read_b128 v[174:177], v143 offset:4096
	ds_read_b128 v[178:181], v143 offset:5120
	ds_read_b128 v[196:199], v143 offset:6144
	ds_read_b128 v[200:203], v143 offset:7168
	global_load_lds_dwordx4 v128, s[48:49]
	s_mov_b32 m0, s75
	s_nop 0
	global_load_lds_dwordx4 v132, s[48:49]
	s_waitcnt lgkmcnt(8)
	s_barrier
	s_waitcnt lgkmcnt(0)
	s_waitcnt lgkmcnt(0)
	v_mfma_f32_16x16x32_bf16 v[124:127], v[136:139], v[158:161], v[124:127]
	v_mfma_f32_16x16x32_bf16 v[120:123], v[150:153], v[158:161], v[120:123]
	v_mfma_f32_16x16x32_bf16 v[108:111], v[136:139], v[166:169], v[108:111]
	v_mfma_f32_16x16x32_bf16 v[104:107], v[150:153], v[166:169], v[104:107]
	v_mfma_f32_16x16x32_bf16 v[92:95], v[136:139], v[174:177], v[92:95]
	v_mfma_f32_16x16x32_bf16 v[88:91], v[150:153], v[174:177], v[88:91]
	v_mfma_f32_16x16x32_bf16 v[76:79], v[136:139], v[196:199], v[76:79]
	v_mfma_f32_16x16x32_bf16 v[72:75], v[150:153], v[196:199], v[72:75]
	v_mfma_f32_16x16x32_bf16 v[124:127], v[146:149], v[162:165], v[124:127]
	v_mfma_f32_16x16x32_bf16 v[120:123], v[154:157], v[162:165], v[120:123]
	v_mfma_f32_16x16x32_bf16 v[108:111], v[146:149], v[170:173], v[108:111]
	v_mfma_f32_16x16x32_bf16 v[104:107], v[154:157], v[170:173], v[104:107]
	v_mfma_f32_16x16x32_bf16 v[92:95], v[146:149], v[178:181], v[92:95]
	v_mfma_f32_16x16x32_bf16 v[88:91], v[154:157], v[178:181], v[88:91]
	v_mfma_f32_16x16x32_bf16 v[76:79], v[146:149], v[200:203], v[76:79]
	v_mfma_f32_16x16x32_bf16 v[72:75], v[154:157], v[200:203], v[72:75]
	s_barrier
	v_add_u32_e32 v140, s73, v142
	s_mov_b32 m0, s74
	ds_read_b128 v[204:207], v140
	ds_read_b128 v[208:211], v140 offset:1024
	ds_read_b128 v[212:215], v140 offset:2048
	ds_read_b128 v[216:219], v140 offset:3072
	s_add_u32 vcc_lo, s46, s0
	s_addc_u32 vcc_hi, s47, s1
	global_load_lds_dwordx4 v130, s[46:47]
	s_mov_b32 m0, s72
	s_nop 0
	global_load_lds_dwordx4 v134, s[46:47]
	s_barrier
	s_waitcnt lgkmcnt(0)
	s_waitcnt lgkmcnt(0)
	v_mfma_f32_16x16x32_bf16 v[116:119], v[204:207], v[158:161], v[116:119]
	v_mfma_f32_16x16x32_bf16 v[112:115], v[212:215], v[158:161], v[112:115]
	v_mfma_f32_16x16x32_bf16 v[100:103], v[204:207], v[166:169], v[100:103]
	v_mfma_f32_16x16x32_bf16 v[96:99], v[212:215], v[166:169], v[96:99]
	v_mfma_f32_16x16x32_bf16 v[84:87], v[204:207], v[174:177], v[84:87]
	v_mfma_f32_16x16x32_bf16 v[80:83], v[212:215], v[174:177], v[80:83]
	v_mfma_f32_16x16x32_bf16 v[68:71], v[204:207], v[196:199], v[68:71]
	v_mfma_f32_16x16x32_bf16 v[64:67], v[212:215], v[196:199], v[64:67]
	v_mfma_f32_16x16x32_bf16 v[116:119], v[208:211], v[162:165], v[116:119]
	v_mfma_f32_16x16x32_bf16 v[112:115], v[216:219], v[162:165], v[112:115]
	v_mfma_f32_16x16x32_bf16 v[100:103], v[208:211], v[170:173], v[100:103]
	v_mfma_f32_16x16x32_bf16 v[96:99], v[216:219], v[170:173], v[96:99]
	v_mfma_f32_16x16x32_bf16 v[84:87], v[208:211], v[178:181], v[84:87]
	v_mfma_f32_16x16x32_bf16 v[80:83], v[216:219], v[178:181], v[80:83]
	v_mfma_f32_16x16x32_bf16 v[68:71], v[208:211], v[200:203], v[68:71]
	v_mfma_f32_16x16x32_bf16 v[64:67], v[216:219], v[200:203], v[64:67]
	s_mov_b32 m0, s56
	s_add_u32 s100, s44, s0
	s_addc_u32 s101, s45, s1
	s_barrier
	ds_read_b128 v[158:161], v143 offset:16384
	ds_read_b128 v[162:165], v143 offset:17408
	ds_read_b128 v[166:169], v143 offset:18432
	ds_read_b128 v[170:173], v143 offset:19456
	ds_read_b128 v[174:177], v143 offset:20480
	ds_read_b128 v[178:181], v143 offset:21504
	ds_read_b128 v[196:199], v143 offset:22528
	ds_read_b128 v[200:203], v143 offset:23552
	global_load_lds_dwordx4 v128, s[44:45]
	s_mov_b32 m0, s57
	s_nop 0
	global_load_lds_dwordx4 v132, s[44:45]
	s_barrier
	s_waitcnt lgkmcnt(0)
	s_waitcnt lgkmcnt(0)
	v_mfma_f32_16x16x32_bf16 v[60:63], v[136:139], v[158:161], v[60:63]
	v_mfma_f32_16x16x32_bf16 v[56:59], v[150:153], v[158:161], v[56:59]
	v_mfma_f32_16x16x32_bf16 v[44:47], v[136:139], v[166:169], v[44:47]
	v_mfma_f32_16x16x32_bf16 v[40:43], v[150:153], v[166:169], v[40:43]
	v_mfma_f32_16x16x32_bf16 v[28:31], v[136:139], v[174:177], v[28:31]
	v_mfma_f32_16x16x32_bf16 v[24:27], v[150:153], v[174:177], v[24:27]
	v_mfma_f32_16x16x32_bf16 v[12:15], v[136:139], v[196:199], v[12:15]
	v_mfma_f32_16x16x32_bf16 v[8:11], v[150:153], v[196:199], v[8:11]
	v_mfma_f32_16x16x32_bf16 v[60:63], v[146:149], v[162:165], v[60:63]
	v_mfma_f32_16x16x32_bf16 v[56:59], v[154:157], v[162:165], v[56:59]
	v_mfma_f32_16x16x32_bf16 v[44:47], v[146:149], v[170:173], v[44:47]
	v_mfma_f32_16x16x32_bf16 v[40:43], v[154:157], v[170:173], v[40:43]
	v_mfma_f32_16x16x32_bf16 v[28:31], v[146:149], v[178:181], v[28:31]
	v_mfma_f32_16x16x32_bf16 v[24:27], v[154:157], v[178:181], v[24:27]
	v_mfma_f32_16x16x32_bf16 v[12:15], v[146:149], v[200:203], v[12:15]
	v_mfma_f32_16x16x32_bf16 v[8:11], v[154:157], v[200:203], v[8:11]
	s_barrier
; #define PG8_STAGE(bufoff, gbase, voff) do { _Pragma("unroll") for (int _i = 0; _i < 2; ++_i) \
;     __builtin_amdgcn_global_load_lds((const unsigned*)((const char*)(gbase) + (voff)[_i]), (LAS unsigned*)(lds + (bufoff) + ldsw + _i * 8192), 16, 0, 0); } while (0)
; #define PG8_LDA(dst, b, h) do { _Pragma("unroll") for (int m = 0; m < 4; ++m) _Pragma("unroll") for (int k = 0; k < 2; ++k) dst[m][k] = *(const LAS bf16x8*)(lds + PG8_SA(b, h) + aoff + m * 2048 + k * 1024); } while (0)
; #define PG8_LDB(dst, b, h) do { _Pragma("unroll") for (int n = 0; n < 2; ++n) _Pragma("unroll") for (int k = 0; k < 2; ++k) dst[n][k] = *(const LAS bf16x8*)(lds + PG8_SB(b, h) + boff + n * 2048 + k * 1024); } while (0)
; #define PG8_WAIT_V(n) asm volatile("s_waitcnt vmcnt(" #n ")" ::: "memory")
; template <class Epi, class Sched>
; DI void gemm_phase(LAS unsigned char* lds, const Gemm g, const Sched& S, const Epi& E) {
;     ...
;     for (int t = 0; t < nt; t += 2) {
;       const bool last = (t == nt - 2);
;       const char* a1 = cA + (size_t)(t + 1) * kstep;
;       const char* a2 = last ? nA : cA + (size_t)(t + 2) * kstep; const char* b2 = last ? nB : cB + (size_t)(t + 2) * kstep;
;       const char* a3 = a2 + kstep; const char* b3 = b2 + kstep;
;       PG8_LDB(B0, 0, 0); PG8_SCHED; PG8_LDA(At, 0, 0); PG8_STAGE(PG8_SA(1, 1), a1 + hstep, voffA);
;       PG8_WAIT_L(8); PG8_BAR; PG8_WAIT_L(0); PG8_MMA(0, 0, At, B0); PG8_BAR; PG8_SCHED;
;       PG8_LDB(B1, 0, 1); PG8_STAGE(PG8_SB(0, 0), b2, voffB);
;       PG8_BAR; PG8_WAIT_L(0); PG8_MMA(0, 1, At, B1); PG8_BAR;
;       PG8_LDA(At, 0, 1); PG8_STAGE(PG8_SA(0, 0), a2, voffA);
;       PG8_BAR; PG8_WAIT_L(0); PG8_MMA(1, 0, At, B0); PG8_BAR; PG8_SCHED;
;       PG8_STAGE(PG8_SB(0, 1), b2 + hstep, voffB);
;       PG8_WAIT_V(6); PG8_BAR; PG8_MMA(1, 1, At, B1); PG8_BAR;
;       PG8_LDB(B0, 1, 0); PG8_SCHED; PG8_LDA(At, 1, 0); PG8_STAGE(PG8_SA(0, 1), a2 + hstep, voffA);
;       PG8_WAIT_L(8); PG8_BAR; PG8_WAIT_L(0); PG8_MMA(0, 0, At, B0); PG8_BAR; PG8_SCHED;
;       PG8_LDB(B1, 1, 1); PG8_STAGE(PG8_SB(1, 0), b3, voffB);
;       PG8_BAR; PG8_WAIT_L(0); PG8_MMA(0, 1, At, B1); PG8_BAR;
;       PG8_LDA(At, 1, 1); PG8_STAGE(PG8_SA(1, 0), a3, voffA);
;       PG8_BAR; PG8_WAIT_L(0); PG8_MMA(1, 0, At, B0); PG8_BAR; PG8_SCHED;
;       PG8_STAGE(PG8_SB(1, 1), b3 + hstep, voffB);
;       PG8_WAIT_V(6); PG8_BAR; PG8_MMA(1, 1, At, B1); PG8_BAR;
	s_mov_b32 m0, s69
	s_nop 0
	global_load_lds_dwordx4 v130, s[42:43]
	s_mov_b32 m0, s68
	s_nop 0
	global_load_lds_dwordx4 v134, s[42:43]
	s_waitcnt vmcnt(6)
	s_barrier
	v_mfma_f32_16x16x32_bf16 v[52:55], v[204:207], v[158:161], v[52:55]
	v_mfma_f32_16x16x32_bf16 v[48:51], v[212:215], v[158:161], v[48:51]
	v_mfma_f32_16x16x32_bf16 v[36:39], v[204:207], v[166:169], v[36:39]
	v_mfma_f32_16x16x32_bf16 v[32:35], v[212:215], v[166:169], v[32:35]
	v_mfma_f32_16x16x32_bf16 v[20:23], v[204:207], v[174:177], v[20:23]
	v_mfma_f32_16x16x32_bf16 v[16:19], v[212:215], v[174:177], v[16:19]
	v_mfma_f32_16x16x32_bf16 v[4:7], v[204:207], v[196:199], v[4:7]
	v_mfma_f32_16x16x32_bf16 v[0:3], v[212:215], v[196:199], v[0:3]
	v_mfma_f32_16x16x32_bf16 v[52:55], v[208:211], v[162:165], v[52:55]
	v_mfma_f32_16x16x32_bf16 v[48:51], v[216:219], v[162:165], v[48:51]
	v_mfma_f32_16x16x32_bf16 v[36:39], v[208:211], v[170:173], v[36:39]
	v_mfma_f32_16x16x32_bf16 v[32:35], v[216:219], v[170:173], v[32:35]
	v_mfma_f32_16x16x32_bf16 v[20:23], v[208:211], v[178:181], v[20:23]
	v_mfma_f32_16x16x32_bf16 v[16:19], v[216:219], v[178:181], v[16:19]
	v_mfma_f32_16x16x32_bf16 v[4:7], v[208:211], v[200:203], v[4:7]
	v_mfma_f32_16x16x32_bf16 v[0:3], v[216:219], v[200:203], v[0:3]
	v_add_u32_e32 v144, s67, v142
	s_barrier
	ds_read_b128 v[136:139], v144
	ds_read_b128 v[146:149], v144 offset:1024
	ds_read_b128 v[150:153], v144 offset:2048
	ds_read_b128 v[154:157], v144 offset:3072
	s_mov_b32 m0, s58
	ds_read_b128 v[158:161], v143 offset:32768
	ds_read_b128 v[162:165], v143 offset:33792
	ds_read_b128 v[166:169], v143 offset:34816
	ds_read_b128 v[170:173], v143 offset:35840
	ds_read_b128 v[174:177], v143 offset:36864
	ds_read_b128 v[178:181], v143 offset:37888
	ds_read_b128 v[196:199], v143 offset:38912
	ds_read_b128 v[200:203], v143 offset:39936
	global_load_lds_dwordx4 v128, s[40:41]
	s_mov_b32 m0, s59
	s_nop 0
	global_load_lds_dwordx4 v132, s[40:41]
	s_waitcnt lgkmcnt(8)
	s_barrier
	s_waitcnt lgkmcnt(0)
	s_waitcnt lgkmcnt(0)
	v_mfma_f32_16x16x32_bf16 v[124:127], v[136:139], v[158:161], v[124:127]
	v_mfma_f32_16x16x32_bf16 v[120:123], v[150:153], v[158:161], v[120:123]
	v_mfma_f32_16x16x32_bf16 v[108:111], v[136:139], v[166:169], v[108:111]
	v_mfma_f32_16x16x32_bf16 v[104:107], v[150:153], v[166:169], v[104:107]
	v_mfma_f32_16x16x32_bf16 v[92:95], v[136:139], v[174:177], v[92:95]
	v_mfma_f32_16x16x32_bf16 v[88:91], v[150:153], v[174:177], v[88:91]
	v_mfma_f32_16x16x32_bf16 v[76:79], v[136:139], v[196:199], v[76:79]
	v_mfma_f32_16x16x32_bf16 v[72:75], v[150:153], v[196:199], v[72:75]
	v_mfma_f32_16x16x32_bf16 v[124:127], v[146:149], v[162:165], v[124:127]
	v_mfma_f32_16x16x32_bf16 v[120:123], v[154:157], v[162:165], v[120:123]
	v_mfma_f32_16x16x32_bf16 v[108:111], v[146:149], v[170:173], v[108:111]
	v_mfma_f32_16x16x32_bf16 v[104:107], v[154:157], v[170:173], v[104:107]
	v_mfma_f32_16x16x32_bf16 v[92:95], v[146:149], v[178:181], v[92:95]
	v_mfma_f32_16x16x32_bf16 v[88:91], v[154:157], v[178:181], v[88:91]
	v_mfma_f32_16x16x32_bf16 v[76:79], v[146:149], v[200:203], v[76:79]
	v_mfma_f32_16x16x32_bf16 v[72:75], v[154:157], v[200:203], v[72:75]
	s_barrier
	s_mov_b32 m0, s66
	v_add_u32_e32 v144, s65, v142
	ds_read_b128 v[204:207], v144
	ds_read_b128 v[208:211], v144 offset:1024
	ds_read_b128 v[212:215], v144 offset:2048
	ds_read_b128 v[216:219], v144 offset:3072
	global_load_lds_dwordx4 v130, vcc
	s_mov_b32 m0, s64
	s_nop 0
	global_load_lds_dwordx4 v134, vcc
	s_barrier
	s_waitcnt lgkmcnt(0)
	s_waitcnt lgkmcnt(0)
	v_mfma_f32_16x16x32_bf16 v[116:119], v[204:207], v[158:161], v[116:119]
	v_mfma_f32_16x16x32_bf16 v[112:115], v[212:215], v[158:161], v[112:115]
	v_mfma_f32_16x16x32_bf16 v[100:103], v[204:207], v[166:169], v[100:103]
	v_mfma_f32_16x16x32_bf16 v[96:99], v[212:215], v[166:169], v[96:99]
	v_mfma_f32_16x16x32_bf16 v[84:87], v[204:207], v[174:177], v[84:87]
	v_mfma_f32_16x16x32_bf16 v[80:83], v[212:215], v[174:177], v[80:83]
	v_mfma_f32_16x16x32_bf16 v[68:71], v[204:207], v[196:199], v[68:71]
	v_mfma_f32_16x16x32_bf16 v[64:67], v[212:215], v[196:199], v[64:67]
	v_mfma_f32_16x16x32_bf16 v[116:119], v[208:211], v[162:165], v[116:119]
	v_mfma_f32_16x16x32_bf16 v[112:115], v[216:219], v[162:165], v[112:115]
	v_mfma_f32_16x16x32_bf16 v[100:103], v[208:211], v[170:173], v[100:103]
	v_mfma_f32_16x16x32_bf16 v[96:99], v[216:219], v[170:173], v[96:99]
	v_mfma_f32_16x16x32_bf16 v[84:87], v[208:211], v[178:181], v[84:87]
	v_mfma_f32_16x16x32_bf16 v[80:83], v[216:219], v[178:181], v[80:83]
	v_mfma_f32_16x16x32_bf16 v[68:71], v[208:211], v[200:203], v[68:71]
	v_mfma_f32_16x16x32_bf16 v[64:67], v[216:219], v[200:203], v[64:67]
	s_mov_b32 m0, s62
	s_barrier
; #define PG8_STAGE(bufoff, gbase, voff) do { _Pragma("unroll") for (int _i = 0; _i < 2; ++_i) \
;     __builtin_amdgcn_global_load_lds((const unsigned*)((const char*)(gbase) + (voff)[_i]), (LAS unsigned*)(lds + (bufoff) + ldsw + _i * 8192), 16, 0, 0); } while (0)
; #define PG8_MMA(ai, bj, At, Bt) do { __builtin_amdgcn_s_setprio(1); _Pragma("unroll") for (int m = 0; m < 4; ++m) _Pragma("unroll") for (int n = 0; n < 2; ++n) _Pragma("unroll") for (int k = 0; k < 2; ++k) \
;     acc[ai][bj][m][n] = __builtin_amdgcn_mfma_f32_16x16x32_bf16(Bt[n][k], At[m][k], acc[ai][bj][m][n], 0, 0, 0); __builtin_amdgcn_s_setprio(0); } while (0)
; #define PG8_WAIT_V(n) asm volatile("s_waitcnt vmcnt(" #n ")" ::: "memory")
; #define PG8_WAIT_L(n) asm volatile("s_waitcnt lgkmcnt(" #n ")" ::: "memory")
; #define PG8_BAR __builtin_amdgcn_s_barrier()
; #define PG8_SCHED __builtin_amdgcn_sched_barrier(0)
; template <class Epi, class Sched>
; DI void gemm_phase(LAS unsigned char* lds, const Gemm g, const Sched& S, const Epi& E) {
;     ...
;       PG8_BAR; PG8_WAIT_L(0); PG8_MMA(1, 0, At, B0); PG8_BAR; PG8_SCHED;
;       PG8_STAGE(PG8_SB(1, 1), b3 + hstep, voffB);
;       PG8_WAIT_V(6); PG8_BAR; PG8_MMA(1, 1, At, B1); PG8_BAR;
;   DI void operator()(const f32x4 (&acc)[2][2][4][2], const pg8::Unit& u, int wr, int wc, int fr_, int fq_) const {
;     ...
;             } else if (EPI == EPI_UKV) {
;               if (n == 0) {
;                 const int gb = u.pn * 256 + bj * 128 + wc * 32;
;                 const int hd = gb >> 7, within = (gb & 127) + 8 * fq;
;                 const f32x4 v1 = acc[ai][bj][m][1];
;                 if (within < 64) st_bf8((u16*)(big + E_KNOPE) + (size_t)token * 512 + hd * 64 + within, v, v1, rinv);
;                 else st_bf8((u16*)(big + E_VMLAT) + (size_t)token * 512 + hd * 64 + (within - 64), v, v1, rinv);
;               }
	ds_read_b128 v[158:161], v143 offset:49152
	ds_read_b128 v[162:165], v143 offset:50176
	ds_read_b128 v[166:169], v143 offset:51200
	ds_read_b128 v[170:173], v143 offset:52224
	ds_read_b128 v[174:177], v143 offset:53248
	ds_read_b128 v[178:181], v143 offset:54272
	ds_read_b128 v[196:199], v143 offset:55296
	ds_read_b128 v[200:203], v143 offset:56320
	global_load_lds_dwordx4 v128, s[100:101]
	s_mov_b32 m0, s63
	s_nop 0
	global_load_lds_dwordx4 v132, s[100:101]
	s_barrier
	s_waitcnt lgkmcnt(0)
	s_waitcnt lgkmcnt(0)
	v_mfma_f32_16x16x32_bf16 v[60:63], v[136:139], v[158:161], v[60:63]
	v_mfma_f32_16x16x32_bf16 v[56:59], v[150:153], v[158:161], v[56:59]
	v_mfma_f32_16x16x32_bf16 v[44:47], v[136:139], v[166:169], v[44:47]
	v_mfma_f32_16x16x32_bf16 v[40:43], v[150:153], v[166:169], v[40:43]
	v_mfma_f32_16x16x32_bf16 v[28:31], v[136:139], v[174:177], v[28:31]
	v_mfma_f32_16x16x32_bf16 v[24:27], v[150:153], v[174:177], v[24:27]
	v_mfma_f32_16x16x32_bf16 v[12:15], v[136:139], v[196:199], v[12:15]
	v_mfma_f32_16x16x32_bf16 v[8:11], v[150:153], v[196:199], v[8:11]
	v_mfma_f32_16x16x32_bf16 v[60:63], v[146:149], v[162:165], v[60:63]
	v_mfma_f32_16x16x32_bf16 v[56:59], v[154:157], v[162:165], v[56:59]
	v_mfma_f32_16x16x32_bf16 v[44:47], v[146:149], v[170:173], v[44:47]
	v_mfma_f32_16x16x32_bf16 v[40:43], v[154:157], v[170:173], v[40:43]
	v_mfma_f32_16x16x32_bf16 v[28:31], v[146:149], v[178:181], v[28:31]
	v_mfma_f32_16x16x32_bf16 v[24:27], v[154:157], v[178:181], v[24:27]
	v_mfma_f32_16x16x32_bf16 v[12:15], v[146:149], v[200:203], v[12:15]
	v_mfma_f32_16x16x32_bf16 v[8:11], v[154:157], v[200:203], v[8:11]
	s_barrier
	s_mov_b32 m0, s71
	s_nop 0
	global_load_lds_dwordx4 v130, s[36:37]
	s_mov_b32 m0, s70
	s_nop 0
	global_load_lds_dwordx4 v134, s[36:37]
	s_waitcnt vmcnt(6)
	s_barrier
	v_mfma_f32_16x16x32_bf16 v[52:55], v[204:207], v[158:161], v[52:55]
	v_mfma_f32_16x16x32_bf16 v[48:51], v[212:215], v[158:161], v[48:51]
	v_mfma_f32_16x16x32_bf16 v[36:39], v[204:207], v[166:169], v[36:39]
	v_mfma_f32_16x16x32_bf16 v[32:35], v[212:215], v[166:169], v[32:35]
	v_mfma_f32_16x16x32_bf16 v[20:23], v[204:207], v[174:177], v[20:23]
	v_mfma_f32_16x16x32_bf16 v[16:19], v[212:215], v[174:177], v[16:19]
	v_mfma_f32_16x16x32_bf16 v[4:7], v[204:207], v[196:199], v[4:7]
	v_mfma_f32_16x16x32_bf16 v[0:3], v[212:215], v[196:199], v[0:3]
	v_mfma_f32_16x16x32_bf16 v[52:55], v[208:211], v[162:165], v[52:55]
	v_mfma_f32_16x16x32_bf16 v[48:51], v[216:219], v[162:165], v[48:51]
	v_mfma_f32_16x16x32_bf16 v[36:39], v[208:211], v[170:173], v[36:39]
	v_mfma_f32_16x16x32_bf16 v[32:35], v[216:219], v[170:173], v[32:35]
	v_mfma_f32_16x16x32_bf16 v[20:23], v[208:211], v[178:181], v[20:23]
	v_mfma_f32_16x16x32_bf16 v[16:19], v[216:219], v[178:181], v[16:19]
	v_mfma_f32_16x16x32_bf16 v[4:7], v[208:211], v[200:203], v[4:7]
	v_mfma_f32_16x16x32_bf16 v[0:3], v[216:219], v[200:203], v[0:3]
	s_andn2_b64 vcc, exec, s[34:35]
	s_mov_b64 s[36:37], -1
	s_mov_b64 s[34:35], 0
	s_mov_b64 s[40:41], 0x100
	s_barrier
	s_cbranch_vccz .LBB0_1346
	v_mov_b32_e32 v136, v182
	s_lshl_b32 s3, s3, 10
	s_add_i32 s3, s3, 0
	v_and_or_b32 v147, v136, 15, s60
	v_lshl_add_u32 v137, v147, 2, s3
	v_add_u32_e32 v146, 0x20000, v137
	ds_read_b32 v138, v146
	s_lshl_b32 s13, s20, 8
	v_lshrrev_b32_e32 v136, 1, v136
	v_and_or_b32 v139, v136, 24, s61
	v_add_u32_e32 v136, s13, v147
	v_ashrrev_i32_e32 v137, 31, v136
	s_waitcnt lgkmcnt(0)
	v_pk_mul_f32 v[124:125], v[124:125], v[138:139] op_sel_hi:[1,0]
	v_pk_mul_f32 v[126:127], v[126:127], v[138:139] op_sel_hi:[1,0]
	v_pk_mul_f32 v[120:121], v[120:121], v[138:139] op_sel_hi:[1,0]
	v_lshlrev_b64 v[140:141], 10, v[136:137]
	s_lshl_b32 s20, s2, 7
	v_cvt_pk_bf16_f32 v124, v124, v125
	v_cvt_pk_bf16_f32 v125, v126, v127
	v_cvt_pk_bf16_f32 v126, v120, v121
	v_pk_mul_f32 v[120:121], v[122:123], v[138:139] op_sel_hi:[1,0]
	s_ashr_i32 s21, s20, 31
	v_cvt_pk_bf16_f32 v127, v120, v121
	v_lshl_add_u64 v[120:121], s[6:7], 0, v[140:141]
	s_mov_b64 s[2:3], -1
	s_and_b64 vcc, exec, s[4:5]
	v_lshl_add_u64 v[120:121], s[20:21], 1, v[120:121]
	v_lshlrev_b32_e32 v144, 1, v139
	s_cbranch_vccz .LBB0_1349
	v_lshl_add_u64 v[122:123], v[120:121], 0, v[144:145]
	v_add_co_u32_e32 v122, vcc, 0xd9ff000, v122
	s_mov_b64 s[2:3], 0
	s_nop 0
	v_addc_co_u32_e32 v123, vcc, 0, v123, vcc
	global_store_dwordx4 v[122:123], v[124:127], off offset:3968

; #define PG8_STAGE(bufoff, gbase, voff) do { _Pragma("unroll") for (int _i = 0; _i < 2; ++_i) \
;     __builtin_amdgcn_global_load_lds((const unsigned*)((const char*)(gbase) + (voff)[_i]), (LAS unsigned*)(lds + (bufoff) + ldsw + _i * 8192), 16, 0, 0); } while (0)
; #define PG8_LDA(dst, b, h) do { _Pragma("unroll") for (int m = 0; m < 4; ++m) _Pragma("unroll") for (int k = 0; k < 2; ++k) dst[m][k] = *(const LAS bf16x8*)(lds + PG8_SA(b, h) + aoff + m * 2048 + k * 1024); } while (0)
; #define PG8_LDB(dst, b, h) do { _Pragma("unroll") for (int n = 0; n < 2; ++n) _Pragma("unroll") for (int k = 0; k < 2; ++k) dst[n][k] = *(const LAS bf16x8*)(lds + PG8_SB(b, h) + boff + n * 2048 + k * 1024); } while (0)
; #define PG8_WAIT_V(n) asm volatile("s_waitcnt vmcnt(" #n ")" ::: "memory")
; template <class Epi, class Sched>
; DI void gemm_phase(LAS unsigned char* lds, const Gemm g, const Sched& S, const Epi& E) {
;     ...
;     for (int t = 0; t < nt; t += 2) {
;       const bool last = (t == nt - 2);
;       const char* a1 = cA + (size_t)(t + 1) * kstep;
;       const char* a2 = last ? nA : cA + (size_t)(t + 2) * kstep; const char* b2 = last ? nB : cB + (size_t)(t + 2) * kstep;
;       const char* a3 = a2 + kstep; const char* b3 = b2 + kstep;
;       PG8_LDB(B0, 0, 0); PG8_SCHED; PG8_LDA(At, 0, 0); PG8_STAGE(PG8_SA(1, 1), a1 + hstep, voffA);
;       PG8_WAIT_L(8); PG8_BAR; PG8_WAIT_L(0); PG8_MMA(0, 0, At, B0); PG8_BAR; PG8_SCHED;
;       PG8_LDB(B1, 0, 1); PG8_STAGE(PG8_SB(0, 0), b2, voffB);
;       PG8_BAR; PG8_WAIT_L(0); PG8_MMA(0, 1, At, B1); PG8_BAR;
;       PG8_LDA(At, 0, 1); PG8_STAGE(PG8_SA(0, 0), a2, voffA);
;       PG8_BAR; PG8_WAIT_L(0); PG8_MMA(1, 0, At, B0); PG8_BAR; PG8_SCHED;
;       PG8_STAGE(PG8_SB(0, 1), b2 + hstep, voffB);
;       PG8_WAIT_V(6); PG8_BAR; PG8_MMA(1, 1, At, B1); PG8_BAR;
;       PG8_LDB(B0, 1, 0); PG8_SCHED; PG8_LDA(At, 1, 0); PG8_STAGE(PG8_SA(0, 1), a2 + hstep, voffA);
;       PG8_WAIT_L(8); PG8_BAR; PG8_WAIT_L(0); PG8_MMA(0, 0, At, B0); PG8_BAR; PG8_SCHED;
;       PG8_LDB(B1, 1, 1); PG8_STAGE(PG8_SB(1, 0), b3, voffB);
;       PG8_BAR; PG8_WAIT_L(0); PG8_MMA(0, 1, At, B1); PG8_BAR;
;       PG8_LDA(At, 1, 1); PG8_STAGE(PG8_SA(1, 0), a3, voffA);
;       PG8_BAR; PG8_WAIT_L(0); PG8_MMA(1, 0, At, B0); PG8_BAR; PG8_SCHED;
;       PG8_STAGE(PG8_SB(1, 1), b3 + hstep, voffB);
;       PG8_WAIT_V(6); PG8_BAR; PG8_MMA(1, 1, At, B1); PG8_BAR;
.LBB0_1644:
	s_add_u32 s4, s2, 0xfffc0080
	s_addc_u32 s5, s3, -1
	s_add_i32 s55, 0, 0x10000
	v_add_u32_e32 v152, s55, v158
	ds_read_b128 v[128:131], v152
	ds_read_b128 v[132:135], v152 offset:1024
	ds_read_b128 v[148:151], v152 offset:2048
	ds_read_b128 v[152:155], v152 offset:3072
	s_cmp_eq_u32 s54, 12
	s_cselect_b32 s29, s19, s5
	s_cselect_b32 s28, s35, s4
	s_cselect_b32 s5, s17, s53
	s_cselect_b32 s4, s51, s52
	s_add_i32 m0, s41, 0xc000
	ds_read_b128 v[160:163], v159
	ds_read_b128 v[164:167], v159 offset:1024
	ds_read_b128 v[168:171], v159 offset:2048
	ds_read_b128 v[172:175], v159 offset:3072
	ds_read_b128 v[176:179], v159 offset:4096
	ds_read_b128 v[196:199], v159 offset:5120
	ds_read_b128 v[200:203], v159 offset:6144
	ds_read_b128 v[204:207], v159 offset:7168
	global_load_lds_dwordx4 v142, s[2:3]
	s_add_i32 m0, s41, 0xe000
	s_nop 0
	global_load_lds_dwordx4 v146, s[2:3]
	s_waitcnt lgkmcnt(8)
	s_barrier
	s_waitcnt lgkmcnt(0)
	s_waitcnt lgkmcnt(0)
	v_mfma_f32_16x16x32_bf16 v[124:127], v[128:131], v[160:163], v[124:127]
	v_mfma_f32_16x16x32_bf16 v[120:123], v[148:151], v[160:163], v[120:123]
	v_mfma_f32_16x16x32_bf16 v[108:111], v[128:131], v[168:171], v[108:111]
	v_mfma_f32_16x16x32_bf16 v[104:107], v[148:151], v[168:171], v[104:107]
	v_mfma_f32_16x16x32_bf16 v[92:95], v[128:131], v[176:179], v[92:95]
	v_mfma_f32_16x16x32_bf16 v[88:91], v[148:151], v[176:179], v[88:91]
	v_mfma_f32_16x16x32_bf16 v[76:79], v[128:131], v[200:203], v[76:79]
	v_mfma_f32_16x16x32_bf16 v[72:75], v[148:151], v[200:203], v[72:75]
	v_mfma_f32_16x16x32_bf16 v[124:127], v[132:135], v[164:167], v[124:127]
	v_mfma_f32_16x16x32_bf16 v[120:123], v[152:155], v[164:167], v[120:123]
	v_mfma_f32_16x16x32_bf16 v[108:111], v[132:135], v[172:175], v[108:111]
	v_mfma_f32_16x16x32_bf16 v[104:107], v[152:155], v[172:175], v[104:107]
	v_mfma_f32_16x16x32_bf16 v[92:95], v[132:135], v[196:199], v[92:95]
	v_mfma_f32_16x16x32_bf16 v[88:91], v[152:155], v[196:199], v[88:91]
	v_mfma_f32_16x16x32_bf16 v[76:79], v[132:135], v[204:207], v[76:79]
	v_mfma_f32_16x16x32_bf16 v[72:75], v[152:155], v[204:207], v[72:75]
	s_barrier
	s_add_i32 s58, 0, 0x14000
	v_add_u32_e32 v156, s58, v158
	s_add_i32 s55, s55, s40
	ds_read_b128 v[208:211], v156
	ds_read_b128 v[212:215], v156 offset:1024
	ds_read_b128 v[216:219], v156 offset:2048
	ds_read_b128 v[220:223], v156 offset:3072
	s_add_u32 vcc_lo, s4, s0
	s_addc_u32 vcc_hi, s5, s1
	s_mov_b32 m0, s55
	s_nop 0
	global_load_lds_dwordx4 v144, s[4:5]
	s_add_i32 m0, s55, 0x2000
	s_nop 0
	global_load_lds_dwordx4 v136, s[4:5]
	s_barrier
	s_waitcnt lgkmcnt(0)
	s_waitcnt lgkmcnt(0)
	v_mfma_f32_16x16x32_bf16 v[116:119], v[208:211], v[160:163], v[116:119]
	v_mfma_f32_16x16x32_bf16 v[112:115], v[216:219], v[160:163], v[112:115]
	v_mfma_f32_16x16x32_bf16 v[100:103], v[208:211], v[168:171], v[100:103]
	v_mfma_f32_16x16x32_bf16 v[96:99], v[216:219], v[168:171], v[96:99]
	v_mfma_f32_16x16x32_bf16 v[84:87], v[208:211], v[176:179], v[84:87]
	v_mfma_f32_16x16x32_bf16 v[80:83], v[216:219], v[176:179], v[80:83]
	v_mfma_f32_16x16x32_bf16 v[68:71], v[208:211], v[200:203], v[68:71]
	v_mfma_f32_16x16x32_bf16 v[64:67], v[216:219], v[200:203], v[64:67]
	v_mfma_f32_16x16x32_bf16 v[116:119], v[212:215], v[164:167], v[116:119]
	v_mfma_f32_16x16x32_bf16 v[112:115], v[220:223], v[164:167], v[112:115]
	v_mfma_f32_16x16x32_bf16 v[100:103], v[212:215], v[172:175], v[100:103]
	v_mfma_f32_16x16x32_bf16 v[96:99], v[220:223], v[172:175], v[96:99]
	v_mfma_f32_16x16x32_bf16 v[84:87], v[212:215], v[196:199], v[84:87]
	v_mfma_f32_16x16x32_bf16 v[80:83], v[220:223], v[196:199], v[80:83]
	v_mfma_f32_16x16x32_bf16 v[68:71], v[212:215], v[204:207], v[68:71]
	v_mfma_f32_16x16x32_bf16 v[64:67], v[220:223], v[204:207], v[64:67]
	s_mov_b32 m0, s41
	s_add_u32 s100, s28, s0
	s_addc_u32 s101, s29, s1
	s_barrier
	ds_read_b128 v[160:163], v159 offset:16384
	ds_read_b128 v[164:167], v159 offset:17408
	ds_read_b128 v[168:171], v159 offset:18432
	ds_read_b128 v[172:175], v159 offset:19456
	ds_read_b128 v[176:179], v159 offset:20480
	ds_read_b128 v[196:199], v159 offset:21504
	ds_read_b128 v[200:203], v159 offset:22528
	ds_read_b128 v[204:207], v159 offset:23552
	global_load_lds_dwordx4 v140, s[28:29]
	s_mov_b32 m0, s42
	s_nop 0
	global_load_lds_dwordx4 v138, s[28:29]
	s_barrier
	s_waitcnt lgkmcnt(0)
	s_waitcnt lgkmcnt(0)
	v_mfma_f32_16x16x32_bf16 v[60:63], v[128:131], v[160:163], v[60:63]
	v_mfma_f32_16x16x32_bf16 v[56:59], v[148:151], v[160:163], v[56:59]
	v_mfma_f32_16x16x32_bf16 v[44:47], v[128:131], v[168:171], v[44:47]
	v_mfma_f32_16x16x32_bf16 v[40:43], v[148:151], v[168:171], v[40:43]
	v_mfma_f32_16x16x32_bf16 v[28:31], v[128:131], v[176:179], v[28:31]
	v_mfma_f32_16x16x32_bf16 v[24:27], v[148:151], v[176:179], v[24:27]
	v_mfma_f32_16x16x32_bf16 v[12:15], v[128:131], v[200:203], v[12:15]
	v_mfma_f32_16x16x32_bf16 v[8:11], v[148:151], v[200:203], v[8:11]
	v_mfma_f32_16x16x32_bf16 v[60:63], v[132:135], v[164:167], v[60:63]
	v_mfma_f32_16x16x32_bf16 v[56:59], v[152:155], v[164:167], v[56:59]
	v_mfma_f32_16x16x32_bf16 v[44:47], v[132:135], v[172:175], v[44:47]
	v_mfma_f32_16x16x32_bf16 v[40:43], v[152:155], v[172:175], v[40:43]
	v_mfma_f32_16x16x32_bf16 v[28:31], v[132:135], v[196:199], v[28:31]
	v_mfma_f32_16x16x32_bf16 v[24:27], v[152:155], v[196:199], v[24:27]
	v_mfma_f32_16x16x32_bf16 v[12:15], v[132:135], v[204:207], v[12:15]
	v_mfma_f32_16x16x32_bf16 v[8:11], v[152:155], v[204:207], v[8:11]
	s_barrier
	s_add_u32 s56, s4, 0x40000
	s_addc_u32 s57, s5, 0
	s_add_i32 s55, s58, s40
	s_mov_b32 m0, s55
	s_nop 0
	global_load_lds_dwordx4 v144, s[56:57]
	s_add_i32 m0, s55, 0x2000
	s_nop 0
	global_load_lds_dwordx4 v136, s[56:57]
	s_waitcnt vmcnt(6)
	s_barrier
; #define PG8_STAGE(bufoff, gbase, voff) do { _Pragma("unroll") for (int _i = 0; _i < 2; ++_i) \
;     __builtin_amdgcn_global_load_lds((const unsigned*)((const char*)(gbase) + (voff)[_i]), (LAS unsigned*)(lds + (bufoff) + ldsw + _i * 8192), 16, 0, 0); } while (0)
; #define PG8_LDA(dst, b, h) do { _Pragma("unroll") for (int m = 0; m < 4; ++m) _Pragma("unroll") for (int k = 0; k < 2; ++k) dst[m][k] = *(const LAS bf16x8*)(lds + PG8_SA(b, h) + aoff + m * 2048 + k * 1024); } while (0)
; #define PG8_LDB(dst, b, h) do { _Pragma("unroll") for (int n = 0; n < 2; ++n) _Pragma("unroll") for (int k = 0; k < 2; ++k) dst[n][k] = *(const LAS bf16x8*)(lds + PG8_SB(b, h) + boff + n * 2048 + k * 1024); } while (0)
; #define PG8_WAIT_V(n) asm volatile("s_waitcnt vmcnt(" #n ")" ::: "memory")
; template <class Epi, class Sched>
; DI void gemm_phase(LAS unsigned char* lds, const Gemm g, const Sched& S, const Epi& E) {
;     ...
;     for (int t = 0; t < nt; t += 2) {
;       const bool last = (t == nt - 2);
;       const char* a1 = cA + (size_t)(t + 1) * kstep;
;       const char* a2 = last ? nA : cA + (size_t)(t + 2) * kstep; const char* b2 = last ? nB : cB + (size_t)(t + 2) * kstep;
;       const char* a3 = a2 + kstep; const char* b3 = b2 + kstep;
;       PG8_LDB(B0, 0, 0); PG8_SCHED; PG8_LDA(At, 0, 0); PG8_STAGE(PG8_SA(1, 1), a1 + hstep, voffA);
;       PG8_WAIT_L(8); PG8_BAR; PG8_WAIT_L(0); PG8_MMA(0, 0, At, B0); PG8_BAR; PG8_SCHED;
;       PG8_LDB(B1, 0, 1); PG8_STAGE(PG8_SB(0, 0), b2, voffB);
;       PG8_BAR; PG8_WAIT_L(0); PG8_MMA(0, 1, At, B1); PG8_BAR;
;       PG8_LDA(At, 0, 1); PG8_STAGE(PG8_SA(0, 0), a2, voffA);
;       PG8_BAR; PG8_WAIT_L(0); PG8_MMA(1, 0, At, B0); PG8_BAR; PG8_SCHED;
;       PG8_STAGE(PG8_SB(0, 1), b2 + hstep, voffB);
;       PG8_WAIT_V(6); PG8_BAR; PG8_MMA(1, 1, At, B1); PG8_BAR;
;       PG8_LDB(B0, 1, 0); PG8_SCHED; PG8_LDA(At, 1, 0); PG8_STAGE(PG8_SA(0, 1), a2 + hstep, voffA);
;       PG8_WAIT_L(8); PG8_BAR; PG8_WAIT_L(0); PG8_MMA(0, 0, At, B0); PG8_BAR; PG8_SCHED;
;       PG8_LDB(B1, 1, 1); PG8_STAGE(PG8_SB(1, 0), b3, voffB);
;       PG8_BAR; PG8_WAIT_L(0); PG8_MMA(0, 1, At, B1); PG8_BAR;
;       PG8_LDA(At, 1, 1); PG8_STAGE(PG8_SA(1, 0), a3, voffA);
;       PG8_BAR; PG8_WAIT_L(0); PG8_MMA(1, 0, At, B0); PG8_BAR; PG8_SCHED;
;       PG8_STAGE(PG8_SB(1, 1), b3 + hstep, voffB);
;       PG8_WAIT_V(6); PG8_BAR; PG8_MMA(1, 1, At, B1); PG8_BAR;
	v_mfma_f32_16x16x32_bf16 v[52:55], v[208:211], v[160:163], v[52:55]
	v_mfma_f32_16x16x32_bf16 v[48:51], v[216:219], v[160:163], v[48:51]
	v_mfma_f32_16x16x32_bf16 v[36:39], v[208:211], v[168:171], v[36:39]
	v_mfma_f32_16x16x32_bf16 v[32:35], v[216:219], v[168:171], v[32:35]
	v_mfma_f32_16x16x32_bf16 v[20:23], v[208:211], v[176:179], v[20:23]
	v_mfma_f32_16x16x32_bf16 v[16:19], v[216:219], v[176:179], v[16:19]
	v_mfma_f32_16x16x32_bf16 v[4:7], v[208:211], v[200:203], v[4:7]
	v_mfma_f32_16x16x32_bf16 v[0:3], v[216:219], v[200:203], v[0:3]
	v_mfma_f32_16x16x32_bf16 v[52:55], v[212:215], v[164:167], v[52:55]
	v_mfma_f32_16x16x32_bf16 v[48:51], v[220:223], v[164:167], v[48:51]
	v_mfma_f32_16x16x32_bf16 v[36:39], v[212:215], v[172:175], v[36:39]
	v_mfma_f32_16x16x32_bf16 v[32:35], v[220:223], v[172:175], v[32:35]
	v_mfma_f32_16x16x32_bf16 v[20:23], v[212:215], v[196:199], v[20:23]
	v_mfma_f32_16x16x32_bf16 v[16:19], v[220:223], v[196:199], v[16:19]
	v_mfma_f32_16x16x32_bf16 v[4:7], v[212:215], v[204:207], v[4:7]
	v_mfma_f32_16x16x32_bf16 v[0:3], v[220:223], v[204:207], v[0:3]
	s_add_i32 s55, 0, 0x18000
	v_add_u32_e32 v152, s55, v158
	s_barrier
	ds_read_b128 v[128:131], v152
	ds_read_b128 v[132:135], v152 offset:1024
	ds_read_b128 v[148:151], v152 offset:2048
	ds_read_b128 v[152:155], v152 offset:3072
	s_add_u32 s28, s28, 0x40000
	s_addc_u32 s29, s29, 0
	s_mov_b32 m0, s43
	ds_read_b128 v[160:163], v159 offset:32768
	ds_read_b128 v[164:167], v159 offset:33792
	ds_read_b128 v[168:171], v159 offset:34816
	ds_read_b128 v[172:175], v159 offset:35840
	ds_read_b128 v[176:179], v159 offset:36864
	ds_read_b128 v[196:199], v159 offset:37888
	ds_read_b128 v[200:203], v159 offset:38912
	ds_read_b128 v[204:207], v159 offset:39936
	global_load_lds_dwordx4 v140, s[28:29]
	s_mov_b32 m0, s44
	s_nop 0
	global_load_lds_dwordx4 v138, s[28:29]
	s_waitcnt lgkmcnt(8)
	s_barrier
	s_waitcnt lgkmcnt(0)
	s_waitcnt lgkmcnt(0)
	v_mfma_f32_16x16x32_bf16 v[124:127], v[128:131], v[160:163], v[124:127]
	v_mfma_f32_16x16x32_bf16 v[120:123], v[148:151], v[160:163], v[120:123]
	v_mfma_f32_16x16x32_bf16 v[108:111], v[128:131], v[168:171], v[108:111]
	v_mfma_f32_16x16x32_bf16 v[104:107], v[148:151], v[168:171], v[104:107]
	v_mfma_f32_16x16x32_bf16 v[92:95], v[128:131], v[176:179], v[92:95]
	v_mfma_f32_16x16x32_bf16 v[88:91], v[148:151], v[176:179], v[88:91]
	v_mfma_f32_16x16x32_bf16 v[76:79], v[128:131], v[200:203], v[76:79]
	v_mfma_f32_16x16x32_bf16 v[72:75], v[148:151], v[200:203], v[72:75]
	v_mfma_f32_16x16x32_bf16 v[124:127], v[132:135], v[164:167], v[124:127]
	v_mfma_f32_16x16x32_bf16 v[120:123], v[152:155], v[164:167], v[120:123]
	v_mfma_f32_16x16x32_bf16 v[108:111], v[132:135], v[172:175], v[108:111]
	v_mfma_f32_16x16x32_bf16 v[104:107], v[152:155], v[172:175], v[104:107]
	v_mfma_f32_16x16x32_bf16 v[92:95], v[132:135], v[196:199], v[92:95]
	v_mfma_f32_16x16x32_bf16 v[88:91], v[152:155], v[196:199], v[88:91]
	v_mfma_f32_16x16x32_bf16 v[76:79], v[132:135], v[204:207], v[76:79]
	v_mfma_f32_16x16x32_bf16 v[72:75], v[152:155], v[204:207], v[72:75]
	s_barrier
	s_add_i32 s28, 0, 0x1c000
	s_add_i32 s29, s55, s40
	v_add_u32_e32 v220, s28, v158
	s_mov_b32 m0, s29
	ds_read_b128 v[208:211], v220
	ds_read_b128 v[212:215], v220 offset:1024
	ds_read_b128 v[216:219], v220 offset:2048
	ds_read_b128 v[220:223], v220 offset:3072
	global_load_lds_dwordx4 v144, vcc
	s_add_i32 m0, s29, 0x2000
	s_nop 0
	global_load_lds_dwordx4 v136, vcc
	s_barrier
	s_waitcnt lgkmcnt(0)
	s_waitcnt lgkmcnt(0)
	v_mfma_f32_16x16x32_bf16 v[116:119], v[208:211], v[160:163], v[116:119]
	v_mfma_f32_16x16x32_bf16 v[112:115], v[216:219], v[160:163], v[112:115]
	v_mfma_f32_16x16x32_bf16 v[100:103], v[208:211], v[168:171], v[100:103]
	v_mfma_f32_16x16x32_bf16 v[96:99], v[216:219], v[168:171], v[96:99]
	v_mfma_f32_16x16x32_bf16 v[84:87], v[208:211], v[176:179], v[84:87]
	v_mfma_f32_16x16x32_bf16 v[80:83], v[216:219], v[176:179], v[80:83]
	v_mfma_f32_16x16x32_bf16 v[68:71], v[208:211], v[200:203], v[68:71]
	v_mfma_f32_16x16x32_bf16 v[64:67], v[216:219], v[200:203], v[64:67]
	v_mfma_f32_16x16x32_bf16 v[116:119], v[212:215], v[164:167], v[116:119]
	v_mfma_f32_16x16x32_bf16 v[112:115], v[220:223], v[164:167], v[112:115]
	v_mfma_f32_16x16x32_bf16 v[100:103], v[212:215], v[172:175], v[100:103]
	v_mfma_f32_16x16x32_bf16 v[96:99], v[220:223], v[172:175], v[96:99]
	v_mfma_f32_16x16x32_bf16 v[84:87], v[212:215], v[196:199], v[84:87]
	v_mfma_f32_16x16x32_bf16 v[80:83], v[220:223], v[196:199], v[80:83]
	v_mfma_f32_16x16x32_bf16 v[68:71], v[212:215], v[204:207], v[68:71]
	v_mfma_f32_16x16x32_bf16 v[64:67], v[220:223], v[204:207], v[64:67]
	s_mov_b32 m0, s49
	s_barrier
; DI float bf2f(unsigned v) { return __uint_as_float(v << 16); }
; #define PG8_STAGE(bufoff, gbase, voff) do { _Pragma("unroll") for (int _i = 0; _i < 2; ++_i) \
;     __builtin_amdgcn_global_load_lds((const unsigned*)((const char*)(gbase) + (voff)[_i]), (LAS unsigned*)(lds + (bufoff) + ldsw + _i * 8192), 16, 0, 0); } while (0)
; #define PG8_MMA(ai, bj, At, Bt) do { __builtin_amdgcn_s_setprio(1); _Pragma("unroll") for (int m = 0; m < 4; ++m) _Pragma("unroll") for (int n = 0; n < 2; ++n) _Pragma("unroll") for (int k = 0; k < 2; ++k) \
;     acc[ai][bj][m][n] = __builtin_amdgcn_mfma_f32_16x16x32_bf16(Bt[n][k], At[m][k], acc[ai][bj][m][n], 0, 0, 0); __builtin_amdgcn_s_setprio(0); } while (0)
; #define PG8_WAIT_V(n) asm volatile("s_waitcnt vmcnt(" #n ")" ::: "memory")
; #define PG8_WAIT_L(n) asm volatile("s_waitcnt lgkmcnt(" #n ")" ::: "memory")
; #define PG8_BAR __builtin_amdgcn_s_barrier()
; #define PG8_SCHED __builtin_amdgcn_sched_barrier(0)
; template <class Epi, class Sched>
; DI void gemm_phase(LAS unsigned char* lds, const Gemm g, const Sched& S, const Epi& E) {
;     ...
;       PG8_BAR; PG8_WAIT_L(0); PG8_MMA(1, 0, At, B0); PG8_BAR; PG8_SCHED;
;       PG8_STAGE(PG8_SB(1, 1), b3 + hstep, voffB);
;       PG8_WAIT_V(6); PG8_BAR; PG8_MMA(1, 1, At, B1); PG8_BAR;
;   DI void operator()(const f32x4 (&acc)[2][2][4][2], const pg8::Unit& u, int wr, int wc, int fr_, int fq_) const {
;     ...
;             } else if (EPI == EPI_RESID) {
;               if (n == 0) {
;                 const int f8 = u.pn * 256 + bj * 128 + wc * 32 + 8 * fq;
;                 const f32x4 v1 = acc[ai][bj][m][1];
;                 f32x4 r0, r1;
;                 if (rsrc) {
;                   r0 = *(const f32x4*)(rsrc + (size_t)token * 1024 + f8); r1 = *(const f32x4*)(rsrc + (size_t)token * 1024 + f8 + 4);
;                 } else {
;                   const u32x4 xu = *(const u32x4*)(xr + (size_t)token * 1024 + f8);
;                   r0 = (f32x4){bf2f(xu.x & 0xffffu), bf2f(xu.x >> 16), bf2f(xu.y & 0xffffu), bf2f(xu.y >> 16)};
;                   r1 = (f32x4){bf2f(xu.z & 0xffffu), bf2f(xu.z >> 16), bf2f(xu.w & 0xffffu), bf2f(xu.w >> 16)};
;                 }
	ds_read_b128 v[160:163], v159 offset:49152
	ds_read_b128 v[164:167], v159 offset:50176
	ds_read_b128 v[168:171], v159 offset:51200
	ds_read_b128 v[172:175], v159 offset:52224
	ds_read_b128 v[176:179], v159 offset:53248
	ds_read_b128 v[196:199], v159 offset:54272
	ds_read_b128 v[200:203], v159 offset:55296
	ds_read_b128 v[204:207], v159 offset:56320
	global_load_lds_dwordx4 v140, s[100:101]
	s_mov_b32 m0, s50
	s_nop 0
	global_load_lds_dwordx4 v138, s[100:101]
	s_barrier
	s_waitcnt lgkmcnt(0)
	s_waitcnt lgkmcnt(0)
	v_mfma_f32_16x16x32_bf16 v[60:63], v[128:131], v[160:163], v[60:63]
	v_mfma_f32_16x16x32_bf16 v[56:59], v[148:151], v[160:163], v[56:59]
	v_mfma_f32_16x16x32_bf16 v[44:47], v[128:131], v[168:171], v[44:47]
	v_mfma_f32_16x16x32_bf16 v[40:43], v[148:151], v[168:171], v[40:43]
	v_mfma_f32_16x16x32_bf16 v[28:31], v[128:131], v[176:179], v[28:31]
	v_mfma_f32_16x16x32_bf16 v[24:27], v[148:151], v[176:179], v[24:27]
	v_mfma_f32_16x16x32_bf16 v[12:15], v[128:131], v[200:203], v[12:15]
	v_mfma_f32_16x16x32_bf16 v[8:11], v[148:151], v[200:203], v[8:11]
	v_mfma_f32_16x16x32_bf16 v[60:63], v[132:135], v[164:167], v[60:63]
	v_mfma_f32_16x16x32_bf16 v[56:59], v[152:155], v[164:167], v[56:59]
	v_mfma_f32_16x16x32_bf16 v[44:47], v[132:135], v[172:175], v[44:47]
	v_mfma_f32_16x16x32_bf16 v[40:43], v[152:155], v[172:175], v[40:43]
	v_mfma_f32_16x16x32_bf16 v[28:31], v[132:135], v[196:199], v[28:31]
	v_mfma_f32_16x16x32_bf16 v[24:27], v[152:155], v[196:199], v[24:27]
	v_mfma_f32_16x16x32_bf16 v[12:15], v[132:135], v[204:207], v[12:15]
	v_mfma_f32_16x16x32_bf16 v[8:11], v[152:155], v[204:207], v[8:11]
	s_barrier
	s_add_u32 s4, s4, 0x40080
	s_addc_u32 s5, s5, 0
	s_add_i32 s28, s28, s40
	s_mov_b32 m0, s28
	s_nop 0
	global_load_lds_dwordx4 v144, s[4:5]
	s_add_i32 m0, s28, 0x2000
	s_nop 0
	global_load_lds_dwordx4 v136, s[4:5]
	s_waitcnt vmcnt(6)
	s_barrier
	v_mfma_f32_16x16x32_bf16 v[52:55], v[208:211], v[160:163], v[52:55]
	v_mfma_f32_16x16x32_bf16 v[48:51], v[216:219], v[160:163], v[48:51]
	v_mfma_f32_16x16x32_bf16 v[36:39], v[208:211], v[168:171], v[36:39]
	v_mfma_f32_16x16x32_bf16 v[32:35], v[216:219], v[168:171], v[32:35]
	v_mfma_f32_16x16x32_bf16 v[20:23], v[208:211], v[176:179], v[20:23]
	v_mfma_f32_16x16x32_bf16 v[16:19], v[216:219], v[176:179], v[16:19]
	v_mfma_f32_16x16x32_bf16 v[4:7], v[208:211], v[200:203], v[4:7]
	v_mfma_f32_16x16x32_bf16 v[0:3], v[216:219], v[200:203], v[0:3]
	v_mfma_f32_16x16x32_bf16 v[52:55], v[212:215], v[164:167], v[52:55]
	v_mfma_f32_16x16x32_bf16 v[48:51], v[220:223], v[164:167], v[48:51]
	v_mfma_f32_16x16x32_bf16 v[36:39], v[212:215], v[172:175], v[36:39]
	v_mfma_f32_16x16x32_bf16 v[32:35], v[220:223], v[172:175], v[32:35]
	v_mfma_f32_16x16x32_bf16 v[20:23], v[212:215], v[196:199], v[20:23]
	v_mfma_f32_16x16x32_bf16 v[16:19], v[220:223], v[196:199], v[16:19]
	v_mfma_f32_16x16x32_bf16 v[4:7], v[212:215], v[204:207], v[4:7]
	v_mfma_f32_16x16x32_bf16 v[0:3], v[220:223], v[204:207], v[0:3]
	s_add_i32 s54, s54, 2
	s_add_u32 s2, s2, 0x100
	s_addc_u32 s3, s3, 0
	s_add_u32 s52, s52, 0x100
	s_addc_u32 s53, s53, 0
	s_cmp_gt_u32 s54, 13
	s_barrier
	s_cbranch_scc0 .LBB0_1644
	s_lshl_b32 s2, s34, 8
	v_mov_b32_e32 v161, v182
	s_add_i32 s2, s2, s47
	v_cndmask_b32_e64 v130, 0, 1, s[14:15]
	v_and_or_b32 v150, v161, 15, s2
	s_lshl_b32 s2, s24, 8
	v_bfe_u32 v160, v161, 4, 2
	s_or_b32 s2, s2, s48
	v_ashrrev_i32_e32 v151, 31, v150
	v_lshl_or_b32 v148, v160, 3, s2
	v_lshlrev_b64 v[128:129], 12, v[150:151]
	v_ashrrev_i32_e32 v149, 31, v148
	v_lshl_add_u64 v[128:129], s[6:7], 0, v[128:129]
	v_cmp_ne_u32_e64 s[2:3], 1, v130
	s_andn2_b64 vcc, exec, s[14:15]
	v_lshl_add_u64 v[154:155], v[148:149], 2, v[128:129]
	s_cbranch_vccnz .LBB0_1647
	global_load_dwordx4 v[132:135], v[154:155], off offset:16
	global_load_dwordx4 v[128:131], v[154:155], off
	s_mov_b64 s[4:5], 0
	s_branch .LBB0_1648

; #define PG8_STAGE(bufoff, gbase, voff) do { _Pragma("unroll") for (int _i = 0; _i < 2; ++_i) \
;     __builtin_amdgcn_global_load_lds((const unsigned*)((const char*)(gbase) + (voff)[_i]), (LAS unsigned*)(lds + (bufoff) + ldsw + _i * 8192), 16, 0, 0); } while (0)
; #define PG8_LDA(dst, b, h) do { _Pragma("unroll") for (int m = 0; m < 4; ++m) _Pragma("unroll") for (int k = 0; k < 2; ++k) dst[m][k] = *(const LAS bf16x8*)(lds + PG8_SA(b, h) + aoff + m * 2048 + k * 1024); } while (0)
; #define PG8_LDB(dst, b, h) do { _Pragma("unroll") for (int n = 0; n < 2; ++n) _Pragma("unroll") for (int k = 0; k < 2; ++k) dst[n][k] = *(const LAS bf16x8*)(lds + PG8_SB(b, h) + boff + n * 2048 + k * 1024); } while (0)
; #define PG8_MMA(ai, bj, At, Bt) do { __builtin_amdgcn_s_setprio(1); _Pragma("unroll") for (int m = 0; m < 4; ++m) _Pragma("unroll") for (int n = 0; n < 2; ++n) _Pragma("unroll") for (int k = 0; k < 2; ++k) \
;     acc[ai][bj][m][n] = __builtin_amdgcn_mfma_f32_16x16x32_bf16(Bt[n][k], At[m][k], acc[ai][bj][m][n], 0, 0, 0); __builtin_amdgcn_s_setprio(0); } while (0)
; #define PG8_WAIT_V(n) asm volatile("s_waitcnt vmcnt(" #n ")" ::: "memory")
; #define PG8_WAIT_L(n) asm volatile("s_waitcnt lgkmcnt(" #n ")" ::: "memory")
; #define PG8_BAR __builtin_amdgcn_s_barrier()
; #define PG8_SCHED __builtin_amdgcn_sched_barrier(0)
; template <class Epi, class Sched>
; DI void gemm_phase(LAS unsigned char* lds, const Gemm g, const Sched& S, const Epi& E) {
;     ...
;       PG8_LDB(B0, 0, 0); PG8_SCHED; PG8_LDA(At, 0, 0); PG8_STAGE(PG8_SA(1, 1), a1 + hstep, voffA);
;       PG8_WAIT_L(8); PG8_BAR; PG8_WAIT_L(0); PG8_MMA(0, 0, At, B0); PG8_BAR; PG8_SCHED;
;       PG8_LDB(B1, 0, 1); PG8_STAGE(PG8_SB(0, 0), b2, voffB);
;       PG8_BAR; PG8_WAIT_L(0); PG8_MMA(0, 1, At, B1); PG8_BAR;
;       PG8_LDA(At, 0, 1); PG8_STAGE(PG8_SA(0, 0), a2, voffA);
;       PG8_BAR; PG8_WAIT_L(0); PG8_MMA(1, 0, At, B0); PG8_BAR; PG8_SCHED;
;       PG8_STAGE(PG8_SB(0, 1), b2 + hstep, voffB);
;       PG8_WAIT_V(6); PG8_BAR; PG8_MMA(1, 1, At, B1); PG8_BAR;
.LBB0_1829:
	s_add_u32 s16, s14, 0xfffc0080
	s_addc_u32 s17, s15, -1
	s_add_i32 s51, 0, 0x10000
	v_add_u32_e32 v140, s51, v142
	ds_read_b128 v[146:149], v140
	ds_read_b128 v[150:153], v140 offset:1024
	ds_read_b128 v[154:157], v140 offset:2048
	ds_read_b128 v[158:161], v140 offset:3072
	s_cmp_eq_u32 s50, 12
	s_cselect_b32 s19, s7, s17
	s_cselect_b32 s18, s46, s16
	s_cselect_b32 s17, s5, s49
	s_cselect_b32 s16, s47, s48
	s_add_i32 m0, s29, 0xc000
	ds_read_b128 v[162:165], v143
	ds_read_b128 v[166:169], v143 offset:1024
	ds_read_b128 v[170:173], v143 offset:2048
	ds_read_b128 v[174:177], v143 offset:3072
	ds_read_b128 v[178:181], v143 offset:4096
	ds_read_b128 v[196:199], v143 offset:5120
	ds_read_b128 v[200:203], v143 offset:6144
	ds_read_b128 v[204:207], v143 offset:7168
	global_load_lds_dwordx4 v136, s[14:15]
	s_add_i32 m0, s29, 0xe000
	s_nop 0
	global_load_lds_dwordx4 v138, s[14:15]
	s_waitcnt lgkmcnt(8)
	s_barrier
	s_waitcnt lgkmcnt(0)
	s_waitcnt lgkmcnt(0)
	v_mfma_f32_16x16x32_bf16 v[124:127], v[146:149], v[162:165], v[124:127]
	v_mfma_f32_16x16x32_bf16 v[120:123], v[154:157], v[162:165], v[120:123]
	v_mfma_f32_16x16x32_bf16 v[112:115], v[146:149], v[170:173], v[112:115]
	v_mfma_f32_16x16x32_bf16 v[104:107], v[154:157], v[170:173], v[104:107]
	v_mfma_f32_16x16x32_bf16 v[92:95], v[146:149], v[178:181], v[92:95]
	v_mfma_f32_16x16x32_bf16 v[88:91], v[154:157], v[178:181], v[88:91]
	v_mfma_f32_16x16x32_bf16 v[80:83], v[146:149], v[200:203], v[80:83]
	v_mfma_f32_16x16x32_bf16 v[72:75], v[154:157], v[200:203], v[72:75]
	v_mfma_f32_16x16x32_bf16 v[124:127], v[150:153], v[166:169], v[124:127]
	v_mfma_f32_16x16x32_bf16 v[120:123], v[158:161], v[166:169], v[120:123]
	v_mfma_f32_16x16x32_bf16 v[112:115], v[150:153], v[174:177], v[112:115]
	v_mfma_f32_16x16x32_bf16 v[104:107], v[158:161], v[174:177], v[104:107]
	v_mfma_f32_16x16x32_bf16 v[92:95], v[150:153], v[196:199], v[92:95]
	v_mfma_f32_16x16x32_bf16 v[88:91], v[158:161], v[196:199], v[88:91]
	v_mfma_f32_16x16x32_bf16 v[80:83], v[150:153], v[204:207], v[80:83]
	v_mfma_f32_16x16x32_bf16 v[72:75], v[158:161], v[204:207], v[72:75]
	s_barrier
	s_add_i32 s54, 0, 0x14000
	v_add_u32_e32 v140, s54, v142
	s_add_i32 s51, s51, s20
	ds_read_b128 v[208:211], v140
	ds_read_b128 v[212:215], v140 offset:1024
	ds_read_b128 v[216:219], v140 offset:2048
	ds_read_b128 v[220:223], v140 offset:3072
	s_add_u32 vcc_lo, s16, s0
	s_addc_u32 vcc_hi, s17, s1
	s_mov_b32 m0, s51
	s_nop 0
	global_load_lds_dwordx4 v132, s[16:17]
	s_add_i32 m0, s51, 0x2000
	s_nop 0
	global_load_lds_dwordx4 v128, s[16:17]
	s_barrier
	s_waitcnt lgkmcnt(0)
	s_waitcnt lgkmcnt(0)
	v_mfma_f32_16x16x32_bf16 v[116:119], v[208:211], v[162:165], v[116:119]
	v_mfma_f32_16x16x32_bf16 v[108:111], v[216:219], v[162:165], v[108:111]
	v_mfma_f32_16x16x32_bf16 v[100:103], v[208:211], v[170:173], v[100:103]
	v_mfma_f32_16x16x32_bf16 v[96:99], v[216:219], v[170:173], v[96:99]
	v_mfma_f32_16x16x32_bf16 v[84:87], v[208:211], v[178:181], v[84:87]
	v_mfma_f32_16x16x32_bf16 v[76:79], v[216:219], v[178:181], v[76:79]
	v_mfma_f32_16x16x32_bf16 v[68:71], v[208:211], v[200:203], v[68:71]
	v_mfma_f32_16x16x32_bf16 v[64:67], v[216:219], v[200:203], v[64:67]
	v_mfma_f32_16x16x32_bf16 v[116:119], v[212:215], v[166:169], v[116:119]
	v_mfma_f32_16x16x32_bf16 v[108:111], v[220:223], v[166:169], v[108:111]
	v_mfma_f32_16x16x32_bf16 v[100:103], v[212:215], v[174:177], v[100:103]
	v_mfma_f32_16x16x32_bf16 v[96:99], v[220:223], v[174:177], v[96:99]
	v_mfma_f32_16x16x32_bf16 v[84:87], v[212:215], v[196:199], v[84:87]
	v_mfma_f32_16x16x32_bf16 v[76:79], v[220:223], v[196:199], v[76:79]
	v_mfma_f32_16x16x32_bf16 v[68:71], v[212:215], v[204:207], v[68:71]
	v_mfma_f32_16x16x32_bf16 v[64:67], v[220:223], v[204:207], v[64:67]
	s_mov_b32 m0, s29
	s_add_u32 s100, s18, s0
	s_addc_u32 s101, s19, s1
	s_barrier
	ds_read_b128 v[162:165], v143 offset:16384
	ds_read_b128 v[166:169], v143 offset:17408
	ds_read_b128 v[170:173], v143 offset:18432
	ds_read_b128 v[174:177], v143 offset:19456
	ds_read_b128 v[178:181], v143 offset:20480
	ds_read_b128 v[196:199], v143 offset:21504
	ds_read_b128 v[200:203], v143 offset:22528
	ds_read_b128 v[204:207], v143 offset:23552
	global_load_lds_dwordx4 v134, s[18:19]
	s_mov_b32 m0, s34
	s_nop 0
	global_load_lds_dwordx4 v130, s[18:19]
	s_barrier
	s_waitcnt lgkmcnt(0)
	s_waitcnt lgkmcnt(0)
	v_mfma_f32_16x16x32_bf16 v[60:63], v[146:149], v[162:165], v[60:63]
	v_mfma_f32_16x16x32_bf16 v[56:59], v[154:157], v[162:165], v[56:59]
	v_mfma_f32_16x16x32_bf16 v[48:51], v[146:149], v[170:173], v[48:51]
	v_mfma_f32_16x16x32_bf16 v[40:43], v[154:157], v[170:173], v[40:43]
	v_mfma_f32_16x16x32_bf16 v[28:31], v[146:149], v[178:181], v[28:31]
	v_mfma_f32_16x16x32_bf16 v[24:27], v[154:157], v[178:181], v[24:27]
	v_mfma_f32_16x16x32_bf16 v[16:19], v[146:149], v[200:203], v[16:19]
	v_mfma_f32_16x16x32_bf16 v[8:11], v[154:157], v[200:203], v[8:11]
	v_mfma_f32_16x16x32_bf16 v[60:63], v[150:153], v[166:169], v[60:63]
	v_mfma_f32_16x16x32_bf16 v[56:59], v[158:161], v[166:169], v[56:59]
	v_mfma_f32_16x16x32_bf16 v[48:51], v[150:153], v[174:177], v[48:51]
	v_mfma_f32_16x16x32_bf16 v[40:43], v[158:161], v[174:177], v[40:43]
	v_mfma_f32_16x16x32_bf16 v[28:31], v[150:153], v[196:199], v[28:31]
	v_mfma_f32_16x16x32_bf16 v[24:27], v[158:161], v[196:199], v[24:27]
	v_mfma_f32_16x16x32_bf16 v[16:19], v[150:153], v[204:207], v[16:19]
	v_mfma_f32_16x16x32_bf16 v[8:11], v[158:161], v[204:207], v[8:11]
	s_barrier
	s_add_u32 s52, s16, 0x40000
	s_addc_u32 s53, s17, 0
	s_add_i32 s51, s54, s20
	s_mov_b32 m0, s51
	s_nop 0
	global_load_lds_dwordx4 v132, s[52:53]
	s_add_i32 m0, s51, 0x2000
	s_nop 0
	global_load_lds_dwordx4 v128, s[52:53]
	s_waitcnt vmcnt(6)
	s_barrier
; #define PG8_STAGE(bufoff, gbase, voff) do { _Pragma("unroll") for (int _i = 0; _i < 2; ++_i) \
;     __builtin_amdgcn_global_load_lds((const unsigned*)((const char*)(gbase) + (voff)[_i]), (LAS unsigned*)(lds + (bufoff) + ldsw + _i * 8192), 16, 0, 0); } while (0)
; #define PG8_LDA(dst, b, h) do { _Pragma("unroll") for (int m = 0; m < 4; ++m) _Pragma("unroll") for (int k = 0; k < 2; ++k) dst[m][k] = *(const LAS bf16x8*)(lds + PG8_SA(b, h) + aoff + m * 2048 + k * 1024); } while (0)
; #define PG8_LDB(dst, b, h) do { _Pragma("unroll") for (int n = 0; n < 2; ++n) _Pragma("unroll") for (int k = 0; k < 2; ++k) dst[n][k] = *(const LAS bf16x8*)(lds + PG8_SB(b, h) + boff + n * 2048 + k * 1024); } while (0)
; #define PG8_MMA(ai, bj, At, Bt) do { __builtin_amdgcn_s_setprio(1); _Pragma("unroll") for (int m = 0; m < 4; ++m) _Pragma("unroll") for (int n = 0; n < 2; ++n) _Pragma("unroll") for (int k = 0; k < 2; ++k) \
;     acc[ai][bj][m][n] = __builtin_amdgcn_mfma_f32_16x16x32_bf16(Bt[n][k], At[m][k], acc[ai][bj][m][n], 0, 0, 0); __builtin_amdgcn_s_setprio(0); } while (0)
; #define PG8_WAIT_V(n) asm volatile("s_waitcnt vmcnt(" #n ")" ::: "memory")
; #define PG8_WAIT_L(n) asm volatile("s_waitcnt lgkmcnt(" #n ")" ::: "memory")
; #define PG8_BAR __builtin_amdgcn_s_barrier()
; #define PG8_SCHED __builtin_amdgcn_sched_barrier(0)
; template <class Epi, class Sched>
; DI void gemm_phase(LAS unsigned char* lds, const Gemm g, const Sched& S, const Epi& E) {
;     ...
;       PG8_WAIT_V(6); PG8_BAR; PG8_MMA(1, 1, At, B1); PG8_BAR;
;       PG8_LDB(B0, 1, 0); PG8_SCHED; PG8_LDA(At, 1, 0); PG8_STAGE(PG8_SA(0, 1), a2 + hstep, voffA);
;       PG8_WAIT_L(8); PG8_BAR; PG8_WAIT_L(0); PG8_MMA(0, 0, At, B0); PG8_BAR; PG8_SCHED;
;       PG8_LDB(B1, 1, 1); PG8_STAGE(PG8_SB(1, 0), b3, voffB);
;       PG8_BAR; PG8_WAIT_L(0); PG8_MMA(0, 1, At, B1); PG8_BAR;
;       PG8_LDA(At, 1, 1); PG8_STAGE(PG8_SA(1, 0), a3, voffA);
;       PG8_BAR; PG8_WAIT_L(0); PG8_MMA(1, 0, At, B0); PG8_BAR; PG8_SCHED;
	v_mfma_f32_16x16x32_bf16 v[52:55], v[208:211], v[162:165], v[52:55]
	v_mfma_f32_16x16x32_bf16 v[44:47], v[216:219], v[162:165], v[44:47]
	v_mfma_f32_16x16x32_bf16 v[36:39], v[208:211], v[170:173], v[36:39]
	v_mfma_f32_16x16x32_bf16 v[32:35], v[216:219], v[170:173], v[32:35]
	v_mfma_f32_16x16x32_bf16 v[20:23], v[208:211], v[178:181], v[20:23]
	v_mfma_f32_16x16x32_bf16 v[12:15], v[216:219], v[178:181], v[12:15]
	v_mfma_f32_16x16x32_bf16 v[4:7], v[208:211], v[200:203], v[4:7]
	v_mfma_f32_16x16x32_bf16 v[0:3], v[216:219], v[200:203], v[0:3]
	v_mfma_f32_16x16x32_bf16 v[52:55], v[212:215], v[166:169], v[52:55]
	v_mfma_f32_16x16x32_bf16 v[44:47], v[220:223], v[166:169], v[44:47]
	v_mfma_f32_16x16x32_bf16 v[36:39], v[212:215], v[174:177], v[36:39]
	v_mfma_f32_16x16x32_bf16 v[32:35], v[220:223], v[174:177], v[32:35]
	v_mfma_f32_16x16x32_bf16 v[20:23], v[212:215], v[196:199], v[20:23]
	v_mfma_f32_16x16x32_bf16 v[12:15], v[220:223], v[196:199], v[12:15]
	v_mfma_f32_16x16x32_bf16 v[4:7], v[212:215], v[204:207], v[4:7]
	v_mfma_f32_16x16x32_bf16 v[0:3], v[220:223], v[204:207], v[0:3]
	s_add_i32 s51, 0, 0x18000
	v_add_u32_e32 v144, s51, v142
	s_barrier
	ds_read_b128 v[146:149], v144
	ds_read_b128 v[150:153], v144 offset:1024
	ds_read_b128 v[154:157], v144 offset:2048
	ds_read_b128 v[158:161], v144 offset:3072
	s_add_u32 s18, s18, 0x40000
	s_addc_u32 s19, s19, 0
	s_mov_b32 m0, s35
	ds_read_b128 v[162:165], v143 offset:32768
	ds_read_b128 v[166:169], v143 offset:33792
	ds_read_b128 v[170:173], v143 offset:34816
	ds_read_b128 v[174:177], v143 offset:35840
	ds_read_b128 v[178:181], v143 offset:36864
	ds_read_b128 v[196:199], v143 offset:37888
	ds_read_b128 v[200:203], v143 offset:38912
	ds_read_b128 v[204:207], v143 offset:39936
	global_load_lds_dwordx4 v134, s[18:19]
	s_mov_b32 m0, s38
	s_nop 0
	global_load_lds_dwordx4 v130, s[18:19]
	s_waitcnt lgkmcnt(8)
	s_barrier
	s_waitcnt lgkmcnt(0)
	s_waitcnt lgkmcnt(0)
	v_mfma_f32_16x16x32_bf16 v[124:127], v[146:149], v[162:165], v[124:127]
	v_mfma_f32_16x16x32_bf16 v[120:123], v[154:157], v[162:165], v[120:123]
	v_mfma_f32_16x16x32_bf16 v[112:115], v[146:149], v[170:173], v[112:115]
	v_mfma_f32_16x16x32_bf16 v[104:107], v[154:157], v[170:173], v[104:107]
	v_mfma_f32_16x16x32_bf16 v[92:95], v[146:149], v[178:181], v[92:95]
	v_mfma_f32_16x16x32_bf16 v[88:91], v[154:157], v[178:181], v[88:91]
	v_mfma_f32_16x16x32_bf16 v[80:83], v[146:149], v[200:203], v[80:83]
	v_mfma_f32_16x16x32_bf16 v[72:75], v[154:157], v[200:203], v[72:75]
	v_mfma_f32_16x16x32_bf16 v[124:127], v[150:153], v[166:169], v[124:127]
	v_mfma_f32_16x16x32_bf16 v[120:123], v[158:161], v[166:169], v[120:123]
	v_mfma_f32_16x16x32_bf16 v[112:115], v[150:153], v[174:177], v[112:115]
	v_mfma_f32_16x16x32_bf16 v[104:107], v[158:161], v[174:177], v[104:107]
	v_mfma_f32_16x16x32_bf16 v[92:95], v[150:153], v[196:199], v[92:95]
	v_mfma_f32_16x16x32_bf16 v[88:91], v[158:161], v[196:199], v[88:91]
	v_mfma_f32_16x16x32_bf16 v[80:83], v[150:153], v[204:207], v[80:83]
	v_mfma_f32_16x16x32_bf16 v[72:75], v[158:161], v[204:207], v[72:75]
	s_barrier
	s_add_i32 s18, 0, 0x1c000
	s_add_i32 s19, s51, s20
	v_add_u32_e32 v144, s18, v142
	s_mov_b32 m0, s19
	ds_read_b128 v[208:211], v144
	ds_read_b128 v[212:215], v144 offset:1024
	ds_read_b128 v[216:219], v144 offset:2048
	ds_read_b128 v[220:223], v144 offset:3072
	global_load_lds_dwordx4 v132, vcc
	s_add_i32 m0, s19, 0x2000
	s_nop 0
	global_load_lds_dwordx4 v128, vcc
	s_barrier
	s_waitcnt lgkmcnt(0)
	s_waitcnt lgkmcnt(0)
	v_mfma_f32_16x16x32_bf16 v[116:119], v[208:211], v[162:165], v[116:119]
	v_mfma_f32_16x16x32_bf16 v[108:111], v[216:219], v[162:165], v[108:111]
	v_mfma_f32_16x16x32_bf16 v[100:103], v[208:211], v[170:173], v[100:103]
	v_mfma_f32_16x16x32_bf16 v[96:99], v[216:219], v[170:173], v[96:99]
	v_mfma_f32_16x16x32_bf16 v[84:87], v[208:211], v[178:181], v[84:87]
	v_mfma_f32_16x16x32_bf16 v[76:79], v[216:219], v[178:181], v[76:79]
	v_mfma_f32_16x16x32_bf16 v[68:71], v[208:211], v[200:203], v[68:71]
	v_mfma_f32_16x16x32_bf16 v[64:67], v[216:219], v[200:203], v[64:67]
	v_mfma_f32_16x16x32_bf16 v[116:119], v[212:215], v[166:169], v[116:119]
	v_mfma_f32_16x16x32_bf16 v[108:111], v[220:223], v[166:169], v[108:111]
	v_mfma_f32_16x16x32_bf16 v[100:103], v[212:215], v[174:177], v[100:103]
	v_mfma_f32_16x16x32_bf16 v[96:99], v[220:223], v[174:177], v[96:99]
	v_mfma_f32_16x16x32_bf16 v[84:87], v[212:215], v[196:199], v[84:87]
	v_mfma_f32_16x16x32_bf16 v[76:79], v[220:223], v[196:199], v[76:79]
	v_mfma_f32_16x16x32_bf16 v[68:71], v[212:215], v[204:207], v[68:71]
	v_mfma_f32_16x16x32_bf16 v[64:67], v[220:223], v[204:207], v[64:67]
	s_mov_b32 m0, s40
	s_barrier
	ds_read_b128 v[162:165], v143 offset:49152
	ds_read_b128 v[166:169], v143 offset:50176
	ds_read_b128 v[170:173], v143 offset:51200
	ds_read_b128 v[174:177], v143 offset:52224
	ds_read_b128 v[178:181], v143 offset:53248
	ds_read_b128 v[196:199], v143 offset:54272
	ds_read_b128 v[200:203], v143 offset:55296
	ds_read_b128 v[204:207], v143 offset:56320
	global_load_lds_dwordx4 v134, s[100:101]
	s_mov_b32 m0, s41
	s_nop 0
	global_load_lds_dwordx4 v130, s[100:101]
	s_barrier
; #define PG8_STAGE(bufoff, gbase, voff) do { _Pragma("unroll") for (int _i = 0; _i < 2; ++_i) \
;     __builtin_amdgcn_global_load_lds((const unsigned*)((const char*)(gbase) + (voff)[_i]), (LAS unsigned*)(lds + (bufoff) + ldsw + _i * 8192), 16, 0, 0); } while (0)
; #define PG8_MMA(ai, bj, At, Bt) do { __builtin_amdgcn_s_setprio(1); _Pragma("unroll") for (int m = 0; m < 4; ++m) _Pragma("unroll") for (int n = 0; n < 2; ++n) _Pragma("unroll") for (int k = 0; k < 2; ++k) \
;     acc[ai][bj][m][n] = __builtin_amdgcn_mfma_f32_16x16x32_bf16(Bt[n][k], At[m][k], acc[ai][bj][m][n], 0, 0, 0); __builtin_amdgcn_s_setprio(0); } while (0)
; #define PG8_WAIT_V(n) asm volatile("s_waitcnt vmcnt(" #n ")" ::: "memory")
; #define PG8_WAIT_L(n) asm volatile("s_waitcnt lgkmcnt(" #n ")" ::: "memory")
; #define PG8_BAR __builtin_amdgcn_s_barrier()
; #define PG8_SCHED __builtin_amdgcn_sched_barrier(0)
; template <class Epi, class Sched>
; DI void gemm_phase(LAS unsigned char* lds, const Gemm g, const Sched& S, const Epi& E) {
;     ...
;       PG8_BAR; PG8_WAIT_L(0); PG8_MMA(1, 0, At, B0); PG8_BAR; PG8_SCHED;
;       PG8_STAGE(PG8_SB(1, 1), b3 + hstep, voffB);
;       PG8_WAIT_V(6); PG8_BAR; PG8_MMA(1, 1, At, B1); PG8_BAR;
;     }
;   DI void operator()(const f32x4 (&acc)[2][2][4][2], const pg8::Unit& u, int wr, int wc, int fr_, int fq_) const {
;     ...
;               if (n == 0) {
;                 const f32x4 v1 = acc[ai][bj][m][1];
;                 u32x4 o4;
;                 { const float t0 = fmaxf(v[0], 0.f) * rinv, t1 = fmaxf(v[1], 0.f) * rinv, t2 = fmaxf(v[2], 0.f) * rinv, t3 = fmaxf(v[3], 0.f) * rinv;
;                   o4.x = pack2(t0 * t0, t1 * t1); o4.y = pack2(t2 * t2, t3 * t3); }
;                 { const float t0 = fmaxf(v1[0], 0.f) * rinv, t1 = fmaxf(v1[1], 0.f) * rinv, t2 = fmaxf(v1[2], 0.f) * rinv, t3 = fmaxf(v1[3], 0.f) * rinv;
;                   o4.z = pack2(t0 * t0, t1 * t1); o4.w = pack2(t2 * t2, t3 * t3); }
;                 *(u32x4*)((u16*)big + (size_t)token * 4096 + u.pn * 256 + bj * 128 + wc * 32 + 8 * fq) = o4;
	s_waitcnt lgkmcnt(0)
	s_waitcnt lgkmcnt(0)
	v_mfma_f32_16x16x32_bf16 v[60:63], v[146:149], v[162:165], v[60:63]
	v_mfma_f32_16x16x32_bf16 v[56:59], v[154:157], v[162:165], v[56:59]
	v_mfma_f32_16x16x32_bf16 v[48:51], v[146:149], v[170:173], v[48:51]
	v_mfma_f32_16x16x32_bf16 v[40:43], v[154:157], v[170:173], v[40:43]
	v_mfma_f32_16x16x32_bf16 v[28:31], v[146:149], v[178:181], v[28:31]
	v_mfma_f32_16x16x32_bf16 v[24:27], v[154:157], v[178:181], v[24:27]
	v_mfma_f32_16x16x32_bf16 v[16:19], v[146:149], v[200:203], v[16:19]
	v_mfma_f32_16x16x32_bf16 v[8:11], v[154:157], v[200:203], v[8:11]
	v_mfma_f32_16x16x32_bf16 v[60:63], v[150:153], v[166:169], v[60:63]
	v_mfma_f32_16x16x32_bf16 v[56:59], v[158:161], v[166:169], v[56:59]
	v_mfma_f32_16x16x32_bf16 v[48:51], v[150:153], v[174:177], v[48:51]
	v_mfma_f32_16x16x32_bf16 v[40:43], v[158:161], v[174:177], v[40:43]
	v_mfma_f32_16x16x32_bf16 v[28:31], v[150:153], v[196:199], v[28:31]
	v_mfma_f32_16x16x32_bf16 v[24:27], v[158:161], v[196:199], v[24:27]
	v_mfma_f32_16x16x32_bf16 v[16:19], v[150:153], v[204:207], v[16:19]
	v_mfma_f32_16x16x32_bf16 v[8:11], v[158:161], v[204:207], v[8:11]
	s_barrier
	s_add_u32 s16, s16, 0x40080
	s_addc_u32 s17, s17, 0
	s_add_i32 s18, s18, s20
	s_mov_b32 m0, s18
	s_nop 0
	global_load_lds_dwordx4 v132, s[16:17]
	s_add_i32 m0, s18, 0x2000
	s_nop 0
	global_load_lds_dwordx4 v128, s[16:17]
	s_waitcnt vmcnt(6)
	s_barrier
	v_mfma_f32_16x16x32_bf16 v[52:55], v[208:211], v[162:165], v[52:55]
	v_mfma_f32_16x16x32_bf16 v[44:47], v[216:219], v[162:165], v[44:47]
	v_mfma_f32_16x16x32_bf16 v[36:39], v[208:211], v[170:173], v[36:39]
	v_mfma_f32_16x16x32_bf16 v[32:35], v[216:219], v[170:173], v[32:35]
	v_mfma_f32_16x16x32_bf16 v[20:23], v[208:211], v[178:181], v[20:23]
	v_mfma_f32_16x16x32_bf16 v[12:15], v[216:219], v[178:181], v[12:15]
	v_mfma_f32_16x16x32_bf16 v[4:7], v[208:211], v[200:203], v[4:7]
	v_mfma_f32_16x16x32_bf16 v[0:3], v[216:219], v[200:203], v[0:3]
	v_mfma_f32_16x16x32_bf16 v[52:55], v[212:215], v[166:169], v[52:55]
	v_mfma_f32_16x16x32_bf16 v[44:47], v[220:223], v[166:169], v[44:47]
	v_mfma_f32_16x16x32_bf16 v[36:39], v[212:215], v[174:177], v[36:39]
	v_mfma_f32_16x16x32_bf16 v[32:35], v[220:223], v[174:177], v[32:35]
	v_mfma_f32_16x16x32_bf16 v[20:23], v[212:215], v[196:199], v[20:23]
	v_mfma_f32_16x16x32_bf16 v[12:15], v[220:223], v[196:199], v[12:15]
	v_mfma_f32_16x16x32_bf16 v[4:7], v[212:215], v[204:207], v[4:7]
	v_mfma_f32_16x16x32_bf16 v[0:3], v[220:223], v[204:207], v[0:3]
	s_add_i32 s50, s50, 2
	s_add_u32 s14, s14, 0x100
	s_addc_u32 s15, s15, 0
	s_add_u32 s48, s48, 0x100
	s_addc_u32 s49, s49, 0
	s_cmp_gt_u32 s50, 13
	s_barrier
	s_cbranch_scc0 .LBB0_1829
	v_mov_b32_e32 v144, v182
	s_lshl_b32 s5, s43, 10
	s_add_i32 s5, s5, 0
	v_and_or_b32 v141, v144, 15, s39
	v_lshl_add_u32 v140, s44, 8, v141
	v_lshl_add_u32 v141, v141, 2, s5
	v_add_u32_e32 v146, 0x20000, v141
	ds_read2_b32 v[148:149], v146 offset1:16
	v_max_f32_e32 v124, 0, v124
	v_max_f32_e32 v125, 0, v125
	v_max_f32_e32 v126, 0, v126
	v_max_f32_e32 v127, 0, v127
	v_max_f32_e32 v120, 0, v120
	v_max_f32_e32 v121, 0, v121
	s_waitcnt lgkmcnt(0)
	v_pk_mul_f32 v[124:125], v[124:125], v[148:149] op_sel_hi:[1,0]
	v_pk_mul_f32 v[126:127], v[126:127], v[148:149] op_sel_hi:[1,0]
	v_pk_mul_f32 v[120:121], v[120:121], v[148:149] op_sel_hi:[1,0]
	v_pk_mul_f32 v[124:125], v[124:125], v[124:125]
	v_pk_mul_f32 v[126:127], v[126:127], v[126:127]
	v_max_f32_e32 v122, 0, v122
	v_max_f32_e32 v123, 0, v123
	v_pk_mul_f32 v[120:121], v[120:121], v[120:121]
	v_max_f32_e32 v116, 0, v116
	v_max_f32_e32 v117, 0, v117
	v_max_f32_e32 v118, 0, v118
	v_max_f32_e32 v119, 0, v119
	v_max_f32_e32 v108, 0, v108
	v_max_f32_e32 v109, 0, v109
	s_lshl_b32 s14, s45, 8
	v_ashrrev_i32_e32 v141, 31, v140
	v_cvt_pk_bf16_f32 v124, v124, v125
	v_cvt_pk_bf16_f32 v125, v126, v127
	v_cvt_pk_bf16_f32 v126, v120, v121
	v_pk_mul_f32 v[120:121], v[122:123], v[148:149] op_sel_hi:[1,0]
	v_pk_mul_f32 v[116:117], v[116:117], v[148:149] op_sel_hi:[1,0]
	v_pk_mul_f32 v[118:119], v[118:119], v[148:149] op_sel_hi:[1,0]
	v_pk_mul_f32 v[108:109], v[108:109], v[148:149] op_sel_hi:[1,0]
	s_ashr_i32 s15, s14, 31
	v_lshlrev_b64 v[150:151], 13, v[140:141]
	v_pk_mul_f32 v[120:121], v[120:121], v[120:121]
	v_pk_mul_f32 v[116:117], v[116:117], v[116:117]
	v_pk_mul_f32 v[118:119], v[118:119], v[118:119]
	v_max_f32_e32 v110, 0, v110
	v_max_f32_e32 v111, 0, v111
	v_pk_mul_f32 v[108:109], v[108:109], v[108:109]
	v_cvt_pk_bf16_f32 v127, v120, v121
	v_lshl_add_u64 v[120:121], s[2:3], 0, v[150:151]
	s_lshl_b64 s[14:15], s[14:15], 1
	v_cvt_pk_bf16_f32 v116, v116, v117
	v_cvt_pk_bf16_f32 v117, v118, v119
	v_cvt_pk_bf16_f32 v118, v108, v109
	v_pk_mul_f32 v[108:109], v[110:111], v[148:149] op_sel_hi:[1,0]
	v_lshl_add_u64 v[120:121], v[120:121], 0, s[14:15]
	v_pk_mul_f32 v[108:109], v[108:109], v[108:109]
	v_lshl_add_u64 v[120:121], v[120:121], 0, s[24:25]
	v_and_b32_e32 v144, 48, v144
	v_cvt_pk_bf16_f32 v119, v108, v109
	v_add_u32_e32 v108, 16, v140
	v_lshl_add_u64 v[120:121], v[120:121], 0, v[144:145]
	v_ashrrev_i32_e32 v109, 31, v108
	global_store_dwordx4 v[120:121], v[116:119], off offset:256
	v_max_f32_e32 v100, 0, v100
	v_max_f32_e32 v101, 0, v101
	v_lshlrev_b64 v[116:117], 13, v[108:109]
	v_max_f32_e32 v108, v112, v112
	v_mov_b32_e32 v112, v149
	v_max_f32_e32 v102, 0, v102
	v_max_f32_e32 v103, 0, v103
	v_max_f32_e32 v96, 0, v96
	v_max_f32_e32 v97, 0, v97
	v_pk_mul_f32 v[100:101], v[100:101], v[112:113] op_sel_hi:[1,0]
	v_pk_mul_f32 v[102:103], v[102:103], v[112:113] op_sel_hi:[1,0]
	v_pk_mul_f32 v[96:97], v[96:97], v[112:113] op_sel_hi:[1,0]
	v_pk_mul_f32 v[100:101], v[100:101], v[100:101]
	v_pk_mul_f32 v[102:103], v[102:103], v[102:103]
	v_max_f32_e32 v98, 0, v98
	v_max_f32_e32 v99, 0, v99
	v_pk_mul_f32 v[96:97], v[96:97], v[96:97]
	v_cvt_pk_bf16_f32 v100, v100, v101
	v_cvt_pk_bf16_f32 v101, v102, v103
	v_cvt_pk_bf16_f32 v102, v96, v97
	v_pk_mul_f32 v[96:97], v[98:99], v[112:113] op_sel_hi:[1,0]
	ds_read2_b32 v[98:99], v146 offset0:32 offset1:48
	v_max_f32_e32 v92, 0, v92
	v_max_f32_e32 v93, 0, v93
	v_max_f32_e32 v94, 0, v94
	v_max_f32_e32 v95, 0, v95
	v_max_f32_e32 v88, 0, v88
	v_max_f32_e32 v89, 0, v89
	v_pk_mul_f32 v[96:97], v[96:97], v[96:97]
	s_waitcnt lgkmcnt(0)
;   DI void operator()(const f32x4 (&acc)[2][2][4][2], const pg8::Unit& u, int wr, int wc, int fr_, int fq_) const {
;     ...
;               if (n == 0) {
;                 const f32x4 v1 = acc[ai][bj][m][1];
;                 u32x4 o4;
;                 { const float t0 = fmaxf(v[0], 0.f) * rinv, t1 = fmaxf(v[1], 0.f) * rinv, t2 = fmaxf(v[2], 0.f) * rinv, t3 = fmaxf(v[3], 0.f) * rinv;
;                   o4.x = pack2(t0 * t0, t1 * t1); o4.y = pack2(t2 * t2, t3 * t3); }
;                 { const float t0 = fmaxf(v1[0], 0.f) * rinv, t1 = fmaxf(v1[1], 0.f) * rinv, t2 = fmaxf(v1[2], 0.f) * rinv, t3 = fmaxf(v1[3], 0.f) * rinv;
;                   o4.z = pack2(t0 * t0, t1 * t1); o4.w = pack2(t2 * t2, t3 * t3); }
;                 *(u32x4*)((u16*)big + (size_t)token * 4096 + u.pn * 256 + bj * 128 + wc * 32 + 8 * fq) = o4;
	v_pk_mul_f32 v[92:93], v[92:93], v[98:99] op_sel_hi:[1,0]
	v_pk_mul_f32 v[94:95], v[94:95], v[98:99] op_sel_hi:[1,0]
	v_pk_mul_f32 v[88:89], v[88:89], v[98:99] op_sel_hi:[1,0]
	v_cvt_pk_bf16_f32 v103, v96, v97
	v_add_u32_e32 v96, 32, v140
	v_pk_mul_f32 v[92:93], v[92:93], v[92:93]
	v_pk_mul_f32 v[94:95], v[94:95], v[94:95]
	v_max_f32_e32 v90, 0, v90
	v_max_f32_e32 v91, 0, v91
	v_pk_mul_f32 v[88:89], v[88:89], v[88:89]
	v_max_f32_e32 v84, 0, v84
	v_max_f32_e32 v85, 0, v85
	v_max_f32_e32 v86, 0, v86
	v_max_f32_e32 v87, 0, v87
	v_max_f32_e32 v76, 0, v76
	v_max_f32_e32 v77, 0, v77
	v_ashrrev_i32_e32 v97, 31, v96
	v_cvt_pk_bf16_f32 v92, v92, v93
	v_cvt_pk_bf16_f32 v93, v94, v95
	v_cvt_pk_bf16_f32 v94, v88, v89
	v_pk_mul_f32 v[88:89], v[90:91], v[98:99] op_sel_hi:[1,0]
	v_pk_mul_f32 v[84:85], v[84:85], v[98:99] op_sel_hi:[1,0]
	v_pk_mul_f32 v[86:87], v[86:87], v[98:99] op_sel_hi:[1,0]
	v_pk_mul_f32 v[76:77], v[76:77], v[98:99] op_sel_hi:[1,0]
	v_lshlrev_b64 v[96:97], 13, v[96:97]
	v_pk_mul_f32 v[88:89], v[88:89], v[88:89]
	v_pk_mul_f32 v[84:85], v[84:85], v[84:85]
	v_pk_mul_f32 v[86:87], v[86:87], v[86:87]
	v_max_f32_e32 v78, 0, v78
	v_max_f32_e32 v79, 0, v79
	v_pk_mul_f32 v[76:77], v[76:77], v[76:77]
	v_cvt_pk_bf16_f32 v95, v88, v89
	v_lshl_add_u64 v[88:89], s[2:3], 0, v[96:97]
	v_cvt_pk_bf16_f32 v84, v84, v85
	v_cvt_pk_bf16_f32 v85, v86, v87
	v_cvt_pk_bf16_f32 v86, v76, v77
	v_pk_mul_f32 v[76:77], v[78:79], v[98:99] op_sel_hi:[1,0]
	v_lshl_add_u64 v[88:89], v[88:89], 0, s[14:15]
	v_pk_mul_f32 v[76:77], v[76:77], v[76:77]
	v_lshl_add_u64 v[88:89], v[88:89], 0, s[24:25]
	v_cvt_pk_bf16_f32 v87, v76, v77
	v_add_u32_e32 v76, 48, v140
	v_lshl_add_u64 v[88:89], v[88:89], 0, v[144:145]
	v_ashrrev_i32_e32 v77, 31, v76
	global_store_dwordx4 v[88:89], v[84:87], off offset:256
	v_max_f32_e32 v68, 0, v68
	v_max_f32_e32 v69, 0, v69
	v_lshlrev_b64 v[84:85], 13, v[76:77]
	v_max_f32_e32 v76, v80, v80
	v_mov_b32_e32 v80, v99
	v_max_f32_e32 v70, 0, v70
	v_max_f32_e32 v71, 0, v71
	v_max_f32_e32 v64, 0, v64
	v_max_f32_e32 v65, 0, v65
	v_pk_mul_f32 v[68:69], v[68:69], v[80:81] op_sel_hi:[1,0]
	v_pk_mul_f32 v[70:71], v[70:71], v[80:81] op_sel_hi:[1,0]
	v_pk_mul_f32 v[64:65], v[64:65], v[80:81] op_sel_hi:[1,0]
	v_pk_mul_f32 v[68:69], v[68:69], v[68:69]
	v_pk_mul_f32 v[70:71], v[70:71], v[70:71]
	v_max_f32_e32 v66, 0, v66
	v_max_f32_e32 v67, 0, v67
	v_pk_mul_f32 v[64:65], v[64:65], v[64:65]
	v_cvt_pk_bf16_f32 v68, v68, v69
	v_cvt_pk_bf16_f32 v69, v70, v71
	v_cvt_pk_bf16_f32 v70, v64, v65
	v_pk_mul_f32 v[64:65], v[66:67], v[80:81] op_sel_hi:[1,0]
	ds_read2_b32 v[66:67], v146 offset0:128 offset1:144
	v_max_f32_e32 v60, 0, v60
	v_max_f32_e32 v61, 0, v61
	v_max_f32_e32 v62, 0, v62
	v_max_f32_e32 v63, 0, v63
	v_max_f32_e32 v56, 0, v56
	v_max_f32_e32 v57, 0, v57
	v_pk_mul_f32 v[64:65], v[64:65], v[64:65]
	s_waitcnt lgkmcnt(0)
	v_pk_mul_f32 v[60:61], v[60:61], v[66:67] op_sel_hi:[1,0]
	v_pk_mul_f32 v[62:63], v[62:63], v[66:67] op_sel_hi:[1,0]
	v_pk_mul_f32 v[56:57], v[56:57], v[66:67] op_sel_hi:[1,0]
	v_cvt_pk_bf16_f32 v71, v64, v65
	v_add_u32_e32 v64, 0x80, v140
	v_pk_mul_f32 v[60:61], v[60:61], v[60:61]
	v_pk_mul_f32 v[62:63], v[62:63], v[62:63]
	v_max_f32_e32 v58, 0, v58
	v_max_f32_e32 v59, 0, v59
	v_pk_mul_f32 v[56:57], v[56:57], v[56:57]
	v_max_f32_e32 v52, 0, v52
	v_max_f32_e32 v53, 0, v53
	v_max_f32_e32 v54, 0, v54
	v_max_f32_e32 v55, 0, v55
	v_max_f32_e32 v44, 0, v44
	v_max_f32_e32 v45, 0, v45
	v_ashrrev_i32_e32 v65, 31, v64
	v_cvt_pk_bf16_f32 v60, v60, v61
	v_cvt_pk_bf16_f32 v61, v62, v63
	v_cvt_pk_bf16_f32 v62, v56, v57
	v_pk_mul_f32 v[56:57], v[58:59], v[66:67] op_sel_hi:[1,0]
	v_pk_mul_f32 v[52:53], v[52:53], v[66:67] op_sel_hi:[1,0]
	v_pk_mul_f32 v[54:55], v[54:55], v[66:67] op_sel_hi:[1,0]
	v_pk_mul_f32 v[44:45], v[44:45], v[66:67] op_sel_hi:[1,0]
	v_lshlrev_b64 v[64:65], 13, v[64:65]
	v_pk_mul_f32 v[56:57], v[56:57], v[56:57]
	v_pk_mul_f32 v[52:53], v[52:53], v[52:53]
	v_pk_mul_f32 v[54:55], v[54:55], v[54:55]
	v_max_f32_e32 v46, 0, v46
	v_max_f32_e32 v47, 0, v47
	v_pk_mul_f32 v[44:45], v[44:45], v[44:45]
	v_cvt_pk_bf16_f32 v63, v56, v57
	v_lshl_add_u64 v[56:57], s[2:3], 0, v[64:65]
	v_cvt_pk_bf16_f32 v52, v52, v53
	v_cvt_pk_bf16_f32 v53, v54, v55
	v_cvt_pk_bf16_f32 v54, v44, v45
	v_pk_mul_f32 v[44:45], v[46:47], v[66:67] op_sel_hi:[1,0]
	v_lshl_add_u64 v[56:57], v[56:57], 0, s[14:15]
	v_pk_mul_f32 v[44:45], v[44:45], v[44:45]
	v_lshl_add_u64 v[56:57], v[56:57], 0, s[24:25]
	v_cvt_pk_bf16_f32 v55, v44, v45
	v_add_u32_e32 v44, 0x90, v140
	v_lshl_add_u64 v[56:57], v[56:57], 0, v[144:145]
	v_ashrrev_i32_e32 v45, 31, v44
	global_store_dwordx4 v[56:57], v[52:55], off offset:256
	v_max_f32_e32 v36, 0, v36
	v_max_f32_e32 v37, 0, v37
	v_lshlrev_b64 v[52:53], 13, v[44:45]
	v_max_f32_e32 v44, v48, v48
	v_mov_b32_e32 v48, v67
	v_max_f32_e32 v38, 0, v38
	v_max_f32_e32 v39, 0, v39
	v_max_f32_e32 v32, 0, v32
	v_max_f32_e32 v33, 0, v33
	v_pk_mul_f32 v[36:37], v[36:37], v[48:49] op_sel_hi:[1,0]
	v_pk_mul_f32 v[38:39], v[38:39], v[48:49] op_sel_hi:[1,0]
	v_pk_mul_f32 v[32:33], v[32:33], v[48:49] op_sel_hi:[1,0]
	v_pk_mul_f32 v[36:37], v[36:37], v[36:37]
	v_pk_mul_f32 v[38:39], v[38:39], v[38:39]
	v_max_f32_e32 v34, 0, v34
	v_max_f32_e32 v35, 0, v35
	v_pk_mul_f32 v[32:33], v[32:33], v[32:33]
	v_cvt_pk_bf16_f32 v36, v36, v37
	v_cvt_pk_bf16_f32 v37, v38, v39
	v_cvt_pk_bf16_f32 v38, v32, v33
	v_pk_mul_f32 v[32:33], v[34:35], v[48:49] op_sel_hi:[1,0]
	ds_read2_b32 v[34:35], v146 offset0:160 offset1:176
	v_max_f32_e32 v28, 0, v28
	v_max_f32_e32 v29, 0, v29
	v_max_f32_e32 v30, 0, v30
	v_max_f32_e32 v31, 0, v31
	v_max_f32_e32 v24, 0, v24
	v_max_f32_e32 v25, 0, v25
	v_pk_mul_f32 v[32:33], v[32:33], v[32:33]
	s_waitcnt lgkmcnt(0)
;   DI void operator()(const f32x4 (&acc)[2][2][4][2], const pg8::Unit& u, int wr, int wc, int fr_, int fq_) const {
;     ...
;               if (n == 0) {
;                 const f32x4 v1 = acc[ai][bj][m][1];
;                 u32x4 o4;
;                 { const float t0 = fmaxf(v[0], 0.f) * rinv, t1 = fmaxf(v[1], 0.f) * rinv, t2 = fmaxf(v[2], 0.f) * rinv, t3 = fmaxf(v[3], 0.f) * rinv;
;                   o4.x = pack2(t0 * t0, t1 * t1); o4.y = pack2(t2 * t2, t3 * t3); }
;                 { const float t0 = fmaxf(v1[0], 0.f) * rinv, t1 = fmaxf(v1[1], 0.f) * rinv, t2 = fmaxf(v1[2], 0.f) * rinv, t3 = fmaxf(v1[3], 0.f) * rinv;
;                   o4.z = pack2(t0 * t0, t1 * t1); o4.w = pack2(t2 * t2, t3 * t3); }
;                 *(u32x4*)((u16*)big + (size_t)token * 4096 + u.pn * 256 + bj * 128 + wc * 32 + 8 * fq) = o4;
	v_pk_mul_f32 v[28:29], v[28:29], v[34:35] op_sel_hi:[1,0]
	v_pk_mul_f32 v[30:31], v[30:31], v[34:35] op_sel_hi:[1,0]
	v_pk_mul_f32 v[24:25], v[24:25], v[34:35] op_sel_hi:[1,0]
	v_cvt_pk_bf16_f32 v39, v32, v33
	v_add_u32_e32 v32, 0xa0, v140
	v_pk_mul_f32 v[28:29], v[28:29], v[28:29]
	v_pk_mul_f32 v[30:31], v[30:31], v[30:31]
	v_max_f32_e32 v26, 0, v26
	v_max_f32_e32 v27, 0, v27
	v_pk_mul_f32 v[24:25], v[24:25], v[24:25]
	v_max_f32_e32 v20, 0, v20
	v_max_f32_e32 v21, 0, v21
	v_max_f32_e32 v22, 0, v22
	v_max_f32_e32 v23, 0, v23
	v_max_f32_e32 v12, 0, v12
	v_max_f32_e32 v13, 0, v13
	v_ashrrev_i32_e32 v33, 31, v32
	v_cvt_pk_bf16_f32 v28, v28, v29
	v_cvt_pk_bf16_f32 v29, v30, v31
	v_cvt_pk_bf16_f32 v30, v24, v25
	v_pk_mul_f32 v[24:25], v[26:27], v[34:35] op_sel_hi:[1,0]
	v_pk_mul_f32 v[20:21], v[20:21], v[34:35] op_sel_hi:[1,0]
	v_pk_mul_f32 v[22:23], v[22:23], v[34:35] op_sel_hi:[1,0]
	v_pk_mul_f32 v[12:13], v[12:13], v[34:35] op_sel_hi:[1,0]
	v_lshlrev_b64 v[32:33], 13, v[32:33]
	v_pk_mul_f32 v[24:25], v[24:25], v[24:25]
	v_pk_mul_f32 v[20:21], v[20:21], v[20:21]
	v_pk_mul_f32 v[22:23], v[22:23], v[22:23]
	v_max_f32_e32 v14, 0, v14
	v_max_f32_e32 v15, 0, v15
	v_pk_mul_f32 v[12:13], v[12:13], v[12:13]
	v_cvt_pk_bf16_f32 v31, v24, v25
	v_lshl_add_u64 v[24:25], s[2:3], 0, v[32:33]
	v_cvt_pk_bf16_f32 v20, v20, v21
	v_cvt_pk_bf16_f32 v21, v22, v23
	v_cvt_pk_bf16_f32 v22, v12, v13
	v_pk_mul_f32 v[12:13], v[14:15], v[34:35] op_sel_hi:[1,0]
	v_lshl_add_u64 v[24:25], v[24:25], 0, s[14:15]
	v_pk_mul_f32 v[12:13], v[12:13], v[12:13]
	v_lshl_add_u64 v[24:25], v[24:25], 0, s[24:25]
	v_cvt_pk_bf16_f32 v23, v12, v13
	v_add_u32_e32 v12, 0xb0, v140
	v_lshl_add_u64 v[24:25], v[24:25], 0, v[144:145]
	v_ashrrev_i32_e32 v13, 31, v12
	v_max_f32_e32 v109, v113, v113
	v_max_f32_e32 v110, v114, v114
	v_max_f32_e32 v111, v115, v115
	v_max_f32_e32 v77, v81, v81
	v_max_f32_e32 v78, v82, v82
	v_max_f32_e32 v79, v83, v83
	v_max_f32_e32 v45, v49, v49
	v_max_f32_e32 v46, v50, v50
	v_max_f32_e32 v47, v51, v51
	global_store_dwordx4 v[24:25], v[20:23], off offset:256
	v_max_f32_e32 v14, v18, v18
	v_max_f32_e32 v15, v19, v19
	v_lshlrev_b64 v[20:21], 13, v[12:13]
	v_max_f32_e32 v12, v16, v16
	v_max_f32_e32 v13, v17, v17
	v_max_f32_e32 v108, 0, v108
	v_max_f32_e32 v109, 0, v109
	v_max_f32_e32 v110, 0, v110
	v_max_f32_e32 v111, 0, v111
	v_max_f32_e32 v104, 0, v104
	v_max_f32_e32 v105, 0, v105
	v_max_f32_e32 v76, 0, v76
	v_max_f32_e32 v77, 0, v77
	v_max_f32_e32 v78, 0, v78
	v_max_f32_e32 v79, 0, v79
	v_max_f32_e32 v72, 0, v72
	v_max_f32_e32 v73, 0, v73
	v_max_f32_e32 v44, 0, v44
	v_max_f32_e32 v45, 0, v45
	v_max_f32_e32 v46, 0, v46
	v_max_f32_e32 v47, 0, v47
	v_max_f32_e32 v40, 0, v40
	v_max_f32_e32 v41, 0, v41
	v_max_f32_e32 v12, 0, v12
	v_max_f32_e32 v13, 0, v13
	v_max_f32_e32 v14, 0, v14
	v_max_f32_e32 v15, 0, v15
	v_mov_b32_e32 v16, v35
	v_max_f32_e32 v8, 0, v8
	v_max_f32_e32 v9, 0, v9
	v_pk_mul_f32 v[108:109], v[108:109], v[112:113] op_sel_hi:[1,0]
	v_pk_mul_f32 v[110:111], v[110:111], v[112:113] op_sel_hi:[1,0]
	v_pk_mul_f32 v[104:105], v[104:105], v[112:113] op_sel_hi:[1,0]
	v_pk_mul_f32 v[76:77], v[76:77], v[80:81] op_sel_hi:[1,0]
	v_pk_mul_f32 v[78:79], v[78:79], v[80:81] op_sel_hi:[1,0]
	v_pk_mul_f32 v[72:73], v[72:73], v[80:81] op_sel_hi:[1,0]
	v_pk_mul_f32 v[44:45], v[44:45], v[48:49] op_sel_hi:[1,0]
	v_pk_mul_f32 v[46:47], v[46:47], v[48:49] op_sel_hi:[1,0]
	v_pk_mul_f32 v[40:41], v[40:41], v[48:49] op_sel_hi:[1,0]
	v_pk_mul_f32 v[12:13], v[12:13], v[16:17] op_sel_hi:[1,0]
	v_pk_mul_f32 v[14:15], v[14:15], v[16:17] op_sel_hi:[1,0]
	v_pk_mul_f32 v[8:9], v[8:9], v[16:17] op_sel_hi:[1,0]
	v_pk_mul_f32 v[108:109], v[108:109], v[108:109]
	v_pk_mul_f32 v[110:111], v[110:111], v[110:111]
	v_max_f32_e32 v106, 0, v106
	v_max_f32_e32 v107, 0, v107
	v_pk_mul_f32 v[104:105], v[104:105], v[104:105]
; #define PG8_WAIT_V(n) asm volatile("s_waitcnt vmcnt(" #n ")" ::: "memory")
; #define PG8_BAR __builtin_amdgcn_s_barrier()
; template <class Epi, class Sched>
; DI void gemm_phase(LAS unsigned char* lds, const Gemm g, const Sched& S, const Epi& E) {
;     ...
;     E(acc, cur, wr, wc, fr, fq);
;     if (!has_next) break;
; #pragma unroll
;     for (int a = 0; a < 2; ++a)
; #pragma unroll
;       for (int b = 0; b < 2; ++b)
; #pragma unroll
;         for (int m = 0; m < 4; ++m)
; #pragma unroll
;           for (int n = 0; n < 2; ++n) acc[a][b][m][n] = (f32x4){0.f, 0.f, 0.f, 0.f};
;     cur = nxt; cA = nA; cB = nB; ++ui;
;   }
;   PG8_WAIT_V(0);
;   if (wr == 0) PG8_BAR;
;   PG8_BAR;
;   DI void operator()(const f32x4 (&acc)[2][2][4][2], const pg8::Unit& u, int wr, int wc, int fr_, int fq_) const {
;     ...
;               if (n == 0) {
;                 const f32x4 v1 = acc[ai][bj][m][1];
;                 u32x4 o4;
;                 { const float t0 = fmaxf(v[0], 0.f) * rinv, t1 = fmaxf(v[1], 0.f) * rinv, t2 = fmaxf(v[2], 0.f) * rinv, t3 = fmaxf(v[3], 0.f) * rinv;
;                   o4.x = pack2(t0 * t0, t1 * t1); o4.y = pack2(t2 * t2, t3 * t3); }
;                 { const float t0 = fmaxf(v1[0], 0.f) * rinv, t1 = fmaxf(v1[1], 0.f) * rinv, t2 = fmaxf(v1[2], 0.f) * rinv, t3 = fmaxf(v1[3], 0.f) * rinv;
;                   o4.z = pack2(t0 * t0, t1 * t1); o4.w = pack2(t2 * t2, t3 * t3); }
;                 *(u32x4*)((u16*)big + (size_t)token * 4096 + u.pn * 256 + bj * 128 + wc * 32 + 8 * fq) = o4;
	v_pk_mul_f32 v[76:77], v[76:77], v[76:77]
	v_pk_mul_f32 v[78:79], v[78:79], v[78:79]
	v_max_f32_e32 v74, 0, v74
	v_max_f32_e32 v75, 0, v75
	v_pk_mul_f32 v[72:73], v[72:73], v[72:73]
	v_pk_mul_f32 v[44:45], v[44:45], v[44:45]
	v_pk_mul_f32 v[46:47], v[46:47], v[46:47]
	v_max_f32_e32 v42, 0, v42
	v_max_f32_e32 v43, 0, v43
	v_pk_mul_f32 v[40:41], v[40:41], v[40:41]
	v_pk_mul_f32 v[12:13], v[12:13], v[12:13]
	v_pk_mul_f32 v[14:15], v[14:15], v[14:15]
	v_max_f32_e32 v10, 0, v10
	v_max_f32_e32 v11, 0, v11
	v_pk_mul_f32 v[8:9], v[8:9], v[8:9]
	v_cvt_pk_bf16_f32 v108, v108, v109
	v_cvt_pk_bf16_f32 v109, v110, v111
	v_cvt_pk_bf16_f32 v110, v104, v105
	v_pk_mul_f32 v[104:105], v[106:107], v[112:113] op_sel_hi:[1,0]
	v_cvt_pk_bf16_f32 v76, v76, v77
	v_cvt_pk_bf16_f32 v77, v78, v79
	v_cvt_pk_bf16_f32 v78, v72, v73
	v_pk_mul_f32 v[72:73], v[74:75], v[80:81] op_sel_hi:[1,0]
	v_cvt_pk_bf16_f32 v44, v44, v45
	v_cvt_pk_bf16_f32 v45, v46, v47
	v_cvt_pk_bf16_f32 v46, v40, v41
	v_pk_mul_f32 v[40:41], v[42:43], v[48:49] op_sel_hi:[1,0]
	v_cvt_pk_bf16_f32 v12, v12, v13
	v_cvt_pk_bf16_f32 v13, v14, v15
	v_cvt_pk_bf16_f32 v14, v8, v9
	v_pk_mul_f32 v[8:9], v[10:11], v[16:17] op_sel_hi:[1,0]
	v_max_f32_e32 v4, 0, v4
	v_max_f32_e32 v5, 0, v5
	v_max_f32_e32 v6, 0, v6
	v_max_f32_e32 v7, 0, v7
	v_max_f32_e32 v0, 0, v0
	v_max_f32_e32 v1, 0, v1
	v_pk_mul_f32 v[104:105], v[104:105], v[104:105]
	v_pk_mul_f32 v[72:73], v[72:73], v[72:73]
	v_pk_mul_f32 v[40:41], v[40:41], v[40:41]
	v_pk_mul_f32 v[8:9], v[8:9], v[8:9]
	v_pk_mul_f32 v[4:5], v[4:5], v[16:17] op_sel_hi:[1,0]
	v_pk_mul_f32 v[6:7], v[6:7], v[16:17] op_sel_hi:[1,0]
	v_pk_mul_f32 v[0:1], v[0:1], v[16:17] op_sel_hi:[1,0]
	v_cvt_pk_bf16_f32 v111, v104, v105
	v_lshl_add_u64 v[104:105], s[2:3], 0, v[116:117]
	v_cvt_pk_bf16_f32 v79, v72, v73
	v_lshl_add_u64 v[72:73], s[2:3], 0, v[84:85]
	v_cvt_pk_bf16_f32 v47, v40, v41
	v_lshl_add_u64 v[40:41], s[2:3], 0, v[52:53]
	v_cvt_pk_bf16_f32 v15, v8, v9
	v_lshl_add_u64 v[8:9], s[2:3], 0, v[20:21]
	v_pk_mul_f32 v[4:5], v[4:5], v[4:5]
	v_pk_mul_f32 v[6:7], v[6:7], v[6:7]
	v_max_f32_e32 v2, 0, v2
	v_max_f32_e32 v3, 0, v3
	v_pk_mul_f32 v[0:1], v[0:1], v[0:1]
	v_lshl_add_u64 v[104:105], v[104:105], 0, s[14:15]
	v_lshl_add_u64 v[72:73], v[72:73], 0, s[14:15]
	v_lshl_add_u64 v[40:41], v[40:41], 0, s[14:15]
	v_lshl_add_u64 v[8:9], v[8:9], 0, s[14:15]
	v_cvt_pk_bf16_f32 v4, v4, v5
	v_cvt_pk_bf16_f32 v5, v6, v7
	v_cvt_pk_bf16_f32 v6, v0, v1
	v_pk_mul_f32 v[0:1], v[2:3], v[16:17] op_sel_hi:[1,0]
	v_lshl_add_u64 v[104:105], v[104:105], 0, s[24:25]
	v_lshl_add_u64 v[72:73], v[72:73], 0, s[24:25]
	v_lshl_add_u64 v[40:41], v[40:41], 0, s[24:25]
	v_lshl_add_u64 v[8:9], v[8:9], 0, s[24:25]
	v_pk_mul_f32 v[0:1], v[0:1], v[0:1]
	v_lshl_add_u64 v[104:105], v[104:105], 0, v[144:145]
	v_lshl_add_u64 v[72:73], v[72:73], 0, v[144:145]
	v_lshl_add_u64 v[40:41], v[40:41], 0, v[144:145]
	v_lshl_add_u64 v[8:9], v[8:9], 0, v[144:145]
	v_cvt_pk_bf16_f32 v7, v0, v1
	s_and_b64 vcc, exec, s[36:37]
	s_mov_b32 s43, s42
	s_mov_b32 s45, s4
	s_mov_b32 s44, s6
	s_mov_b64 s[16:17], s[12:13]
	s_mov_b64 s[14:15], s[10:11]
	v_readlane_b32 s51, v237, 11
	global_store_dwordx4 v[120:121], v[124:127], off
	global_store_dwordx4 v[104:105], v[108:111], off
	global_store_dwordx4 v[104:105], v[100:103], off offset:256
	global_store_dwordx4 v[88:89], v[92:95], off
	global_store_dwordx4 v[72:73], v[76:79], off
	global_store_dwordx4 v[72:73], v[68:71], off offset:256
	global_store_dwordx4 v[56:57], v[60:63], off
	global_store_dwordx4 v[40:41], v[44:47], off
	global_store_dwordx4 v[40:41], v[36:39], off offset:256
	global_store_dwordx4 v[24:25], v[28:31], off
	global_store_dwordx4 v[8:9], v[12:15], off
	global_store_dwordx4 v[8:9], v[4:7], off offset:256
	s_cbranch_vccz .LBB0_1822
	s_waitcnt vmcnt(0)
	s_cmpk_gt_u32 s9, 0xff
	s_cbranch_scc1 .LBB0_1833
	s_barrier

; #define PG8_STAGE(bufoff, gbase, voff) do { _Pragma("unroll") for (int _i = 0; _i < 2; ++_i) \
;     __builtin_amdgcn_global_load_lds((const unsigned*)((const char*)(gbase) + (voff)[_i]), (LAS unsigned*)(lds + (bufoff) + ldsw + _i * 8192), 16, 0, 0); } while (0)
; #define PG8_LDA(dst, b, h) do { _Pragma("unroll") for (int m = 0; m < 4; ++m) _Pragma("unroll") for (int k = 0; k < 2; ++k) dst[m][k] = *(const LAS bf16x8*)(lds + PG8_SA(b, h) + aoff + m * 2048 + k * 1024); } while (0)
; #define PG8_LDB(dst, b, h) do { _Pragma("unroll") for (int n = 0; n < 2; ++n) _Pragma("unroll") for (int k = 0; k < 2; ++k) dst[n][k] = *(const LAS bf16x8*)(lds + PG8_SB(b, h) + boff + n * 2048 + k * 1024); } while (0)
; #define PG8_MMA(ai, bj, At, Bt) do { __builtin_amdgcn_s_setprio(1); _Pragma("unroll") for (int m = 0; m < 4; ++m) _Pragma("unroll") for (int n = 0; n < 2; ++n) _Pragma("unroll") for (int k = 0; k < 2; ++k) \
;     acc[ai][bj][m][n] = __builtin_amdgcn_mfma_f32_16x16x32_bf16(Bt[n][k], At[m][k], acc[ai][bj][m][n], 0, 0, 0); __builtin_amdgcn_s_setprio(0); } while (0)
; #define PG8_WAIT_V(n) asm volatile("s_waitcnt vmcnt(" #n ")" ::: "memory")
; #define PG8_WAIT_L(n) asm volatile("s_waitcnt lgkmcnt(" #n ")" ::: "memory")
; #define PG8_BAR __builtin_amdgcn_s_barrier()
; #define PG8_SCHED __builtin_amdgcn_sched_barrier(0)
; template <class Epi, class Sched>
; DI void gemm_phase(LAS unsigned char* lds, const Gemm g, const Sched& S, const Epi& E) {
;     ...
;       PG8_LDB(B0, 0, 0); PG8_SCHED; PG8_LDA(At, 0, 0); PG8_STAGE(PG8_SA(1, 1), a1 + hstep, voffA);
;       PG8_WAIT_L(8); PG8_BAR; PG8_WAIT_L(0); PG8_MMA(0, 0, At, B0); PG8_BAR; PG8_SCHED;
;       PG8_LDB(B1, 0, 1); PG8_STAGE(PG8_SB(0, 0), b2, voffB);
;       PG8_BAR; PG8_WAIT_L(0); PG8_MMA(0, 1, At, B1); PG8_BAR;
;       PG8_LDA(At, 0, 1); PG8_STAGE(PG8_SA(0, 0), a2, voffA);
;       PG8_BAR; PG8_WAIT_L(0); PG8_MMA(1, 0, At, B0); PG8_BAR; PG8_SCHED;
;       PG8_STAGE(PG8_SB(0, 1), b2 + hstep, voffB);
;       PG8_WAIT_V(6); PG8_BAR; PG8_MMA(1, 1, At, B1); PG8_BAR;
.LBB0_1905:
	s_add_u32 s22, s20, 0xfff00080
	s_addc_u32 s23, s21, -1
	s_add_i32 s51, 0, 0x10000
	v_add_u32_e32 v142, s51, v146
	ds_read_b128 v[138:141], v142
	ds_read_b128 v[148:151], v142 offset:1024
	ds_read_b128 v[152:155], v142 offset:2048
	ds_read_b128 v[156:159], v142 offset:3072
	s_cmp_eq_u32 s50, 60
	s_cselect_b32 s29, s11, s23
	s_cselect_b32 s28, s17, s22
	s_cselect_b32 s23, s7, s49
	s_cselect_b32 s22, s19, s24
	s_add_i32 m0, s39, 0xc000
	ds_read_b128 v[160:163], v147
	ds_read_b128 v[164:167], v147 offset:1024
	ds_read_b128 v[168:171], v147 offset:2048
	ds_read_b128 v[172:175], v147 offset:3072
	ds_read_b128 v[176:179], v147 offset:4096
	ds_read_b128 v[196:199], v147 offset:5120
	ds_read_b128 v[200:203], v147 offset:6144
	ds_read_b128 v[204:207], v147 offset:7168
	global_load_lds_dwordx4 v134, s[20:21]
	s_add_i32 m0, s39, 0xe000
	s_nop 0
	global_load_lds_dwordx4 v136, s[20:21]
	s_waitcnt lgkmcnt(8)
	s_barrier
	s_waitcnt lgkmcnt(0)
	s_waitcnt lgkmcnt(0)
	v_mfma_f32_16x16x32_bf16 v[124:127], v[138:141], v[160:163], v[124:127]
	v_mfma_f32_16x16x32_bf16 v[120:123], v[152:155], v[160:163], v[120:123]
	v_mfma_f32_16x16x32_bf16 v[108:111], v[138:141], v[168:171], v[108:111]
	v_mfma_f32_16x16x32_bf16 v[104:107], v[152:155], v[168:171], v[104:107]
	v_mfma_f32_16x16x32_bf16 v[92:95], v[138:141], v[176:179], v[92:95]
	v_mfma_f32_16x16x32_bf16 v[88:91], v[152:155], v[176:179], v[88:91]
	v_mfma_f32_16x16x32_bf16 v[76:79], v[138:141], v[200:203], v[76:79]
	v_mfma_f32_16x16x32_bf16 v[72:75], v[152:155], v[200:203], v[72:75]
	v_mfma_f32_16x16x32_bf16 v[124:127], v[148:151], v[164:167], v[124:127]
	v_mfma_f32_16x16x32_bf16 v[120:123], v[156:159], v[164:167], v[120:123]
	v_mfma_f32_16x16x32_bf16 v[108:111], v[148:151], v[172:175], v[108:111]
	v_mfma_f32_16x16x32_bf16 v[104:107], v[156:159], v[172:175], v[104:107]
	v_mfma_f32_16x16x32_bf16 v[92:95], v[148:151], v[196:199], v[92:95]
	v_mfma_f32_16x16x32_bf16 v[88:91], v[156:159], v[196:199], v[88:91]
	v_mfma_f32_16x16x32_bf16 v[76:79], v[148:151], v[204:207], v[76:79]
	v_mfma_f32_16x16x32_bf16 v[72:75], v[156:159], v[204:207], v[72:75]
	s_barrier
	s_add_i32 s54, 0, 0x14000
	v_add_u32_e32 v142, s54, v146
	s_add_i32 s51, s51, s38
	ds_read_b128 v[208:211], v142
	ds_read_b128 v[212:215], v142 offset:1024
	ds_read_b128 v[216:219], v142 offset:2048
	ds_read_b128 v[220:223], v142 offset:3072
	s_add_u32 vcc_lo, s22, s0
	s_addc_u32 vcc_hi, s23, s1
	s_mov_b32 m0, s51
	s_nop 0
	global_load_lds_dwordx4 v144, s[22:23]
	s_add_i32 m0, s51, 0x2000
	s_nop 0
	global_load_lds_dwordx4 v132, s[22:23]
	s_barrier
	s_waitcnt lgkmcnt(0)
	s_waitcnt lgkmcnt(0)
	v_mfma_f32_16x16x32_bf16 v[116:119], v[208:211], v[160:163], v[116:119]
	v_mfma_f32_16x16x32_bf16 v[112:115], v[216:219], v[160:163], v[112:115]
	v_mfma_f32_16x16x32_bf16 v[100:103], v[208:211], v[168:171], v[100:103]
	v_mfma_f32_16x16x32_bf16 v[96:99], v[216:219], v[168:171], v[96:99]
	v_mfma_f32_16x16x32_bf16 v[84:87], v[208:211], v[176:179], v[84:87]
	v_mfma_f32_16x16x32_bf16 v[80:83], v[216:219], v[176:179], v[80:83]
	v_mfma_f32_16x16x32_bf16 v[68:71], v[208:211], v[200:203], v[68:71]
	v_mfma_f32_16x16x32_bf16 v[64:67], v[216:219], v[200:203], v[64:67]
	v_mfma_f32_16x16x32_bf16 v[116:119], v[212:215], v[164:167], v[116:119]
	v_mfma_f32_16x16x32_bf16 v[112:115], v[220:223], v[164:167], v[112:115]
	v_mfma_f32_16x16x32_bf16 v[100:103], v[212:215], v[172:175], v[100:103]
	v_mfma_f32_16x16x32_bf16 v[96:99], v[220:223], v[172:175], v[96:99]
	v_mfma_f32_16x16x32_bf16 v[84:87], v[212:215], v[196:199], v[84:87]
	v_mfma_f32_16x16x32_bf16 v[80:83], v[220:223], v[196:199], v[80:83]
	v_mfma_f32_16x16x32_bf16 v[68:71], v[212:215], v[204:207], v[68:71]
	v_mfma_f32_16x16x32_bf16 v[64:67], v[220:223], v[204:207], v[64:67]
	s_mov_b32 m0, s39
	s_add_u32 s100, s28, s0
	s_addc_u32 s101, s29, s1
	s_barrier
	ds_read_b128 v[160:163], v147 offset:16384
	ds_read_b128 v[164:167], v147 offset:17408
	ds_read_b128 v[168:171], v147 offset:18432
	ds_read_b128 v[172:175], v147 offset:19456
	ds_read_b128 v[176:179], v147 offset:20480
	ds_read_b128 v[196:199], v147 offset:21504
	ds_read_b128 v[200:203], v147 offset:22528
	ds_read_b128 v[204:207], v147 offset:23552
	global_load_lds_dwordx4 v128, s[28:29]
	s_mov_b32 m0, s40
	s_nop 0
	global_load_lds_dwordx4 v130, s[28:29]
	s_barrier
	s_waitcnt lgkmcnt(0)
	s_waitcnt lgkmcnt(0)
	v_mfma_f32_16x16x32_bf16 v[60:63], v[138:141], v[160:163], v[60:63]
	v_mfma_f32_16x16x32_bf16 v[56:59], v[152:155], v[160:163], v[56:59]
	v_mfma_f32_16x16x32_bf16 v[44:47], v[138:141], v[168:171], v[44:47]
	v_mfma_f32_16x16x32_bf16 v[40:43], v[152:155], v[168:171], v[40:43]
	v_mfma_f32_16x16x32_bf16 v[28:31], v[138:141], v[176:179], v[28:31]
	v_mfma_f32_16x16x32_bf16 v[24:27], v[152:155], v[176:179], v[24:27]
	v_mfma_f32_16x16x32_bf16 v[12:15], v[138:141], v[200:203], v[12:15]
	v_mfma_f32_16x16x32_bf16 v[8:11], v[152:155], v[200:203], v[8:11]
	v_mfma_f32_16x16x32_bf16 v[60:63], v[148:151], v[164:167], v[60:63]
	v_mfma_f32_16x16x32_bf16 v[56:59], v[156:159], v[164:167], v[56:59]
	v_mfma_f32_16x16x32_bf16 v[44:47], v[148:151], v[172:175], v[44:47]
	v_mfma_f32_16x16x32_bf16 v[40:43], v[156:159], v[172:175], v[40:43]
	v_mfma_f32_16x16x32_bf16 v[28:31], v[148:151], v[196:199], v[28:31]
	v_mfma_f32_16x16x32_bf16 v[24:27], v[156:159], v[196:199], v[24:27]
	v_mfma_f32_16x16x32_bf16 v[12:15], v[148:151], v[204:207], v[12:15]
	v_mfma_f32_16x16x32_bf16 v[8:11], v[156:159], v[204:207], v[8:11]
	s_barrier
	s_add_u32 s52, s22, 0x100000
	s_addc_u32 s53, s23, 0
	s_add_i32 s51, s54, s38
	s_mov_b32 m0, s51
	s_nop 0
	global_load_lds_dwordx4 v144, s[52:53]
	s_add_i32 m0, s51, 0x2000
	s_nop 0
	global_load_lds_dwordx4 v132, s[52:53]
	s_waitcnt vmcnt(6)
	s_barrier
; #define PG8_STAGE(bufoff, gbase, voff) do { _Pragma("unroll") for (int _i = 0; _i < 2; ++_i) \
;     __builtin_amdgcn_global_load_lds((const unsigned*)((const char*)(gbase) + (voff)[_i]), (LAS unsigned*)(lds + (bufoff) + ldsw + _i * 8192), 16, 0, 0); } while (0)
; #define PG8_LDA(dst, b, h) do { _Pragma("unroll") for (int m = 0; m < 4; ++m) _Pragma("unroll") for (int k = 0; k < 2; ++k) dst[m][k] = *(const LAS bf16x8*)(lds + PG8_SA(b, h) + aoff + m * 2048 + k * 1024); } while (0)
; #define PG8_LDB(dst, b, h) do { _Pragma("unroll") for (int n = 0; n < 2; ++n) _Pragma("unroll") for (int k = 0; k < 2; ++k) dst[n][k] = *(const LAS bf16x8*)(lds + PG8_SB(b, h) + boff + n * 2048 + k * 1024); } while (0)
; #define PG8_MMA(ai, bj, At, Bt) do { __builtin_amdgcn_s_setprio(1); _Pragma("unroll") for (int m = 0; m < 4; ++m) _Pragma("unroll") for (int n = 0; n < 2; ++n) _Pragma("unroll") for (int k = 0; k < 2; ++k) \
;     acc[ai][bj][m][n] = __builtin_amdgcn_mfma_f32_16x16x32_bf16(Bt[n][k], At[m][k], acc[ai][bj][m][n], 0, 0, 0); __builtin_amdgcn_s_setprio(0); } while (0)
; #define PG8_WAIT_V(n) asm volatile("s_waitcnt vmcnt(" #n ")" ::: "memory")
; #define PG8_WAIT_L(n) asm volatile("s_waitcnt lgkmcnt(" #n ")" ::: "memory")
; #define PG8_BAR __builtin_amdgcn_s_barrier()
; #define PG8_SCHED __builtin_amdgcn_sched_barrier(0)
; template <class Epi, class Sched>
; DI void gemm_phase(LAS unsigned char* lds, const Gemm g, const Sched& S, const Epi& E) {
;     ...
;       PG8_WAIT_V(6); PG8_BAR; PG8_MMA(1, 1, At, B1); PG8_BAR;
;       PG8_LDB(B0, 1, 0); PG8_SCHED; PG8_LDA(At, 1, 0); PG8_STAGE(PG8_SA(0, 1), a2 + hstep, voffA);
;       PG8_WAIT_L(8); PG8_BAR; PG8_WAIT_L(0); PG8_MMA(0, 0, At, B0); PG8_BAR; PG8_SCHED;
;       PG8_LDB(B1, 1, 1); PG8_STAGE(PG8_SB(1, 0), b3, voffB);
;       PG8_BAR; PG8_WAIT_L(0); PG8_MMA(0, 1, At, B1); PG8_BAR;
;       PG8_LDA(At, 1, 1); PG8_STAGE(PG8_SA(1, 0), a3, voffA);
;       PG8_BAR; PG8_WAIT_L(0); PG8_MMA(1, 0, At, B0); PG8_BAR; PG8_SCHED;
	v_mfma_f32_16x16x32_bf16 v[52:55], v[208:211], v[160:163], v[52:55]
	v_mfma_f32_16x16x32_bf16 v[48:51], v[216:219], v[160:163], v[48:51]
	v_mfma_f32_16x16x32_bf16 v[36:39], v[208:211], v[168:171], v[36:39]
	v_mfma_f32_16x16x32_bf16 v[32:35], v[216:219], v[168:171], v[32:35]
	v_mfma_f32_16x16x32_bf16 v[20:23], v[208:211], v[176:179], v[20:23]
	v_mfma_f32_16x16x32_bf16 v[16:19], v[216:219], v[176:179], v[16:19]
	v_mfma_f32_16x16x32_bf16 v[4:7], v[208:211], v[200:203], v[4:7]
	v_mfma_f32_16x16x32_bf16 v[0:3], v[216:219], v[200:203], v[0:3]
	v_mfma_f32_16x16x32_bf16 v[52:55], v[212:215], v[164:167], v[52:55]
	v_mfma_f32_16x16x32_bf16 v[48:51], v[220:223], v[164:167], v[48:51]
	v_mfma_f32_16x16x32_bf16 v[36:39], v[212:215], v[172:175], v[36:39]
	v_mfma_f32_16x16x32_bf16 v[32:35], v[220:223], v[172:175], v[32:35]
	v_mfma_f32_16x16x32_bf16 v[20:23], v[212:215], v[196:199], v[20:23]
	v_mfma_f32_16x16x32_bf16 v[16:19], v[220:223], v[196:199], v[16:19]
	v_mfma_f32_16x16x32_bf16 v[4:7], v[212:215], v[204:207], v[4:7]
	v_mfma_f32_16x16x32_bf16 v[0:3], v[220:223], v[204:207], v[0:3]
	s_add_i32 s51, 0, 0x18000
	v_add_u32_e32 v156, s51, v146
	s_barrier
	ds_read_b128 v[138:141], v156
	ds_read_b128 v[148:151], v156 offset:1024
	ds_read_b128 v[152:155], v156 offset:2048
	ds_read_b128 v[156:159], v156 offset:3072
	s_add_u32 s28, s28, 0x100000
	s_addc_u32 s29, s29, 0
	s_mov_b32 m0, s41
	ds_read_b128 v[160:163], v147 offset:32768
	ds_read_b128 v[164:167], v147 offset:33792
	ds_read_b128 v[168:171], v147 offset:34816
	ds_read_b128 v[172:175], v147 offset:35840
	ds_read_b128 v[176:179], v147 offset:36864
	ds_read_b128 v[196:199], v147 offset:37888
	ds_read_b128 v[200:203], v147 offset:38912
	ds_read_b128 v[204:207], v147 offset:39936
	global_load_lds_dwordx4 v128, s[28:29]
	s_mov_b32 m0, s42
	s_nop 0
	global_load_lds_dwordx4 v130, s[28:29]
	s_waitcnt lgkmcnt(8)
	s_barrier
	s_waitcnt lgkmcnt(0)
	s_waitcnt lgkmcnt(0)
	v_mfma_f32_16x16x32_bf16 v[124:127], v[138:141], v[160:163], v[124:127]
	v_mfma_f32_16x16x32_bf16 v[120:123], v[152:155], v[160:163], v[120:123]
	v_mfma_f32_16x16x32_bf16 v[108:111], v[138:141], v[168:171], v[108:111]
	v_mfma_f32_16x16x32_bf16 v[104:107], v[152:155], v[168:171], v[104:107]
	v_mfma_f32_16x16x32_bf16 v[92:95], v[138:141], v[176:179], v[92:95]
	v_mfma_f32_16x16x32_bf16 v[88:91], v[152:155], v[176:179], v[88:91]
	v_mfma_f32_16x16x32_bf16 v[76:79], v[138:141], v[200:203], v[76:79]
	v_mfma_f32_16x16x32_bf16 v[72:75], v[152:155], v[200:203], v[72:75]
	v_mfma_f32_16x16x32_bf16 v[124:127], v[148:151], v[164:167], v[124:127]
	v_mfma_f32_16x16x32_bf16 v[120:123], v[156:159], v[164:167], v[120:123]
	v_mfma_f32_16x16x32_bf16 v[108:111], v[148:151], v[172:175], v[108:111]
	v_mfma_f32_16x16x32_bf16 v[104:107], v[156:159], v[172:175], v[104:107]
	v_mfma_f32_16x16x32_bf16 v[92:95], v[148:151], v[196:199], v[92:95]
	v_mfma_f32_16x16x32_bf16 v[88:91], v[156:159], v[196:199], v[88:91]
	v_mfma_f32_16x16x32_bf16 v[76:79], v[148:151], v[204:207], v[76:79]
	v_mfma_f32_16x16x32_bf16 v[72:75], v[156:159], v[204:207], v[72:75]
	s_barrier
	s_add_i32 s28, 0, 0x1c000
	s_add_i32 s29, s51, s38
	v_add_u32_e32 v220, s28, v146
	s_mov_b32 m0, s29
	ds_read_b128 v[208:211], v220
	ds_read_b128 v[212:215], v220 offset:1024
	ds_read_b128 v[216:219], v220 offset:2048
	ds_read_b128 v[220:223], v220 offset:3072
	global_load_lds_dwordx4 v144, vcc
	s_add_i32 m0, s29, 0x2000
	s_nop 0
	global_load_lds_dwordx4 v132, vcc
	s_barrier
	s_waitcnt lgkmcnt(0)
	s_waitcnt lgkmcnt(0)
	v_mfma_f32_16x16x32_bf16 v[116:119], v[208:211], v[160:163], v[116:119]
	v_mfma_f32_16x16x32_bf16 v[112:115], v[216:219], v[160:163], v[112:115]
	v_mfma_f32_16x16x32_bf16 v[100:103], v[208:211], v[168:171], v[100:103]
	v_mfma_f32_16x16x32_bf16 v[96:99], v[216:219], v[168:171], v[96:99]
	v_mfma_f32_16x16x32_bf16 v[84:87], v[208:211], v[176:179], v[84:87]
	v_mfma_f32_16x16x32_bf16 v[80:83], v[216:219], v[176:179], v[80:83]
	v_mfma_f32_16x16x32_bf16 v[68:71], v[208:211], v[200:203], v[68:71]
	v_mfma_f32_16x16x32_bf16 v[64:67], v[216:219], v[200:203], v[64:67]
	v_mfma_f32_16x16x32_bf16 v[116:119], v[212:215], v[164:167], v[116:119]
	v_mfma_f32_16x16x32_bf16 v[112:115], v[220:223], v[164:167], v[112:115]
	v_mfma_f32_16x16x32_bf16 v[100:103], v[212:215], v[172:175], v[100:103]
	v_mfma_f32_16x16x32_bf16 v[96:99], v[220:223], v[172:175], v[96:99]
	v_mfma_f32_16x16x32_bf16 v[84:87], v[212:215], v[196:199], v[84:87]
	v_mfma_f32_16x16x32_bf16 v[80:83], v[220:223], v[196:199], v[80:83]
	v_mfma_f32_16x16x32_bf16 v[68:71], v[212:215], v[204:207], v[68:71]
	v_mfma_f32_16x16x32_bf16 v[64:67], v[220:223], v[204:207], v[64:67]
	s_mov_b32 m0, s46
	s_barrier
	ds_read_b128 v[160:163], v147 offset:49152
	ds_read_b128 v[164:167], v147 offset:50176
	ds_read_b128 v[168:171], v147 offset:51200
	ds_read_b128 v[172:175], v147 offset:52224
	ds_read_b128 v[176:179], v147 offset:53248
	ds_read_b128 v[196:199], v147 offset:54272
	ds_read_b128 v[200:203], v147 offset:55296
	ds_read_b128 v[204:207], v147 offset:56320
	global_load_lds_dwordx4 v128, s[100:101]
	s_mov_b32 m0, s47
	s_nop 0
	global_load_lds_dwordx4 v130, s[100:101]
	s_barrier
; template <class Epi, class Sched>
; DI void gemm_phase(LAS unsigned char* lds, const Gemm g, const Sched& S, const Epi& E) {
;     ...
;       PG8_BAR; PG8_WAIT_L(0); PG8_MMA(1, 0, At, B0); PG8_BAR; PG8_SCHED;
;       PG8_STAGE(PG8_SB(1, 1), b3 + hstep, voffB);
;       PG8_WAIT_V(6); PG8_BAR; PG8_MMA(1, 1, At, B1); PG8_BAR;
;     }
;   DI void operator()(const f32x4 (&acc)[2][2][4][2], const pg8::Unit& u, int wr, int wc, int fr_, int fq_) const {
;     ...
;             } else if (EPI == EPI_RESID) {
;               if (n == 0) {
;                 const int f8 = u.pn * 256 + bj * 128 + wc * 32 + 8 * fq;
;                 const f32x4 v1 = acc[ai][bj][m][1];
;                 f32x4 r0, r1;
;                 if (rsrc) {
;                   r0 = *(const f32x4*)(rsrc + (size_t)token * 1024 + f8); r1 = *(const f32x4*)(rsrc + (size_t)token * 1024 + f8 + 4);
;                 } else {
;                   const u32x4 xu = *(const u32x4*)(xr + (size_t)token * 1024 + f8);
;                   r0 = (f32x4){bf2f(xu.x & 0xffffu), bf2f(xu.x >> 16), bf2f(xu.y & 0xffffu), bf2f(xu.y >> 16)};
;                   r1 = (f32x4){bf2f(xu.z & 0xffffu), bf2f(xu.z >> 16), bf2f(xu.w & 0xffffu), bf2f(xu.w >> 16)};
;                 }
;                 r0 += v; r1 += v1;
;                 st_bf8(xr + (size_t)token * 1024 + f8, r0, r1, 1.f);
;                 ssq += r0[0] * r0[0] + r0[1] * r0[1] + r0[2] * r0[2] + r0[3] * r0[3] + r1[0] * r1[0] + r1[1] * r1[1] + r1[2] * r1[2] + r1[3] * r1[3];
;               }
;             } else {
;               if (n == 0) {
;                 const f32x4 v1 = acc[ai][bj][m][1];
;                 u32x4 o4;
;                 { const float t0 = fmaxf(v[0], 0.f) * rinv, t1 = fmaxf(v[1], 0.f) * rinv, t2 = fmaxf(v[2], 0.f) * rinv, t3 = fmaxf(v[3], 0.f) * rinv;
;                   o4.x = pack2(t0 * t0, t1 * t1); o4.y = pack2(t2 * t2, t3 * t3); }
;                 { const float t0 = fmaxf(v1[0], 0.f) * rinv, t1 = fmaxf(v1[1], 0.f) * rinv, t2 = fmaxf(v1[2], 0.f) * rinv, t3 = fmaxf(v1[3], 0.f) * rinv;
;                   o4.z = pack2(t0 * t0, t1 * t1); o4.w = pack2(t2 * t2, t3 * t3); }
;                 *(u32x4*)((u16*)big + (size_t)token * 4096 + u.pn * 256 + bj * 128 + wc * 32 + 8 * fq) = o4;
;               }
;             }
;           }
;         if (EPI == EPI_RESID) {
;           ssq += shx(ssq, 16, t_ & 63);
;           ssq += shx(ssq, 32, t_ & 63);
	s_waitcnt lgkmcnt(0)
	s_waitcnt lgkmcnt(0)
	v_mfma_f32_16x16x32_bf16 v[60:63], v[138:141], v[160:163], v[60:63]
	v_mfma_f32_16x16x32_bf16 v[56:59], v[152:155], v[160:163], v[56:59]
	v_mfma_f32_16x16x32_bf16 v[44:47], v[138:141], v[168:171], v[44:47]
	v_mfma_f32_16x16x32_bf16 v[40:43], v[152:155], v[168:171], v[40:43]
	v_mfma_f32_16x16x32_bf16 v[28:31], v[138:141], v[176:179], v[28:31]
	v_mfma_f32_16x16x32_bf16 v[24:27], v[152:155], v[176:179], v[24:27]
	v_mfma_f32_16x16x32_bf16 v[12:15], v[138:141], v[200:203], v[12:15]
	v_mfma_f32_16x16x32_bf16 v[8:11], v[152:155], v[200:203], v[8:11]
	v_mfma_f32_16x16x32_bf16 v[60:63], v[148:151], v[164:167], v[60:63]
	v_mfma_f32_16x16x32_bf16 v[56:59], v[156:159], v[164:167], v[56:59]
	v_mfma_f32_16x16x32_bf16 v[44:47], v[148:151], v[172:175], v[44:47]
	v_mfma_f32_16x16x32_bf16 v[40:43], v[156:159], v[172:175], v[40:43]
	v_mfma_f32_16x16x32_bf16 v[28:31], v[148:151], v[196:199], v[28:31]
	v_mfma_f32_16x16x32_bf16 v[24:27], v[156:159], v[196:199], v[24:27]
	v_mfma_f32_16x16x32_bf16 v[12:15], v[148:151], v[204:207], v[12:15]
	v_mfma_f32_16x16x32_bf16 v[8:11], v[156:159], v[204:207], v[8:11]
	s_barrier
	s_add_u32 s22, s22, 0x100080
	s_addc_u32 s23, s23, 0
	s_add_i32 s28, s28, s38
	s_mov_b32 m0, s28
	s_nop 0
	global_load_lds_dwordx4 v144, s[22:23]
	s_add_i32 m0, s28, 0x2000
	s_nop 0
	global_load_lds_dwordx4 v132, s[22:23]
	s_waitcnt vmcnt(6)
	s_barrier
	v_mfma_f32_16x16x32_bf16 v[52:55], v[208:211], v[160:163], v[52:55]
	v_mfma_f32_16x16x32_bf16 v[48:51], v[216:219], v[160:163], v[48:51]
	v_mfma_f32_16x16x32_bf16 v[36:39], v[208:211], v[168:171], v[36:39]
	v_mfma_f32_16x16x32_bf16 v[32:35], v[216:219], v[168:171], v[32:35]
	v_mfma_f32_16x16x32_bf16 v[20:23], v[208:211], v[176:179], v[20:23]
	v_mfma_f32_16x16x32_bf16 v[16:19], v[216:219], v[176:179], v[16:19]
	v_mfma_f32_16x16x32_bf16 v[4:7], v[208:211], v[200:203], v[4:7]
	v_mfma_f32_16x16x32_bf16 v[0:3], v[216:219], v[200:203], v[0:3]
	v_mfma_f32_16x16x32_bf16 v[52:55], v[212:215], v[164:167], v[52:55]
	v_mfma_f32_16x16x32_bf16 v[48:51], v[220:223], v[164:167], v[48:51]
	v_mfma_f32_16x16x32_bf16 v[36:39], v[212:215], v[172:175], v[36:39]
	v_mfma_f32_16x16x32_bf16 v[32:35], v[220:223], v[172:175], v[32:35]
	v_mfma_f32_16x16x32_bf16 v[20:23], v[212:215], v[196:199], v[20:23]
	v_mfma_f32_16x16x32_bf16 v[16:19], v[220:223], v[196:199], v[16:19]
	v_mfma_f32_16x16x32_bf16 v[4:7], v[212:215], v[204:207], v[4:7]
	v_mfma_f32_16x16x32_bf16 v[0:3], v[220:223], v[204:207], v[0:3]
	s_add_i32 s50, s50, 2
	s_add_u32 s20, s20, 0x100
	s_addc_u32 s21, s21, 0
	s_add_u32 s24, s24, 0x100
	s_addc_u32 s49, s49, 0
	s_cmp_gt_u32 s50, 61
	s_barrier
	s_cbranch_scc0 .LBB0_1905
	s_lshl_b32 s7, s18, 8
	v_mov_b32_e32 v139, v182
	s_add_i32 s7, s7, s44
	s_nop 0
	v_and_or_b32 v140, v139, 15, s7
	s_lshl_b32 s7, s16, 8
	v_bfe_u32 v141, v139, 4, 2
	s_or_b32 s7, s7, s45
	v_lshl_or_b32 v138, v141, 3, s7
	v_cmp_eq_u32_e32 vcc, 0, v141
	v_ashrrev_i32_e32 v141, 31, v140
	v_lshlrev_b32_e32 v139, 2, v139
	s_movk_i32 s7, 0x80
	v_lshlrev_b64 v[142:143], 11, v[140:141]
	v_bitop3_b32 v149, v139, 64, v190 bitop3:0x6c
	v_bitop3_b32 v148, v139, s7, v190 bitop3:0x6c
	v_ashrrev_i32_e32 v139, 31, v138
	v_lshl_add_u64 v[142:143], s[4:5], 0, v[142:143]
	v_lshl_add_u64 v[142:143], v[138:139], 1, v[142:143]
	global_load_dwordx4 v[150:153], v[142:143], off
	s_lshl_b32 s16, s16, 2
	s_ashr_i32 s17, s16, 31
	s_waitcnt vmcnt(0)
	v_lshlrev_b32_e32 v154, 16, v150
	v_and_b32_e32 v155, 0xffff0000, v150
	v_lshlrev_b32_e32 v150, 16, v151
	v_and_b32_e32 v151, 0xffff0000, v151
	v_lshlrev_b32_e32 v156, 16, v152
	v_and_b32_e32 v157, 0xffff0000, v152
	v_lshlrev_b32_e32 v152, 16, v153
	v_and_b32_e32 v153, 0xffff0000, v153
	v_pk_add_f32 v[126:127], v[126:127], v[150:151]
	v_pk_add_f32 v[124:125], v[124:125], v[154:155]
	v_pk_add_f32 v[150:151], v[122:123], v[152:153]
	v_pk_add_f32 v[152:153], v[120:121], v[156:157]
	v_cvt_pk_bf16_f32 v120, v124, v125
	v_cvt_pk_bf16_f32 v121, v126, v127
	v_cvt_pk_bf16_f32 v122, v152, v153
	v_cvt_pk_bf16_f32 v123, v150, v151
	global_store_dwordx4 v[142:143], v[120:123], off
	global_load_dwordx4 v[120:123], v[142:143], off offset:256
	v_mul_f32_e32 v154, v125, v125
	v_fmac_f32_e32 v154, v124, v124
	v_fmac_f32_e32 v154, v126, v126
	v_fmac_f32_e32 v154, v127, v127
	v_fmac_f32_e32 v154, v152, v152
	v_fmac_f32_e32 v154, v153, v153
	v_fmac_f32_e32 v154, v150, v150
	v_fmac_f32_e32 v154, v151, v151
	s_waitcnt vmcnt(0)
	v_lshlrev_b32_e32 v124, 16, v120
	v_and_b32_e32 v125, 0xffff0000, v120
	v_lshlrev_b32_e32 v120, 16, v121
	v_and_b32_e32 v121, 0xffff0000, v121
	v_lshlrev_b32_e32 v126, 16, v122
	v_and_b32_e32 v127, 0xffff0000, v122
	v_lshlrev_b32_e32 v122, 16, v123
	v_and_b32_e32 v123, 0xffff0000, v123
	v_pk_add_f32 v[118:119], v[118:119], v[120:121]
	v_pk_add_f32 v[116:117], v[116:117], v[124:125]
	v_pk_add_f32 v[120:121], v[114:115], v[122:123]
	v_pk_add_f32 v[122:123], v[112:113], v[126:127]
	v_cvt_pk_bf16_f32 v112, v116, v117
	v_cvt_pk_bf16_f32 v113, v118, v119
	v_cvt_pk_bf16_f32 v114, v122, v123
	v_cvt_pk_bf16_f32 v115, v120, v121
	global_store_dwordx4 v[142:143], v[112:115], off offset:256
	s_nop 1
	v_mul_f32_e32 v112, v117, v117
	v_fmac_f32_e32 v112, v116, v116
	v_fmac_f32_e32 v112, v118, v118
	v_fmac_f32_e32 v112, v119, v119
	v_fmac_f32_e32 v112, v122, v122
	v_fmac_f32_e32 v112, v123, v123
	v_fmac_f32_e32 v112, v120, v120
	v_fmac_f32_e32 v112, v121, v121
	v_add_f32_e32 v112, v154, v112
	ds_bpermute_b32 v113, v149, v112
	s_waitcnt lgkmcnt(0)
	v_add_f32_e32 v112, v112, v113
	ds_bpermute_b32 v113, v148, v112
	s_and_saveexec_b64 s[18:19], vcc
	s_cbranch_execz .LBB0_1908
	s_waitcnt lgkmcnt(0)
	v_add_f32_e32 v114, v112, v113
	v_lshlrev_b64 v[112:113], 6, v[140:141]
	v_lshl_add_u64 v[112:113], s[2:3], 0, v[112:113]
	v_lshl_add_u64 v[112:113], s[16:17], 2, v[112:113]
	s_lshl_b32 s24, s43, 2
	v_lshl_add_u64 v[112:113], v[112:113], 0, s[24:25]
	global_store_dword v[112:113], v114, off
